# GEMM main loops: priority raise held across back-to-back MMA segments (28 adjacent s_setprio 0 / s_setprio 1 pairs removed), on top of v24
# baseline (speedup 1.0000x reference)
; #define PG8_STAGE(bufoff, gbase, voff) do { _Pragma("unroll") for (int _i = 0; _i < 2; ++_i) \
;         __builtin_amdgcn_global_load_lds((const unsigned*)((const char*)(gbase) + (voff)[_i]), (PG8_LAS unsigned*)(lds + (bufoff) + ldsw + _i * 8192), 16, 0, 0); } while (0)
; #define PG8_LDA(dst, b, h) do { _Pragma("unroll") for (int m = 0; m < 4; ++m) _Pragma("unroll") for (int k = 0; k < 2; ++k) dst[m][k] = *(const PG8_LAS bf16x8*)(lds + PG8_SA(b, h) + aoff + m * 2048 + k * 1024); } while (0)
; #define PG8_LDB(dst, b, h) do { _Pragma("unroll") for (int n = 0; n < 2; ++n) _Pragma("unroll") for (int k = 0; k < 2; ++k) dst[n][k] = *(const PG8_LAS bf16x8*)(lds + PG8_SB(b, h) + boff + n * 2048 + k * 1024); } while (0)
; #define PG8_MMA(ai, bj, At, Bt) do { __builtin_amdgcn_s_setprio(1); _Pragma("unroll") for (int m = 0; m < 4; ++m) _Pragma("unroll") for (int n = 0; n < 2; ++n) _Pragma("unroll") for (int k = 0; k < 2; ++k) \
;         acc[ai][bj][m][n] = __builtin_amdgcn_mfma_f32_16x16x32_bf16(Bt[n][k], At[m][k], acc[ai][bj][m][n], 0, 0, 0); __builtin_amdgcn_s_setprio(0); } while (0)
; #define PG8_WAIT_V(n) asm volatile("s_waitcnt vmcnt(" #n ")" ::: "memory")
; #define PG8_WAIT_L(n) asm volatile("s_waitcnt lgkmcnt(" #n ")" ::: "memory")
; #define PG8_BAR __builtin_amdgcn_s_barrier()
; #define PG8_SCHED __builtin_amdgcn_sched_barrier(0)
; template <class Epi, class Sched, int K, int lda, int ldb, bool ALIGN_EPI = true, bool SP2 = true>
; __device__ __forceinline__ void gemm_phase(PG8_LAS unsigned char* lds, const Sched& S, const Epi& E, const int wave_sgpr) {
;     ...
;         for (int t = 0; t < nt; t += 2) {
;             const bool last = (t == nt - 2);
;             const char* a1 = cA + (size_t)(t + 1) * kstep;
;             const char* a2 = last ? nA : cA + (size_t)(t + 2) * kstep; const char* b2 = last ? nB : cB + (size_t)(t + 2) * kstep;
;             const char* a3 = a2 + kstep; const char* b3 = b2 + kstep;
;             if constexpr (SP2) {
;             PG8_LDB(B0, 0, 0); PG8_LDB(B1, 0, 1); PG8_SCHED; PG8_LDA(At, 0, 0); PG8_STAGE(PG8_SA(1, 1), a1 + hstepA, voffA);
;             PG8_WAIT_V(8); PG8_WAIT_L(0); PG8_BAR; PG8_MMA(0, 0, At, B0); PG8_MMA(0, 1, At, B1); PG8_BAR; PG8_SCHED;
;             PG8_LDA(At, 0, 1); PG8_STAGE(PG8_SB(0, 0), b2, voffB); PG8_STAGE(PG8_SB(0, 1), b2 + hstepB, voffB); PG8_STAGE(PG8_SA(0, 0), a2, voffA);
.LBB0_190:
	s_add_u32 s20, s18, 0xfffc0080
	s_addc_u32 s21, s19, -1
	s_add_i32 s51, 0, 0x10000
	s_cmp_eq_u32 s50, 12
	s_cselect_b32 s23, s15, s21
	s_cselect_b32 s22, s14, s20
	v_add_u32_e32 v146, s51, v142
	s_cselect_b32 s21, s17, s13
	s_cselect_b32 s20, s16, s9
	s_add_i32 s53, 0, 0x14000
	ds_read_b128 v[138:141], v146
	ds_read_b128 v[148:151], v146 offset:1024
	ds_read_b128 v[152:155], v146 offset:2048
	ds_read_b128 v[158:161], v146 offset:3072
	v_add_u32_e32 v146, s53, v142
	ds_read_b128 v[162:165], v146
	ds_read_b128 v[168:171], v146 offset:1024
	ds_read_b128 v[172:175], v146 offset:2048
	ds_read_b128 v[180:183], v146 offset:3072
	v_lshl_add_u64 v[146:147], s[18:19], 0, v[136:137]
	s_add_i32 m0, s38, 0xc000
	ds_read_b128 v[184:187], v143
	ds_read_b128 v[188:191], v143 offset:1024
	ds_read_b128 v[192:195], v143 offset:2048
	ds_read_b128 v[196:199], v143 offset:3072
	ds_read_b128 v[200:203], v143 offset:4096
	ds_read_b128 v[204:207], v143 offset:5120
	ds_read_b128 v[208:211], v143 offset:6144
	ds_read_b128 v[212:215], v143 offset:7168
	global_load_lds_dwordx4 v[146:147], off
	v_lshl_add_u64 v[146:147], s[18:19], 0, v[134:135]
	s_add_i32 m0, s38, 0xe000
	s_nop 0
	global_load_lds_dwordx4 v[146:147], off
	s_waitcnt vmcnt(8)
	s_waitcnt lgkmcnt(0)
	s_barrier
	s_setprio 1
	s_waitcnt lgkmcnt(0)
	v_mfma_f32_16x16x32_bf16 v[124:127], v[138:141], v[184:187], v[124:127]
	v_mfma_f32_16x16x32_bf16 v[120:123], v[152:155], v[184:187], v[120:123]
	v_mfma_f32_16x16x32_bf16 v[116:119], v[138:141], v[192:195], v[116:119]
	v_mfma_f32_16x16x32_bf16 v[108:111], v[152:155], v[192:195], v[108:111]
	v_mfma_f32_16x16x32_bf16 v[100:103], v[138:141], v[200:203], v[100:103]
	v_mfma_f32_16x16x32_bf16 v[92:95], v[152:155], v[200:203], v[92:95]
	v_mfma_f32_16x16x32_bf16 v[84:87], v[138:141], v[208:211], v[84:87]
	v_mfma_f32_16x16x32_bf16 v[76:79], v[152:155], v[208:211], v[76:79]
	v_mfma_f32_16x16x32_bf16 v[124:127], v[148:151], v[188:191], v[124:127]
	v_mfma_f32_16x16x32_bf16 v[120:123], v[158:161], v[188:191], v[120:123]
	v_mfma_f32_16x16x32_bf16 v[116:119], v[148:151], v[196:199], v[116:119]
	v_mfma_f32_16x16x32_bf16 v[108:111], v[158:161], v[196:199], v[108:111]
	v_mfma_f32_16x16x32_bf16 v[100:103], v[148:151], v[204:207], v[100:103]
	v_mfma_f32_16x16x32_bf16 v[92:95], v[158:161], v[204:207], v[92:95]
	v_mfma_f32_16x16x32_bf16 v[84:87], v[148:151], v[212:215], v[84:87]
	v_mfma_f32_16x16x32_bf16 v[76:79], v[158:161], v[212:215], v[76:79]
	v_mfma_f32_16x16x32_bf16 v[112:115], v[162:165], v[184:187], v[112:115]
	v_mfma_f32_16x16x32_bf16 v[104:107], v[172:175], v[184:187], v[104:107]
	v_mfma_f32_16x16x32_bf16 v[96:99], v[162:165], v[192:195], v[96:99]
	v_mfma_f32_16x16x32_bf16 v[88:91], v[172:175], v[192:195], v[88:91]
	v_mfma_f32_16x16x32_bf16 v[80:83], v[162:165], v[200:203], v[80:83]
	v_mfma_f32_16x16x32_bf16 v[72:75], v[172:175], v[200:203], v[72:75]
	v_mfma_f32_16x16x32_bf16 v[68:71], v[162:165], v[208:211], v[68:71]
	v_mfma_f32_16x16x32_bf16 v[64:67], v[172:175], v[208:211], v[64:67]
	v_mfma_f32_16x16x32_bf16 v[112:115], v[168:171], v[188:191], v[112:115]
	v_mfma_f32_16x16x32_bf16 v[104:107], v[180:183], v[188:191], v[104:107]
	v_mfma_f32_16x16x32_bf16 v[96:99], v[168:171], v[196:199], v[96:99]
	v_mfma_f32_16x16x32_bf16 v[88:91], v[180:183], v[196:199], v[88:91]
	v_mfma_f32_16x16x32_bf16 v[80:83], v[168:171], v[204:207], v[80:83]
	v_mfma_f32_16x16x32_bf16 v[72:75], v[180:183], v[204:207], v[72:75]
	v_mfma_f32_16x16x32_bf16 v[68:71], v[168:171], v[212:215], v[68:71]
	v_mfma_f32_16x16x32_bf16 v[64:67], v[180:183], v[212:215], v[64:67]
	s_setprio 0
	s_barrier
	s_add_i32 s51, s51, s34
	v_lshl_add_u64 v[146:147], s[20:21], 0, v[144:145]
	s_mov_b32 m0, s51
	ds_read_b128 v[184:187], v143 offset:16384
	ds_read_b128 v[188:191], v143 offset:17408
	ds_read_b128 v[192:195], v143 offset:18432
	ds_read_b128 v[196:199], v143 offset:19456
	ds_read_b128 v[200:203], v143 offset:20480
	ds_read_b128 v[204:207], v143 offset:21504
	ds_read_b128 v[208:211], v143 offset:22528
	ds_read_b128 v[212:215], v143 offset:23552
	global_load_lds_dwordx4 v[146:147], off
	s_add_i32 m0, s51, 0x2000
	s_add_u32 s54, s20, 0x40000
	v_lshl_add_u64 v[176:177], s[20:21], 0, v[128:129]
	s_addc_u32 s55, s21, 0
	s_add_i32 s51, s53, s34
	global_load_lds_dwordx4 v[176:177], off
	v_lshl_add_u64 v[216:217], s[54:55], 0, v[144:145]
	s_mov_b32 m0, s51
	v_lshl_add_u64 v[218:219], s[22:23], 0, v[130:131]
	global_load_lds_dwordx4 v[216:217], off
	v_lshl_add_u64 v[216:217], s[54:55], 0, v[128:129]
	s_add_i32 m0, s51, 0x2000
	s_nop 0
	global_load_lds_dwordx4 v[216:217], off
	v_lshl_add_u64 v[216:217], s[22:23], 0, v[132:133]
	s_mov_b32 m0, s38
	s_nop 0
	global_load_lds_dwordx4 v[216:217], off
	s_mov_b32 m0, s39
	s_nop 0
	global_load_lds_dwordx4 v[218:219], off
	s_waitcnt vmcnt(8)
	s_waitcnt lgkmcnt(0)
	s_barrier
; #define PG8_STAGE(bufoff, gbase, voff) do { _Pragma("unroll") for (int _i = 0; _i < 2; ++_i) \
;         __builtin_amdgcn_global_load_lds((const unsigned*)((const char*)(gbase) + (voff)[_i]), (PG8_LAS unsigned*)(lds + (bufoff) + ldsw + _i * 8192), 16, 0, 0); } while (0)
; #define PG8_LDA(dst, b, h) do { _Pragma("unroll") for (int m = 0; m < 4; ++m) _Pragma("unroll") for (int k = 0; k < 2; ++k) dst[m][k] = *(const PG8_LAS bf16x8*)(lds + PG8_SA(b, h) + aoff + m * 2048 + k * 1024); } while (0)
; #define PG8_LDB(dst, b, h) do { _Pragma("unroll") for (int n = 0; n < 2; ++n) _Pragma("unroll") for (int k = 0; k < 2; ++k) dst[n][k] = *(const PG8_LAS bf16x8*)(lds + PG8_SB(b, h) + boff + n * 2048 + k * 1024); } while (0)
; #define PG8_MMA(ai, bj, At, Bt) do { __builtin_amdgcn_s_setprio(1); _Pragma("unroll") for (int m = 0; m < 4; ++m) _Pragma("unroll") for (int n = 0; n < 2; ++n) _Pragma("unroll") for (int k = 0; k < 2; ++k) \
;         acc[ai][bj][m][n] = __builtin_amdgcn_mfma_f32_16x16x32_bf16(Bt[n][k], At[m][k], acc[ai][bj][m][n], 0, 0, 0); __builtin_amdgcn_s_setprio(0); } while (0)
; #define PG8_WAIT_V(n) asm volatile("s_waitcnt vmcnt(" #n ")" ::: "memory")
; #define PG8_WAIT_L(n) asm volatile("s_waitcnt lgkmcnt(" #n ")" ::: "memory")
; #define PG8_BAR __builtin_amdgcn_s_barrier()
; #define PG8_SCHED __builtin_amdgcn_sched_barrier(0)
; template <class Epi, class Sched, int K, int lda, int ldb, bool ALIGN_EPI = true, bool SP2 = true>
; __device__ __forceinline__ void gemm_phase(PG8_LAS unsigned char* lds, const Sched& S, const Epi& E, const int wave_sgpr) {
;     ...
;             PG8_WAIT_V(8); PG8_WAIT_L(0); PG8_BAR; PG8_MMA(1, 0, At, B0); PG8_MMA(1, 1, At, B1); PG8_BAR; PG8_SCHED;
;             PG8_LDB(B0, 1, 0); PG8_LDB(B1, 1, 1); PG8_SCHED; PG8_LDA(At, 1, 0); PG8_STAGE(PG8_SA(0, 1), a2 + hstepA, voffA);
;             PG8_WAIT_V(8); PG8_WAIT_L(0); PG8_BAR; PG8_MMA(0, 0, At, B0); PG8_MMA(0, 1, At, B1); PG8_BAR; PG8_SCHED;
	s_setprio 1
	s_waitcnt lgkmcnt(0)
	v_mfma_f32_16x16x32_bf16 v[60:63], v[138:141], v[184:187], v[60:63]
	v_mfma_f32_16x16x32_bf16 v[56:59], v[152:155], v[184:187], v[56:59]
	v_mfma_f32_16x16x32_bf16 v[52:55], v[138:141], v[192:195], v[52:55]
	v_mfma_f32_16x16x32_bf16 v[44:47], v[152:155], v[192:195], v[44:47]
	v_mfma_f32_16x16x32_bf16 v[36:39], v[138:141], v[200:203], v[36:39]
	v_mfma_f32_16x16x32_bf16 v[28:31], v[152:155], v[200:203], v[28:31]
	v_mfma_f32_16x16x32_bf16 v[20:23], v[138:141], v[208:211], v[20:23]
	v_mfma_f32_16x16x32_bf16 v[12:15], v[152:155], v[208:211], v[12:15]
	v_mfma_f32_16x16x32_bf16 v[60:63], v[148:151], v[188:191], v[60:63]
	v_mfma_f32_16x16x32_bf16 v[56:59], v[158:161], v[188:191], v[56:59]
	v_mfma_f32_16x16x32_bf16 v[52:55], v[148:151], v[196:199], v[52:55]
	v_mfma_f32_16x16x32_bf16 v[44:47], v[158:161], v[196:199], v[44:47]
	v_mfma_f32_16x16x32_bf16 v[36:39], v[148:151], v[204:207], v[36:39]
	v_mfma_f32_16x16x32_bf16 v[28:31], v[158:161], v[204:207], v[28:31]
	v_mfma_f32_16x16x32_bf16 v[20:23], v[148:151], v[212:215], v[20:23]
	v_mfma_f32_16x16x32_bf16 v[12:15], v[158:161], v[212:215], v[12:15]
	v_mfma_f32_16x16x32_bf16 v[48:51], v[162:165], v[184:187], v[48:51]
	v_mfma_f32_16x16x32_bf16 v[40:43], v[172:175], v[184:187], v[40:43]
	v_mfma_f32_16x16x32_bf16 v[32:35], v[162:165], v[192:195], v[32:35]
	v_mfma_f32_16x16x32_bf16 v[24:27], v[172:175], v[192:195], v[24:27]
	v_mfma_f32_16x16x32_bf16 v[16:19], v[162:165], v[200:203], v[16:19]
	v_mfma_f32_16x16x32_bf16 v[8:11], v[172:175], v[200:203], v[8:11]
	v_mfma_f32_16x16x32_bf16 v[4:7], v[162:165], v[208:211], v[4:7]
	v_mfma_f32_16x16x32_bf16 v[0:3], v[172:175], v[208:211], v[0:3]
	v_mfma_f32_16x16x32_bf16 v[48:51], v[168:171], v[188:191], v[48:51]
	v_mfma_f32_16x16x32_bf16 v[40:43], v[180:183], v[188:191], v[40:43]
	v_mfma_f32_16x16x32_bf16 v[32:35], v[168:171], v[196:199], v[32:35]
	v_mfma_f32_16x16x32_bf16 v[24:27], v[180:183], v[196:199], v[24:27]
	v_mfma_f32_16x16x32_bf16 v[16:19], v[168:171], v[204:207], v[16:19]
	v_mfma_f32_16x16x32_bf16 v[8:11], v[180:183], v[204:207], v[8:11]
	v_mfma_f32_16x16x32_bf16 v[4:7], v[168:171], v[212:215], v[4:7]
	v_mfma_f32_16x16x32_bf16 v[0:3], v[180:183], v[212:215], v[0:3]
	s_setprio 0
	s_barrier
	s_add_i32 s51, 0, 0x18000
	v_add_u32_e32 v156, s51, v142
	s_add_i32 s53, 0, 0x1c000
	ds_read_b128 v[138:141], v156
	ds_read_b128 v[148:151], v156 offset:1024
	ds_read_b128 v[152:155], v156 offset:2048
	ds_read_b128 v[158:161], v156 offset:3072
	v_add_u32_e32 v156, s53, v142
	ds_read_b128 v[162:165], v156
	ds_read_b128 v[168:171], v156 offset:1024
	ds_read_b128 v[172:175], v156 offset:2048
	ds_read_b128 v[180:183], v156 offset:3072
	s_add_u32 s22, s22, 0x40000
	s_addc_u32 s23, s23, 0
	s_mov_b32 m0, s40
	v_lshl_add_u64 v[220:221], s[22:23], 0, v[132:133]
	ds_read_b128 v[184:187], v143 offset:32768
	ds_read_b128 v[188:191], v143 offset:33792
	ds_read_b128 v[192:195], v143 offset:34816
	ds_read_b128 v[196:199], v143 offset:35840
	ds_read_b128 v[200:203], v143 offset:36864
	ds_read_b128 v[204:207], v143 offset:37888
	ds_read_b128 v[208:211], v143 offset:38912
	ds_read_b128 v[212:215], v143 offset:39936
	global_load_lds_dwordx4 v[220:221], off
	v_lshl_add_u64 v[220:221], s[22:23], 0, v[130:131]
	s_mov_b32 m0, s41
	s_nop 0
	global_load_lds_dwordx4 v[220:221], off
	s_waitcnt vmcnt(8)
	s_waitcnt lgkmcnt(0)
	s_barrier
	s_setprio 1
	s_waitcnt lgkmcnt(0)
	v_mfma_f32_16x16x32_bf16 v[124:127], v[138:141], v[184:187], v[124:127]
	v_mfma_f32_16x16x32_bf16 v[120:123], v[152:155], v[184:187], v[120:123]
	v_mfma_f32_16x16x32_bf16 v[116:119], v[138:141], v[192:195], v[116:119]
	v_mfma_f32_16x16x32_bf16 v[108:111], v[152:155], v[192:195], v[108:111]
	v_mfma_f32_16x16x32_bf16 v[100:103], v[138:141], v[200:203], v[100:103]
	v_mfma_f32_16x16x32_bf16 v[92:95], v[152:155], v[200:203], v[92:95]
	v_mfma_f32_16x16x32_bf16 v[84:87], v[138:141], v[208:211], v[84:87]
	v_mfma_f32_16x16x32_bf16 v[76:79], v[152:155], v[208:211], v[76:79]
	v_mfma_f32_16x16x32_bf16 v[124:127], v[148:151], v[188:191], v[124:127]
	v_mfma_f32_16x16x32_bf16 v[120:123], v[158:161], v[188:191], v[120:123]
	v_mfma_f32_16x16x32_bf16 v[116:119], v[148:151], v[196:199], v[116:119]
	v_mfma_f32_16x16x32_bf16 v[108:111], v[158:161], v[196:199], v[108:111]
	v_mfma_f32_16x16x32_bf16 v[100:103], v[148:151], v[204:207], v[100:103]
	v_mfma_f32_16x16x32_bf16 v[92:95], v[158:161], v[204:207], v[92:95]
	v_mfma_f32_16x16x32_bf16 v[84:87], v[148:151], v[212:215], v[84:87]
	v_mfma_f32_16x16x32_bf16 v[76:79], v[158:161], v[212:215], v[76:79]
	v_mfma_f32_16x16x32_bf16 v[112:115], v[162:165], v[184:187], v[112:115]
	v_mfma_f32_16x16x32_bf16 v[104:107], v[172:175], v[184:187], v[104:107]
	v_mfma_f32_16x16x32_bf16 v[96:99], v[162:165], v[192:195], v[96:99]
	v_mfma_f32_16x16x32_bf16 v[88:91], v[172:175], v[192:195], v[88:91]
	v_mfma_f32_16x16x32_bf16 v[80:83], v[162:165], v[200:203], v[80:83]
	v_mfma_f32_16x16x32_bf16 v[72:75], v[172:175], v[200:203], v[72:75]
	v_mfma_f32_16x16x32_bf16 v[68:71], v[162:165], v[208:211], v[68:71]
	v_mfma_f32_16x16x32_bf16 v[64:67], v[172:175], v[208:211], v[64:67]
	v_mfma_f32_16x16x32_bf16 v[112:115], v[168:171], v[188:191], v[112:115]
	v_mfma_f32_16x16x32_bf16 v[104:107], v[180:183], v[188:191], v[104:107]
	v_mfma_f32_16x16x32_bf16 v[96:99], v[168:171], v[196:199], v[96:99]
	v_mfma_f32_16x16x32_bf16 v[88:91], v[180:183], v[196:199], v[88:91]
	v_mfma_f32_16x16x32_bf16 v[80:83], v[168:171], v[204:207], v[80:83]
	v_mfma_f32_16x16x32_bf16 v[72:75], v[180:183], v[204:207], v[72:75]
	v_mfma_f32_16x16x32_bf16 v[68:71], v[168:171], v[212:215], v[68:71]
	v_mfma_f32_16x16x32_bf16 v[64:67], v[180:183], v[212:215], v[64:67]
	s_setprio 0
	s_barrier
; #define PG8_STAGE(bufoff, gbase, voff) do { _Pragma("unroll") for (int _i = 0; _i < 2; ++_i) \
;         __builtin_amdgcn_global_load_lds((const unsigned*)((const char*)(gbase) + (voff)[_i]), (PG8_LAS unsigned*)(lds + (bufoff) + ldsw + _i * 8192), 16, 0, 0); } while (0)
; #define PG8_LDA(dst, b, h) do { _Pragma("unroll") for (int m = 0; m < 4; ++m) _Pragma("unroll") for (int k = 0; k < 2; ++k) dst[m][k] = *(const PG8_LAS bf16x8*)(lds + PG8_SA(b, h) + aoff + m * 2048 + k * 1024); } while (0)
; #define PG8_MMA(ai, bj, At, Bt) do { __builtin_amdgcn_s_setprio(1); _Pragma("unroll") for (int m = 0; m < 4; ++m) _Pragma("unroll") for (int n = 0; n < 2; ++n) _Pragma("unroll") for (int k = 0; k < 2; ++k) \
;         acc[ai][bj][m][n] = __builtin_amdgcn_mfma_f32_16x16x32_bf16(Bt[n][k], At[m][k], acc[ai][bj][m][n], 0, 0, 0); __builtin_amdgcn_s_setprio(0); } while (0)
; #define PG8_WAIT_V(n) asm volatile("s_waitcnt vmcnt(" #n ")" ::: "memory")
; #define PG8_WAIT_L(n) asm volatile("s_waitcnt lgkmcnt(" #n ")" ::: "memory")
; #define PG8_BAR __builtin_amdgcn_s_barrier()
; #define PG8_SCHED __builtin_amdgcn_sched_barrier(0)
; template <class Epi, class Sched, int K, int lda, int ldb, bool ALIGN_EPI = true, bool SP2 = true>
; __device__ __forceinline__ void gemm_phase(PG8_LAS unsigned char* lds, const Sched& S, const Epi& E, const int wave_sgpr) {
;     ...
;         for (int t = 0; t < nt; t += 2) {
;             const bool last = (t == nt - 2);
;     ...
;             PG8_LDA(At, 1, 1); PG8_STAGE(PG8_SB(1, 0), b3, voffB); PG8_STAGE(PG8_SB(1, 1), b3 + hstepB, voffB); PG8_STAGE(PG8_SA(1, 0), a3, voffA);
;             PG8_WAIT_V(8); PG8_WAIT_L(0); PG8_BAR; PG8_MMA(1, 0, At, B0); PG8_MMA(1, 1, At, B1); PG8_BAR; PG8_SCHED;
	s_add_i32 s22, s51, s34
	v_lshl_add_u64 v[146:147], v[146:147], 0, s[30:31]
	s_mov_b32 m0, s22
	ds_read_b128 v[184:187], v143 offset:49152
	ds_read_b128 v[188:191], v143 offset:50176
	ds_read_b128 v[192:195], v143 offset:51200
	ds_read_b128 v[196:199], v143 offset:52224
	ds_read_b128 v[200:203], v143 offset:53248
	ds_read_b128 v[204:207], v143 offset:54272
	ds_read_b128 v[208:211], v143 offset:55296
	ds_read_b128 v[212:215], v143 offset:56320
	global_load_lds_dwordx4 v[146:147], off
	s_add_i32 m0, s22, 0x2000
	s_add_u32 s20, s20, 0x40080
	v_lshl_add_u64 v[146:147], v[176:177], 0, s[30:31]
	s_addc_u32 s21, s21, 0
	s_add_i32 s22, s53, s34
	global_load_lds_dwordx4 v[146:147], off
	v_lshl_add_u64 v[146:147], s[20:21], 0, v[144:145]
	s_mov_b32 m0, s22
	s_nop 0
	global_load_lds_dwordx4 v[146:147], off
	v_lshl_add_u64 v[146:147], s[20:21], 0, v[128:129]
	s_add_i32 m0, s22, 0x2000
	s_nop 0
	global_load_lds_dwordx4 v[146:147], off
	v_lshl_add_u64 v[146:147], v[216:217], 0, s[30:31]
	s_mov_b32 m0, s44
	s_nop 0
	global_load_lds_dwordx4 v[146:147], off
	v_lshl_add_u64 v[146:147], v[218:219], 0, s[30:31]
	s_mov_b32 m0, s45
	s_nop 0
	global_load_lds_dwordx4 v[146:147], off
	s_waitcnt vmcnt(8)
	s_waitcnt lgkmcnt(0)
	s_barrier
	s_setprio 1
	s_waitcnt lgkmcnt(0)
	v_mfma_f32_16x16x32_bf16 v[60:63], v[138:141], v[184:187], v[60:63]
	v_mfma_f32_16x16x32_bf16 v[56:59], v[152:155], v[184:187], v[56:59]
	v_mfma_f32_16x16x32_bf16 v[52:55], v[138:141], v[192:195], v[52:55]
	v_mfma_f32_16x16x32_bf16 v[44:47], v[152:155], v[192:195], v[44:47]
	v_mfma_f32_16x16x32_bf16 v[36:39], v[138:141], v[200:203], v[36:39]
	v_mfma_f32_16x16x32_bf16 v[28:31], v[152:155], v[200:203], v[28:31]
	v_mfma_f32_16x16x32_bf16 v[20:23], v[138:141], v[208:211], v[20:23]
	v_mfma_f32_16x16x32_bf16 v[12:15], v[152:155], v[208:211], v[12:15]
	v_mfma_f32_16x16x32_bf16 v[60:63], v[148:151], v[188:191], v[60:63]
	v_mfma_f32_16x16x32_bf16 v[56:59], v[158:161], v[188:191], v[56:59]
	v_mfma_f32_16x16x32_bf16 v[52:55], v[148:151], v[196:199], v[52:55]
	v_mfma_f32_16x16x32_bf16 v[44:47], v[158:161], v[196:199], v[44:47]
	v_mfma_f32_16x16x32_bf16 v[36:39], v[148:151], v[204:207], v[36:39]
	v_mfma_f32_16x16x32_bf16 v[28:31], v[158:161], v[204:207], v[28:31]
	v_mfma_f32_16x16x32_bf16 v[20:23], v[148:151], v[212:215], v[20:23]
	v_mfma_f32_16x16x32_bf16 v[12:15], v[158:161], v[212:215], v[12:15]
	v_mfma_f32_16x16x32_bf16 v[48:51], v[162:165], v[184:187], v[48:51]
	v_mfma_f32_16x16x32_bf16 v[40:43], v[172:175], v[184:187], v[40:43]
	v_mfma_f32_16x16x32_bf16 v[32:35], v[162:165], v[192:195], v[32:35]
	v_mfma_f32_16x16x32_bf16 v[24:27], v[172:175], v[192:195], v[24:27]
	v_mfma_f32_16x16x32_bf16 v[16:19], v[162:165], v[200:203], v[16:19]
	v_mfma_f32_16x16x32_bf16 v[8:11], v[172:175], v[200:203], v[8:11]
	v_mfma_f32_16x16x32_bf16 v[4:7], v[162:165], v[208:211], v[4:7]
	v_mfma_f32_16x16x32_bf16 v[0:3], v[172:175], v[208:211], v[0:3]
	v_mfma_f32_16x16x32_bf16 v[48:51], v[168:171], v[188:191], v[48:51]
	v_mfma_f32_16x16x32_bf16 v[40:43], v[180:183], v[188:191], v[40:43]
	v_mfma_f32_16x16x32_bf16 v[32:35], v[168:171], v[196:199], v[32:35]
	v_mfma_f32_16x16x32_bf16 v[24:27], v[180:183], v[196:199], v[24:27]
	v_mfma_f32_16x16x32_bf16 v[16:19], v[168:171], v[204:207], v[16:19]
	v_mfma_f32_16x16x32_bf16 v[8:11], v[180:183], v[204:207], v[8:11]
	v_mfma_f32_16x16x32_bf16 v[4:7], v[168:171], v[212:215], v[4:7]
	v_mfma_f32_16x16x32_bf16 v[0:3], v[180:183], v[212:215], v[0:3]
	s_setprio 0
	s_barrier
	s_add_i32 s50, s50, 2
	s_add_u32 s9, s9, 0x100
	s_addc_u32 s13, s13, 0
	s_add_u32 s18, s18, 0x100
	s_addc_u32 s19, s19, 0
	s_cmp_gt_u32 s50, 13
	s_cbranch_scc0 .LBB0_190
	s_and_b64 vcc, exec, s[6:7]
	s_cbranch_vccz .LBB0_193
	s_barrier

; #define PG8_STAGE(bufoff, gbase, voff) do { _Pragma("unroll") for (int _i = 0; _i < 2; ++_i) \
;         __builtin_amdgcn_global_load_lds((const unsigned*)((const char*)(gbase) + (voff)[_i]), (PG8_LAS unsigned*)(lds + (bufoff) + ldsw + _i * 8192), 16, 0, 0); } while (0)
; #define PG8_LDA(dst, b, h) do { _Pragma("unroll") for (int m = 0; m < 4; ++m) _Pragma("unroll") for (int k = 0; k < 2; ++k) dst[m][k] = *(const PG8_LAS bf16x8*)(lds + PG8_SA(b, h) + aoff + m * 2048 + k * 1024); } while (0)
; #define PG8_LDB(dst, b, h) do { _Pragma("unroll") for (int n = 0; n < 2; ++n) _Pragma("unroll") for (int k = 0; k < 2; ++k) dst[n][k] = *(const PG8_LAS bf16x8*)(lds + PG8_SB(b, h) + boff + n * 2048 + k * 1024); } while (0)
; #define PG8_MMA(ai, bj, At, Bt) do { __builtin_amdgcn_s_setprio(1); _Pragma("unroll") for (int m = 0; m < 4; ++m) _Pragma("unroll") for (int n = 0; n < 2; ++n) _Pragma("unroll") for (int k = 0; k < 2; ++k) \
;         acc[ai][bj][m][n] = __builtin_amdgcn_mfma_f32_16x16x32_bf16(Bt[n][k], At[m][k], acc[ai][bj][m][n], 0, 0, 0); __builtin_amdgcn_s_setprio(0); } while (0)
; #define PG8_WAIT_V(n) asm volatile("s_waitcnt vmcnt(" #n ")" ::: "memory")
; #define PG8_WAIT_L(n) asm volatile("s_waitcnt lgkmcnt(" #n ")" ::: "memory")
; #define PG8_BAR __builtin_amdgcn_s_barrier()
; #define PG8_SCHED __builtin_amdgcn_sched_barrier(0)
; template <class Epi, class Sched, int K, int lda, int ldb, bool ALIGN_EPI = true, bool SP2 = true>
; __device__ __forceinline__ void gemm_phase(PG8_LAS unsigned char* lds, const Sched& S, const Epi& E, const int wave_sgpr) {
;     ...
;         for (int t = 0; t < nt; t += 2) {
;             const bool last = (t == nt - 2);
;             const char* a1 = cA + (size_t)(t + 1) * kstep;
;             const char* a2 = last ? nA : cA + (size_t)(t + 2) * kstep; const char* b2 = last ? nB : cB + (size_t)(t + 2) * kstep;
;             const char* a3 = a2 + kstep; const char* b3 = b2 + kstep;
;             if constexpr (SP2) {
;             PG8_LDB(B0, 0, 0); PG8_LDB(B1, 0, 1); PG8_SCHED; PG8_LDA(At, 0, 0); PG8_STAGE(PG8_SA(1, 1), a1 + hstepA, voffA);
;             PG8_WAIT_V(8); PG8_WAIT_L(0); PG8_BAR; PG8_MMA(0, 0, At, B0); PG8_MMA(0, 1, At, B1); PG8_BAR; PG8_SCHED;
;             PG8_LDA(At, 0, 1); PG8_STAGE(PG8_SB(0, 0), b2, voffB); PG8_STAGE(PG8_SB(0, 1), b2 + hstepB, voffB); PG8_STAGE(PG8_SA(0, 0), a2, voffA);
.LBB0_248:
	s_add_i32 s48, 0, 0x10000
	s_add_i32 s47, 0, 0x14000
	v_add_u32_e32 v146, s48, v136
	v_add_u32_e32 v147, s47, v136
	ds_read_b128 v[0:3], v146
	ds_read_b128 v[4:7], v146 offset:1024
	ds_read_b128 v[8:11], v146 offset:2048
	ds_read_b128 v[12:15], v146 offset:3072
	ds_read_b128 v[16:19], v147
	ds_read_b128 v[20:23], v147 offset:1024
	ds_read_b128 v[24:27], v147 offset:2048
	ds_read_b128 v[28:31], v147 offset:3072
	s_add_u32 s44, s16, 0x40080
	s_addc_u32 s45, s17, 0
	s_add_i32 s50, s25, 0xc000
	v_lshl_add_u64 v[64:65], s[44:45], 0, v[132:133]
	s_mov_b32 m0, s50
	s_add_i32 s43, s25, 0xe000
	ds_read_b128 v[32:35], v137
	ds_read_b128 v[36:39], v137 offset:1024
	ds_read_b128 v[40:43], v137 offset:2048
	ds_read_b128 v[44:47], v137 offset:3072
	ds_read_b128 v[48:51], v137 offset:4096
	ds_read_b128 v[52:55], v137 offset:5120
	ds_read_b128 v[56:59], v137 offset:6144
	ds_read_b128 v[60:63], v137 offset:7168
	global_load_lds_dwordx4 v[64:65], off
	v_lshl_add_u64 v[64:65], s[44:45], 0, v[130:131]
	s_mov_b32 m0, s43
	s_nop 0
	global_load_lds_dwordx4 v[64:65], off
	s_waitcnt vmcnt(8)
	s_waitcnt lgkmcnt(0)
	s_barrier
	s_setprio 1
	s_waitcnt lgkmcnt(0)
	v_mfma_f32_16x16x32_bf16 v[64:67], v[0:3], v[32:35], 0
	v_mfma_f32_16x16x32_bf16 v[68:71], v[8:11], v[32:35], 0
	v_mfma_f32_16x16x32_bf16 v[72:75], v[0:3], v[40:43], 0
	v_mfma_f32_16x16x32_bf16 v[76:79], v[8:11], v[40:43], 0
	v_mfma_f32_16x16x32_bf16 v[80:83], v[0:3], v[48:51], 0
	v_mfma_f32_16x16x32_bf16 v[84:87], v[8:11], v[48:51], 0
	v_mfma_f32_16x16x32_bf16 v[88:91], v[0:3], v[56:59], 0
	v_mfma_f32_16x16x32_bf16 v[92:95], v[8:11], v[56:59], 0
	v_mfma_f32_16x16x32_bf16 v[64:67], v[4:7], v[36:39], v[64:67]
	v_mfma_f32_16x16x32_bf16 v[68:71], v[12:15], v[36:39], v[68:71]
	v_mfma_f32_16x16x32_bf16 v[72:75], v[4:7], v[44:47], v[72:75]
	v_mfma_f32_16x16x32_bf16 v[76:79], v[12:15], v[44:47], v[76:79]
	v_mfma_f32_16x16x32_bf16 v[80:83], v[4:7], v[52:55], v[80:83]
	v_mfma_f32_16x16x32_bf16 v[84:87], v[12:15], v[52:55], v[84:87]
	v_mfma_f32_16x16x32_bf16 v[88:91], v[4:7], v[60:63], v[88:91]
	v_mfma_f32_16x16x32_bf16 v[92:95], v[12:15], v[60:63], v[92:95]
	v_mfma_f32_16x16x32_bf16 v[96:99], v[16:19], v[32:35], 0
	v_mfma_f32_16x16x32_bf16 v[32:35], v[24:27], v[32:35], 0
	v_mfma_f32_16x16x32_bf16 v[96:99], v[20:23], v[36:39], v[96:99]
	v_mfma_f32_16x16x32_bf16 v[32:35], v[28:31], v[36:39], v[32:35]
	v_mfma_f32_16x16x32_bf16 v[36:39], v[16:19], v[40:43], 0
	v_mfma_f32_16x16x32_bf16 v[40:43], v[24:27], v[40:43], 0
	v_mfma_f32_16x16x32_bf16 v[36:39], v[20:23], v[44:47], v[36:39]
	v_mfma_f32_16x16x32_bf16 v[40:43], v[28:31], v[44:47], v[40:43]
	v_mfma_f32_16x16x32_bf16 v[44:47], v[16:19], v[48:51], 0
	v_mfma_f32_16x16x32_bf16 v[48:51], v[24:27], v[48:51], 0
	v_mfma_f32_16x16x32_bf16 v[44:47], v[20:23], v[52:55], v[44:47]
	v_mfma_f32_16x16x32_bf16 v[48:51], v[28:31], v[52:55], v[48:51]
	v_mfma_f32_16x16x32_bf16 v[52:55], v[16:19], v[56:59], 0
	v_mfma_f32_16x16x32_bf16 v[56:59], v[24:27], v[56:59], 0
	v_mfma_f32_16x16x32_bf16 v[52:55], v[20:23], v[60:63], v[52:55]
	v_mfma_f32_16x16x32_bf16 v[56:59], v[28:31], v[60:63], v[56:59]
	s_setprio 0
	s_barrier
	s_add_i32 s48, s48, s24
	v_lshl_add_u64 v[134:135], s[18:19], 0, v[144:145]
	s_mov_b64 s[56:57], 0x100
	s_add_i32 s44, s48, 0x2000
	v_lshl_add_u64 v[138:139], v[134:135], 0, s[56:57]
	s_mov_b32 m0, s48
	v_lshl_add_u64 v[142:143], s[18:19], 0, v[128:129]
	s_add_u32 s54, s18, 0x10100
	ds_read_b128 v[60:63], v137 offset:16384
	ds_read_b128 v[100:103], v137 offset:17408
	ds_read_b128 v[104:107], v137 offset:18432
	ds_read_b128 v[108:111], v137 offset:19456
	ds_read_b128 v[112:115], v137 offset:20480
	ds_read_b128 v[116:119], v137 offset:21504
	ds_read_b128 v[120:123], v137 offset:22528
	ds_read_b128 v[124:127], v137 offset:23552
	global_load_lds_dwordx4 v[138:139], off
	v_lshl_add_u64 v[138:139], v[142:143], 0, s[56:57]
	s_mov_b32 m0, s44
	s_addc_u32 s55, s19, 0
	s_add_i32 s45, s47, s24
	global_load_lds_dwordx4 v[138:139], off
	v_lshl_add_u64 v[138:139], s[54:55], 0, v[144:145]
	s_mov_b32 m0, s45
	s_add_i32 s47, s45, 0x2000
	global_load_lds_dwordx4 v[138:139], off
	v_lshl_add_u64 v[138:139], s[54:55], 0, v[128:129]
	s_mov_b32 m0, s47
	v_lshl_add_u64 v[148:149], s[16:17], 0, v[132:133]
	global_load_lds_dwordx4 v[138:139], off
	v_lshl_add_u64 v[138:139], v[148:149], 0, s[56:57]
	s_mov_b32 m0, s25
	v_lshl_add_u64 v[150:151], s[16:17], 0, v[130:131]
	global_load_lds_dwordx4 v[138:139], off
	v_lshl_add_u64 v[138:139], v[150:151], 0, s[56:57]
	s_mov_b32 m0, s28
	s_nop 0
	global_load_lds_dwordx4 v[138:139], off
	s_waitcnt vmcnt(8)
	s_waitcnt lgkmcnt(0)
	s_barrier
; #define PG8_STAGE(bufoff, gbase, voff) do { _Pragma("unroll") for (int _i = 0; _i < 2; ++_i) \
;         __builtin_amdgcn_global_load_lds((const unsigned*)((const char*)(gbase) + (voff)[_i]), (PG8_LAS unsigned*)(lds + (bufoff) + ldsw + _i * 8192), 16, 0, 0); } while (0)
; #define PG8_LDA(dst, b, h) do { _Pragma("unroll") for (int m = 0; m < 4; ++m) _Pragma("unroll") for (int k = 0; k < 2; ++k) dst[m][k] = *(const PG8_LAS bf16x8*)(lds + PG8_SA(b, h) + aoff + m * 2048 + k * 1024); } while (0)
; #define PG8_LDB(dst, b, h) do { _Pragma("unroll") for (int n = 0; n < 2; ++n) _Pragma("unroll") for (int k = 0; k < 2; ++k) dst[n][k] = *(const PG8_LAS bf16x8*)(lds + PG8_SB(b, h) + boff + n * 2048 + k * 1024); } while (0)
; #define PG8_MMA(ai, bj, At, Bt) do { __builtin_amdgcn_s_setprio(1); _Pragma("unroll") for (int m = 0; m < 4; ++m) _Pragma("unroll") for (int n = 0; n < 2; ++n) _Pragma("unroll") for (int k = 0; k < 2; ++k) \
;         acc[ai][bj][m][n] = __builtin_amdgcn_mfma_f32_16x16x32_bf16(Bt[n][k], At[m][k], acc[ai][bj][m][n], 0, 0, 0); __builtin_amdgcn_s_setprio(0); } while (0)
; #define PG8_WAIT_V(n) asm volatile("s_waitcnt vmcnt(" #n ")" ::: "memory")
; #define PG8_WAIT_L(n) asm volatile("s_waitcnt lgkmcnt(" #n ")" ::: "memory")
; #define PG8_BAR __builtin_amdgcn_s_barrier()
; #define PG8_SCHED __builtin_amdgcn_sched_barrier(0)
; template <class Epi, class Sched, int K, int lda, int ldb, bool ALIGN_EPI = true, bool SP2 = true>
; __device__ __forceinline__ void gemm_phase(PG8_LAS unsigned char* lds, const Sched& S, const Epi& E, const int wave_sgpr) {
;     ...
;             PG8_WAIT_V(8); PG8_WAIT_L(0); PG8_BAR; PG8_MMA(1, 0, At, B0); PG8_MMA(1, 1, At, B1); PG8_BAR; PG8_SCHED;
;             PG8_LDB(B0, 1, 0); PG8_LDB(B1, 1, 1); PG8_SCHED; PG8_LDA(At, 1, 0); PG8_STAGE(PG8_SA(0, 1), a2 + hstepA, voffA);
;             PG8_WAIT_V(8); PG8_WAIT_L(0); PG8_BAR; PG8_MMA(0, 0, At, B0); PG8_MMA(0, 1, At, B1); PG8_BAR; PG8_SCHED;
	s_setprio 1
	s_waitcnt lgkmcnt(0)
	v_mfma_f32_16x16x32_bf16 v[138:141], v[0:3], v[60:63], 0
	v_mfma_f32_16x16x32_bf16 v[166:169], v[0:3], v[104:107], 0
	v_mfma_f32_16x16x32_bf16 v[174:177], v[0:3], v[112:115], 0
	v_mfma_f32_16x16x32_bf16 v[0:3], v[0:3], v[120:123], 0
	v_mfma_f32_16x16x32_bf16 v[138:141], v[4:7], v[100:103], v[138:141]
	v_mfma_f32_16x16x32_bf16 v[166:169], v[4:7], v[108:111], v[166:169]
	v_mfma_f32_16x16x32_bf16 v[174:177], v[4:7], v[116:119], v[174:177]
	v_mfma_f32_16x16x32_bf16 v[0:3], v[4:7], v[124:127], v[0:3]
	v_mfma_f32_16x16x32_bf16 v[4:7], v[8:11], v[120:123], 0
	v_mfma_f32_16x16x32_bf16 v[162:165], v[8:11], v[60:63], 0
	v_mfma_f32_16x16x32_bf16 v[170:173], v[8:11], v[104:107], 0
	v_mfma_f32_16x16x32_bf16 v[188:191], v[8:11], v[112:115], 0
	v_mfma_f32_16x16x32_bf16 v[4:7], v[12:15], v[124:127], v[4:7]
	v_mfma_f32_16x16x32_bf16 v[162:165], v[12:15], v[100:103], v[162:165]
	v_mfma_f32_16x16x32_bf16 v[170:173], v[12:15], v[108:111], v[170:173]
	v_mfma_f32_16x16x32_bf16 v[188:191], v[12:15], v[116:119], v[188:191]
	v_mfma_f32_16x16x32_bf16 v[8:11], v[16:19], v[60:63], 0
	v_mfma_f32_16x16x32_bf16 v[12:15], v[24:27], v[60:63], 0
	v_mfma_f32_16x16x32_bf16 v[8:11], v[20:23], v[100:103], v[8:11]
	v_mfma_f32_16x16x32_bf16 v[12:15], v[28:31], v[100:103], v[12:15]
	v_mfma_f32_16x16x32_bf16 v[60:63], v[16:19], v[104:107], 0
	v_mfma_f32_16x16x32_bf16 v[100:103], v[24:27], v[104:107], 0
	v_mfma_f32_16x16x32_bf16 v[104:107], v[16:19], v[112:115], 0
	v_mfma_f32_16x16x32_bf16 v[16:19], v[16:19], v[120:123], 0
	v_mfma_f32_16x16x32_bf16 v[60:63], v[20:23], v[108:111], v[60:63]
	v_mfma_f32_16x16x32_bf16 v[100:103], v[28:31], v[108:111], v[100:103]
	v_mfma_f32_16x16x32_bf16 v[104:107], v[20:23], v[116:119], v[104:107]
	v_mfma_f32_16x16x32_bf16 v[108:111], v[24:27], v[112:115], 0
	v_mfma_f32_16x16x32_bf16 v[16:19], v[20:23], v[124:127], v[16:19]
	v_mfma_f32_16x16x32_bf16 v[20:23], v[24:27], v[120:123], 0
	v_mfma_f32_16x16x32_bf16 v[108:111], v[28:31], v[116:119], v[108:111]
	v_mfma_f32_16x16x32_bf16 v[20:23], v[28:31], v[124:127], v[20:23]
	s_setprio 0
	s_barrier
	s_add_i32 s51, 0, 0x18000
	s_add_i32 s53, 0, 0x1c000
	v_add_u32_e32 v154, s51, v136
	v_add_u32_e32 v155, s53, v136
	ds_read_b128 v[24:27], v154
	ds_read_b128 v[28:31], v154 offset:1024
	ds_read_b128 v[112:115], v154 offset:2048
	ds_read_b128 v[116:119], v154 offset:3072
	ds_read_b128 v[120:123], v155
	ds_read_b128 v[124:127], v155 offset:1024
	ds_read_b128 v[192:195], v155 offset:2048
	ds_read_b128 v[196:199], v155 offset:3072
	s_add_u32 s54, s16, 0x40100
	s_addc_u32 s55, s17, 0
	s_mov_b32 m0, s29
	v_lshl_add_u64 v[152:153], s[54:55], 0, v[132:133]
	ds_read_b128 v[200:203], v137 offset:32768
	ds_read_b128 v[204:207], v137 offset:33792
	ds_read_b128 v[208:211], v137 offset:34816
	ds_read_b128 v[212:215], v137 offset:35840
	ds_read_b128 v[216:219], v137 offset:36864
	ds_read_b128 v[220:223], v137 offset:37888
	ds_read_b128 v[224:227], v137 offset:38912
	ds_read_b128 v[228:231], v137 offset:39936
	global_load_lds_dwordx4 v[152:153], off
	v_lshl_add_u64 v[152:153], s[54:55], 0, v[130:131]
	s_mov_b32 m0, s34
	s_nop 0
	global_load_lds_dwordx4 v[152:153], off
	s_waitcnt vmcnt(8)
	s_waitcnt lgkmcnt(0)
	s_barrier
	s_setprio 1
	s_waitcnt lgkmcnt(0)
	v_mfma_f32_16x16x32_bf16 v[64:67], v[24:27], v[200:203], v[64:67]
	v_mfma_f32_16x16x32_bf16 v[68:71], v[112:115], v[200:203], v[68:71]
	v_mfma_f32_16x16x32_bf16 v[72:75], v[24:27], v[208:211], v[72:75]
	v_mfma_f32_16x16x32_bf16 v[76:79], v[112:115], v[208:211], v[76:79]
	v_mfma_f32_16x16x32_bf16 v[80:83], v[24:27], v[216:219], v[80:83]
	v_mfma_f32_16x16x32_bf16 v[84:87], v[112:115], v[216:219], v[84:87]
	v_mfma_f32_16x16x32_bf16 v[88:91], v[24:27], v[224:227], v[88:91]
	v_mfma_f32_16x16x32_bf16 v[92:95], v[112:115], v[224:227], v[92:95]
	v_mfma_f32_16x16x32_bf16 v[64:67], v[28:31], v[204:207], v[64:67]
	v_mfma_f32_16x16x32_bf16 v[68:71], v[116:119], v[204:207], v[68:71]
	v_mfma_f32_16x16x32_bf16 v[72:75], v[28:31], v[212:215], v[72:75]
	v_mfma_f32_16x16x32_bf16 v[76:79], v[116:119], v[212:215], v[76:79]
	v_mfma_f32_16x16x32_bf16 v[80:83], v[28:31], v[220:223], v[80:83]
	v_mfma_f32_16x16x32_bf16 v[84:87], v[116:119], v[220:223], v[84:87]
	v_mfma_f32_16x16x32_bf16 v[88:91], v[28:31], v[228:231], v[88:91]
	v_mfma_f32_16x16x32_bf16 v[92:95], v[116:119], v[228:231], v[92:95]
	v_mfma_f32_16x16x32_bf16 v[96:99], v[120:123], v[200:203], v[96:99]
	v_mfma_f32_16x16x32_bf16 v[32:35], v[192:195], v[200:203], v[32:35]
	v_mfma_f32_16x16x32_bf16 v[36:39], v[120:123], v[208:211], v[36:39]
	v_mfma_f32_16x16x32_bf16 v[40:43], v[192:195], v[208:211], v[40:43]
	v_mfma_f32_16x16x32_bf16 v[44:47], v[120:123], v[216:219], v[44:47]
	v_mfma_f32_16x16x32_bf16 v[48:51], v[192:195], v[216:219], v[48:51]
	v_mfma_f32_16x16x32_bf16 v[52:55], v[120:123], v[224:227], v[52:55]
	v_mfma_f32_16x16x32_bf16 v[56:59], v[192:195], v[224:227], v[56:59]
	v_mfma_f32_16x16x32_bf16 v[96:99], v[124:127], v[204:207], v[96:99]
	v_mfma_f32_16x16x32_bf16 v[32:35], v[196:199], v[204:207], v[32:35]
	v_mfma_f32_16x16x32_bf16 v[36:39], v[124:127], v[212:215], v[36:39]
	v_mfma_f32_16x16x32_bf16 v[40:43], v[196:199], v[212:215], v[40:43]
	v_mfma_f32_16x16x32_bf16 v[44:47], v[124:127], v[220:223], v[44:47]
	v_mfma_f32_16x16x32_bf16 v[48:51], v[196:199], v[220:223], v[48:51]
	v_mfma_f32_16x16x32_bf16 v[52:55], v[124:127], v[228:231], v[52:55]
	v_mfma_f32_16x16x32_bf16 v[56:59], v[196:199], v[228:231], v[56:59]
	s_setprio 0
	s_barrier
; #define PG8_STAGE(bufoff, gbase, voff) do { _Pragma("unroll") for (int _i = 0; _i < 2; ++_i) \
;         __builtin_amdgcn_global_load_lds((const unsigned*)((const char*)(gbase) + (voff)[_i]), (PG8_LAS unsigned*)(lds + (bufoff) + ldsw + _i * 8192), 16, 0, 0); } while (0)
; #define PG8_LDA(dst, b, h) do { _Pragma("unroll") for (int m = 0; m < 4; ++m) _Pragma("unroll") for (int k = 0; k < 2; ++k) dst[m][k] = *(const PG8_LAS bf16x8*)(lds + PG8_SA(b, h) + aoff + m * 2048 + k * 1024); } while (0)
; #define PG8_LDB(dst, b, h) do { _Pragma("unroll") for (int n = 0; n < 2; ++n) _Pragma("unroll") for (int k = 0; k < 2; ++k) dst[n][k] = *(const PG8_LAS bf16x8*)(lds + PG8_SB(b, h) + boff + n * 2048 + k * 1024); } while (0)
; #define PG8_MMA(ai, bj, At, Bt) do { __builtin_amdgcn_s_setprio(1); _Pragma("unroll") for (int m = 0; m < 4; ++m) _Pragma("unroll") for (int n = 0; n < 2; ++n) _Pragma("unroll") for (int k = 0; k < 2; ++k) \
;         acc[ai][bj][m][n] = __builtin_amdgcn_mfma_f32_16x16x32_bf16(Bt[n][k], At[m][k], acc[ai][bj][m][n], 0, 0, 0); __builtin_amdgcn_s_setprio(0); } while (0)
; #define PG8_WAIT_V(n) asm volatile("s_waitcnt vmcnt(" #n ")" ::: "memory")
; #define PG8_WAIT_L(n) asm volatile("s_waitcnt lgkmcnt(" #n ")" ::: "memory")
; #define PG8_BAR __builtin_amdgcn_s_barrier()
; #define PG8_SCHED __builtin_amdgcn_sched_barrier(0)
; template <class Epi, class Sched, int K, int lda, int ldb, bool ALIGN_EPI = true, bool SP2 = true>
; __device__ __forceinline__ void gemm_phase(PG8_LAS unsigned char* lds, const Sched& S, const Epi& E, const int wave_sgpr) {
;     ...
;             PG8_LDB(B0, 0, 0); PG8_LDB(B1, 0, 1); PG8_SCHED; PG8_LDA(At, 0, 0); PG8_STAGE(PG8_SA(1, 1), a1 + hstepA, voffA);
;             PG8_WAIT_V(8); PG8_WAIT_L(0); PG8_BAR; PG8_MMA(0, 0, At, B0); PG8_MMA(0, 1, At, B1); PG8_BAR; PG8_SCHED;
;     ...
;             PG8_LDA(At, 1, 1); PG8_STAGE(PG8_SB(1, 0), b3, voffB); PG8_STAGE(PG8_SB(1, 1), b3 + hstepB, voffB); PG8_STAGE(PG8_SA(1, 0), a3, voffA);
;             PG8_WAIT_V(8); PG8_WAIT_L(0); PG8_BAR; PG8_MMA(1, 0, At, B0); PG8_MMA(1, 1, At, B1); PG8_BAR; PG8_SCHED;
	s_add_i32 s51, s51, s24
	s_mov_b64 s[56:57], 0x180
	s_add_i32 s49, s51, 0x2000
	v_lshl_add_u64 v[134:135], v[134:135], 0, s[56:57]
	s_mov_b32 m0, s51
	s_add_u32 s54, s18, 0x10180
	ds_read_b128 v[200:203], v137 offset:49152
	ds_read_b128 v[204:207], v137 offset:50176
	ds_read_b128 v[208:211], v137 offset:51200
	ds_read_b128 v[212:215], v137 offset:52224
	ds_read_b128 v[216:219], v137 offset:53248
	ds_read_b128 v[220:223], v137 offset:54272
	ds_read_b128 v[224:227], v137 offset:55296
	ds_read_b128 v[228:231], v137 offset:56320
	global_load_lds_dwordx4 v[134:135], off
	v_lshl_add_u64 v[134:135], v[142:143], 0, s[56:57]
	s_mov_b32 m0, s49
	s_addc_u32 s55, s19, 0
	s_add_i32 s18, s53, s24
	global_load_lds_dwordx4 v[134:135], off
	v_lshl_add_u64 v[134:135], s[54:55], 0, v[144:145]
	s_mov_b32 m0, s18
	s_add_i32 s19, s18, 0x2000
	global_load_lds_dwordx4 v[134:135], off
	v_lshl_add_u64 v[134:135], s[54:55], 0, v[128:129]
	s_mov_b32 m0, s19
	s_nop 0
	global_load_lds_dwordx4 v[134:135], off
	v_lshl_add_u64 v[134:135], v[148:149], 0, s[56:57]
	s_mov_b32 m0, s38
	s_nop 0
	global_load_lds_dwordx4 v[134:135], off
	v_lshl_add_u64 v[134:135], v[150:151], 0, s[56:57]
	s_mov_b32 m0, s39
	s_nop 0
	global_load_lds_dwordx4 v[134:135], off
	s_waitcnt vmcnt(8)
	s_waitcnt lgkmcnt(0)
	s_barrier
	s_setprio 1
	s_waitcnt lgkmcnt(0)
	v_mfma_f32_16x16x32_bf16 v[0:3], v[24:27], v[224:227], v[0:3]
	v_mfma_f32_16x16x32_bf16 v[4:7], v[112:115], v[224:227], v[4:7]
	v_mfma_f32_16x16x32_bf16 v[138:141], v[24:27], v[200:203], v[138:141]
	v_mfma_f32_16x16x32_bf16 v[162:165], v[112:115], v[200:203], v[162:165]
	v_mfma_f32_16x16x32_bf16 v[166:169], v[24:27], v[208:211], v[166:169]
	v_mfma_f32_16x16x32_bf16 v[170:173], v[112:115], v[208:211], v[170:173]
	v_mfma_f32_16x16x32_bf16 v[174:177], v[24:27], v[216:219], v[174:177]
	v_mfma_f32_16x16x32_bf16 v[188:191], v[112:115], v[216:219], v[188:191]
	v_mfma_f32_16x16x32_bf16 v[0:3], v[28:31], v[228:231], v[0:3]
	v_mfma_f32_16x16x32_bf16 v[4:7], v[116:119], v[228:231], v[4:7]
	v_mfma_f32_16x16x32_bf16 v[138:141], v[28:31], v[204:207], v[138:141]
	v_mfma_f32_16x16x32_bf16 v[162:165], v[116:119], v[204:207], v[162:165]
	v_mfma_f32_16x16x32_bf16 v[166:169], v[28:31], v[212:215], v[166:169]
	v_mfma_f32_16x16x32_bf16 v[170:173], v[116:119], v[212:215], v[170:173]
	v_mfma_f32_16x16x32_bf16 v[174:177], v[28:31], v[220:223], v[174:177]
	v_mfma_f32_16x16x32_bf16 v[188:191], v[116:119], v[220:223], v[188:191]
	v_mfma_f32_16x16x32_bf16 v[8:11], v[120:123], v[200:203], v[8:11]
	v_mfma_f32_16x16x32_bf16 v[12:15], v[192:195], v[200:203], v[12:15]
	v_mfma_f32_16x16x32_bf16 v[24:27], v[120:123], v[208:211], v[60:63]
	v_mfma_f32_16x16x32_bf16 v[28:31], v[192:195], v[208:211], v[100:103]
	v_mfma_f32_16x16x32_bf16 v[60:63], v[120:123], v[216:219], v[104:107]
	v_mfma_f32_16x16x32_bf16 v[100:103], v[192:195], v[216:219], v[108:111]
	v_mfma_f32_16x16x32_bf16 v[16:19], v[120:123], v[224:227], v[16:19]
	v_mfma_f32_16x16x32_bf16 v[20:23], v[192:195], v[224:227], v[20:23]
	v_mfma_f32_16x16x32_bf16 v[8:11], v[124:127], v[204:207], v[8:11]
	v_mfma_f32_16x16x32_bf16 v[12:15], v[196:199], v[204:207], v[12:15]
	v_mfma_f32_16x16x32_bf16 v[24:27], v[124:127], v[212:215], v[24:27]
	v_mfma_f32_16x16x32_bf16 v[28:31], v[196:199], v[212:215], v[28:31]
	v_mfma_f32_16x16x32_bf16 v[60:63], v[124:127], v[220:223], v[60:63]
	v_mfma_f32_16x16x32_bf16 v[100:103], v[196:199], v[220:223], v[100:103]
	v_mfma_f32_16x16x32_bf16 v[16:19], v[124:127], v[228:231], v[16:19]
	v_mfma_f32_16x16x32_bf16 v[20:23], v[196:199], v[228:231], v[20:23]
	s_setprio 0
	s_barrier
	ds_read_b128 v[104:107], v146
	ds_read_b128 v[108:111], v146 offset:1024
	ds_read_b128 v[112:115], v146 offset:2048
	ds_read_b128 v[116:119], v146 offset:3072
	ds_read_b128 v[120:123], v147
	ds_read_b128 v[124:127], v147 offset:1024
	ds_read_b128 v[192:195], v147 offset:2048
	ds_read_b128 v[196:199], v147 offset:3072
	s_add_u32 s16, s16, 0x40180
	s_addc_u32 s17, s17, 0
	s_mov_b32 m0, s50
	v_lshl_add_u64 v[134:135], s[16:17], 0, v[132:133]
	ds_read_b128 v[200:203], v137
	ds_read_b128 v[204:207], v137 offset:1024
	ds_read_b128 v[208:211], v137 offset:2048
	ds_read_b128 v[212:215], v137 offset:3072
	ds_read_b128 v[216:219], v137 offset:4096
	ds_read_b128 v[220:223], v137 offset:5120
	ds_read_b128 v[224:227], v137 offset:6144
	ds_read_b128 v[228:231], v137 offset:7168
	global_load_lds_dwordx4 v[134:135], off
	v_lshl_add_u64 v[134:135], s[16:17], 0, v[130:131]
	s_mov_b32 m0, s43
	s_nop 0
	global_load_lds_dwordx4 v[134:135], off
	s_waitcnt vmcnt(8)
	s_waitcnt lgkmcnt(0)
	s_barrier
; #define PG8_STAGE(bufoff, gbase, voff) do { _Pragma("unroll") for (int _i = 0; _i < 2; ++_i) \
;         __builtin_amdgcn_global_load_lds((const unsigned*)((const char*)(gbase) + (voff)[_i]), (PG8_LAS unsigned*)(lds + (bufoff) + ldsw + _i * 8192), 16, 0, 0); } while (0)
; #define PG8_LDA(dst, b, h) do { _Pragma("unroll") for (int m = 0; m < 4; ++m) _Pragma("unroll") for (int k = 0; k < 2; ++k) dst[m][k] = *(const PG8_LAS bf16x8*)(lds + PG8_SA(b, h) + aoff + m * 2048 + k * 1024); } while (0)
; #define PG8_MMA(ai, bj, At, Bt) do { __builtin_amdgcn_s_setprio(1); _Pragma("unroll") for (int m = 0; m < 4; ++m) _Pragma("unroll") for (int n = 0; n < 2; ++n) _Pragma("unroll") for (int k = 0; k < 2; ++k) \
;         acc[ai][bj][m][n] = __builtin_amdgcn_mfma_f32_16x16x32_bf16(Bt[n][k], At[m][k], acc[ai][bj][m][n], 0, 0, 0); __builtin_amdgcn_s_setprio(0); } while (0)
; #define PG8_WAIT_V(n) asm volatile("s_waitcnt vmcnt(" #n ")" ::: "memory")
; #define PG8_WAIT_L(n) asm volatile("s_waitcnt lgkmcnt(" #n ")" ::: "memory")
; #define PG8_BAR __builtin_amdgcn_s_barrier()
; #define PG8_SCHED __builtin_amdgcn_sched_barrier(0)
; template <class Epi, class Sched, int K, int lda, int ldb, bool ALIGN_EPI = true, bool SP2 = true>
; __device__ __forceinline__ void gemm_phase(PG8_LAS unsigned char* lds, const Sched& S, const Epi& E, const int wave_sgpr) {
;     ...
;             PG8_WAIT_V(8); PG8_WAIT_L(0); PG8_BAR; PG8_MMA(0, 0, At, B0); PG8_MMA(0, 1, At, B1); PG8_BAR; PG8_SCHED;
;             PG8_LDA(At, 0, 1); PG8_STAGE(PG8_SB(0, 0), b2, voffB); PG8_STAGE(PG8_SB(0, 1), b2 + hstepB, voffB); PG8_STAGE(PG8_SA(0, 0), a2, voffA);
;             PG8_WAIT_V(8); PG8_WAIT_L(0); PG8_BAR; PG8_MMA(1, 0, At, B0); PG8_MMA(1, 1, At, B1); PG8_BAR; PG8_SCHED;
	s_setprio 1
	s_waitcnt lgkmcnt(0)
	v_mfma_f32_16x16x32_bf16 v[64:67], v[104:107], v[200:203], v[64:67]
	v_mfma_f32_16x16x32_bf16 v[68:71], v[112:115], v[200:203], v[68:71]
	v_mfma_f32_16x16x32_bf16 v[72:75], v[104:107], v[208:211], v[72:75]
	v_mfma_f32_16x16x32_bf16 v[76:79], v[112:115], v[208:211], v[76:79]
	v_mfma_f32_16x16x32_bf16 v[80:83], v[104:107], v[216:219], v[80:83]
	v_mfma_f32_16x16x32_bf16 v[84:87], v[112:115], v[216:219], v[84:87]
	v_mfma_f32_16x16x32_bf16 v[88:91], v[104:107], v[224:227], v[88:91]
	v_mfma_f32_16x16x32_bf16 v[64:67], v[108:111], v[204:207], v[64:67]
	v_mfma_f32_16x16x32_bf16 v[68:71], v[116:119], v[204:207], v[68:71]
	v_mfma_f32_16x16x32_bf16 v[72:75], v[108:111], v[212:215], v[72:75]
	v_mfma_f32_16x16x32_bf16 v[76:79], v[116:119], v[212:215], v[76:79]
	v_mfma_f32_16x16x32_bf16 v[80:83], v[108:111], v[220:223], v[80:83]
	v_mfma_f32_16x16x32_bf16 v[84:87], v[116:119], v[220:223], v[84:87]
	v_mfma_f32_16x16x32_bf16 v[232:235], v[108:111], v[228:231], v[88:91]
	v_mfma_f32_16x16x32_bf16 v[88:91], v[112:115], v[224:227], v[92:95]
	v_mfma_f32_16x16x32_bf16 v[236:239], v[116:119], v[228:231], v[88:91]
	v_mfma_f32_16x16x32_bf16 v[88:91], v[120:123], v[200:203], v[96:99]
	v_mfma_f32_16x16x32_bf16 v[32:35], v[192:195], v[200:203], v[32:35]
	v_mfma_f32_16x16x32_bf16 v[36:39], v[120:123], v[208:211], v[36:39]
	v_mfma_f32_16x16x32_bf16 v[40:43], v[192:195], v[208:211], v[40:43]
	v_mfma_f32_16x16x32_bf16 v[44:47], v[120:123], v[216:219], v[44:47]
	v_mfma_f32_16x16x32_bf16 v[48:51], v[192:195], v[216:219], v[48:51]
	v_mfma_f32_16x16x32_bf16 v[52:55], v[120:123], v[224:227], v[52:55]
	v_mfma_f32_16x16x32_bf16 v[56:59], v[192:195], v[224:227], v[56:59]
	v_mfma_f32_16x16x32_bf16 v[96:99], v[124:127], v[204:207], v[88:91]
	v_mfma_f32_16x16x32_bf16 v[32:35], v[196:199], v[204:207], v[32:35]
	v_mfma_f32_16x16x32_bf16 v[36:39], v[124:127], v[212:215], v[36:39]
	v_mfma_f32_16x16x32_bf16 v[40:43], v[196:199], v[212:215], v[40:43]
	v_mfma_f32_16x16x32_bf16 v[44:47], v[124:127], v[220:223], v[44:47]
	v_mfma_f32_16x16x32_bf16 v[48:51], v[196:199], v[220:223], v[48:51]
	v_mfma_f32_16x16x32_bf16 v[52:55], v[124:127], v[228:231], v[52:55]
	v_mfma_f32_16x16x32_bf16 v[56:59], v[196:199], v[228:231], v[56:59]
	s_setprio 0
	s_barrier
	s_mov_b32 m0, s48
	v_lshl_add_u64 v[134:135], s[12:13], 0, v[144:145]
	s_add_u32 s16, s12, 0x10000
	ds_read_b128 v[88:91], v137 offset:16384
	ds_read_b128 v[92:95], v137 offset:17408
	ds_read_b128 v[200:203], v137 offset:18432
	ds_read_b128 v[204:207], v137 offset:19456
	ds_read_b128 v[208:211], v137 offset:20480
	ds_read_b128 v[212:215], v137 offset:21504
	ds_read_b128 v[216:219], v137 offset:22528
	ds_read_b128 v[220:223], v137 offset:23552
	global_load_lds_dwordx4 v[134:135], off
	v_lshl_add_u64 v[142:143], s[12:13], 0, v[128:129]
	s_mov_b32 m0, s44
	s_addc_u32 s17, s13, 0
	global_load_lds_dwordx4 v[142:143], off
	v_lshl_add_u64 v[148:149], s[16:17], 0, v[144:145]
	s_mov_b32 m0, s45
	v_lshl_add_u64 v[248:249], s[8:9], 0, v[132:133]
	global_load_lds_dwordx4 v[148:149], off
	v_lshl_add_u64 v[148:149], s[16:17], 0, v[128:129]
	s_mov_b32 m0, s47
	v_lshl_add_u64 v[146:147], s[8:9], 0, v[130:131]
	global_load_lds_dwordx4 v[148:149], off
	s_mov_b32 m0, s25
	s_nop 0
	global_load_lds_dwordx4 v[248:249], off
	s_mov_b32 m0, s28
	s_nop 0
	global_load_lds_dwordx4 v[146:147], off
	s_waitcnt vmcnt(8)
	s_waitcnt lgkmcnt(0)
	s_barrier
	s_setprio 1
	s_waitcnt lgkmcnt(0)
	v_mfma_f32_16x16x32_bf16 v[0:3], v[104:107], v[216:219], v[0:3]
	v_mfma_f32_16x16x32_bf16 v[4:7], v[112:115], v[216:219], v[4:7]
	v_mfma_f32_16x16x32_bf16 v[138:141], v[104:107], v[88:91], v[138:141]
	v_mfma_f32_16x16x32_bf16 v[162:165], v[112:115], v[88:91], v[162:165]
	v_mfma_f32_16x16x32_bf16 v[166:169], v[104:107], v[200:203], v[166:169]
	v_mfma_f32_16x16x32_bf16 v[170:173], v[112:115], v[200:203], v[170:173]
	v_mfma_f32_16x16x32_bf16 v[174:177], v[104:107], v[208:211], v[174:177]
	v_mfma_f32_16x16x32_bf16 v[188:191], v[112:115], v[208:211], v[188:191]
	v_mfma_f32_16x16x32_bf16 v[0:3], v[108:111], v[220:223], v[0:3]
	v_mfma_f32_16x16x32_bf16 v[4:7], v[116:119], v[220:223], v[4:7]
	v_mfma_f32_16x16x32_bf16 v[138:141], v[108:111], v[92:95], v[138:141]
	v_mfma_f32_16x16x32_bf16 v[162:165], v[116:119], v[92:95], v[162:165]
	v_mfma_f32_16x16x32_bf16 v[166:169], v[108:111], v[204:207], v[166:169]
	v_mfma_f32_16x16x32_bf16 v[170:173], v[116:119], v[204:207], v[170:173]
	v_mfma_f32_16x16x32_bf16 v[174:177], v[108:111], v[212:215], v[174:177]
	v_mfma_f32_16x16x32_bf16 v[188:191], v[116:119], v[212:215], v[188:191]
	v_mfma_f32_16x16x32_bf16 v[8:11], v[120:123], v[88:91], v[8:11]
	v_mfma_f32_16x16x32_bf16 v[224:227], v[124:127], v[92:95], v[8:11]
	v_mfma_f32_16x16x32_bf16 v[8:11], v[192:195], v[88:91], v[12:15]
	v_mfma_f32_16x16x32_bf16 v[228:231], v[196:199], v[92:95], v[8:11]
	v_mfma_f32_16x16x32_bf16 v[8:11], v[120:123], v[200:203], v[24:27]
	v_mfma_f32_16x16x32_bf16 v[240:243], v[124:127], v[204:207], v[8:11]
	v_mfma_f32_16x16x32_bf16 v[8:11], v[192:195], v[200:203], v[28:31]
	v_mfma_f32_16x16x32_bf16 v[200:203], v[196:199], v[204:207], v[8:11]
	v_mfma_f32_16x16x32_bf16 v[8:11], v[120:123], v[208:211], v[60:63]
	v_mfma_f32_16x16x32_bf16 v[204:207], v[124:127], v[212:215], v[8:11]
	v_mfma_f32_16x16x32_bf16 v[8:11], v[192:195], v[208:211], v[100:103]
	v_mfma_f32_16x16x32_bf16 v[208:211], v[196:199], v[212:215], v[8:11]
	v_mfma_f32_16x16x32_bf16 v[8:11], v[120:123], v[216:219], v[16:19]
	v_mfma_f32_16x16x32_bf16 v[212:215], v[124:127], v[220:223], v[8:11]
	v_mfma_f32_16x16x32_bf16 v[8:11], v[192:195], v[216:219], v[20:23]
	v_mfma_f32_16x16x32_bf16 v[192:195], v[196:199], v[220:223], v[8:11]
	s_setprio 0
	s_barrier
; #define PG8_STAGE(bufoff, gbase, voff) do { _Pragma("unroll") for (int _i = 0; _i < 2; ++_i) \
;         __builtin_amdgcn_global_load_lds((const unsigned*)((const char*)(gbase) + (voff)[_i]), (PG8_LAS unsigned*)(lds + (bufoff) + ldsw + _i * 8192), 16, 0, 0); } while (0)
; #define PG8_LDA(dst, b, h) do { _Pragma("unroll") for (int m = 0; m < 4; ++m) _Pragma("unroll") for (int k = 0; k < 2; ++k) dst[m][k] = *(const PG8_LAS bf16x8*)(lds + PG8_SA(b, h) + aoff + m * 2048 + k * 1024); } while (0)
; #define PG8_LDB(dst, b, h) do { _Pragma("unroll") for (int n = 0; n < 2; ++n) _Pragma("unroll") for (int k = 0; k < 2; ++k) dst[n][k] = *(const PG8_LAS bf16x8*)(lds + PG8_SB(b, h) + boff + n * 2048 + k * 1024); } while (0)
; #define PG8_MMA(ai, bj, At, Bt) do { __builtin_amdgcn_s_setprio(1); _Pragma("unroll") for (int m = 0; m < 4; ++m) _Pragma("unroll") for (int n = 0; n < 2; ++n) _Pragma("unroll") for (int k = 0; k < 2; ++k) \
;         acc[ai][bj][m][n] = __builtin_amdgcn_mfma_f32_16x16x32_bf16(Bt[n][k], At[m][k], acc[ai][bj][m][n], 0, 0, 0); __builtin_amdgcn_s_setprio(0); } while (0)
; #define PG8_WAIT_V(n) asm volatile("s_waitcnt vmcnt(" #n ")" ::: "memory")
; #define PG8_WAIT_L(n) asm volatile("s_waitcnt lgkmcnt(" #n ")" ::: "memory")
; #define PG8_BAR __builtin_amdgcn_s_barrier()
; #define PG8_SCHED __builtin_amdgcn_sched_barrier(0)
; template <class Epi, class Sched, int K, int lda, int ldb, bool ALIGN_EPI = true, bool SP2 = true>
; __device__ __forceinline__ void gemm_phase(PG8_LAS unsigned char* lds, const Sched& S, const Epi& E, const int wave_sgpr) {
;     ...
;             PG8_LDB(B0, 1, 0); PG8_LDB(B1, 1, 1); PG8_SCHED; PG8_LDA(At, 1, 0); PG8_STAGE(PG8_SA(0, 1), a2 + hstepA, voffA);
;             PG8_WAIT_V(8); PG8_WAIT_L(0); PG8_BAR; PG8_MMA(0, 0, At, B0); PG8_MMA(0, 1, At, B1); PG8_BAR; PG8_SCHED;
;             PG8_LDA(At, 1, 1); PG8_STAGE(PG8_SB(1, 0), b3, voffB); PG8_STAGE(PG8_SB(1, 1), b3 + hstepB, voffB); PG8_STAGE(PG8_SA(1, 0), a3, voffA);
;             PG8_WAIT_V(8); PG8_WAIT_L(0); PG8_BAR; PG8_MMA(1, 0, At, B0); PG8_MMA(1, 1, At, B1); PG8_BAR; PG8_SCHED;
;     ...
;         if constexpr (ALIGN_EPI) { if (wr == 0) PG8_BAR; }
	s_nop 4
	ds_read_b128 v[8:11], v154
	ds_read_b128 v[12:15], v154 offset:1024
	ds_read_b128 v[16:19], v154 offset:2048
	ds_read_b128 v[20:23], v154 offset:3072
	ds_read_b128 v[196:199], v155
	ds_read_b128 v[216:219], v155 offset:1024
	ds_read_b128 v[220:223], v155 offset:2048
	ds_read_b128 v[244:247], v155 offset:3072
	s_add_u32 s16, s8, 0x40000
	s_addc_u32 s17, s9, 0
	s_mov_b32 m0, s29
	v_lshl_add_u64 v[88:89], s[16:17], 0, v[132:133]
	ds_read_b128 v[24:27], v137 offset:32768
	ds_read_b128 v[28:31], v137 offset:33792
	ds_read_b128 v[60:63], v137 offset:34816
	ds_read_b128 v[148:151], v137 offset:35840
	ds_read_b128 v[152:155], v137 offset:36864
	ds_read_b128 v[180:183], v137 offset:37888
	ds_read_b128 v[184:187], v137 offset:38912
	ds_read_b128 v[158:161], v137 offset:39936
	global_load_lds_dwordx4 v[88:89], off
	v_lshl_add_u64 v[88:89], s[16:17], 0, v[130:131]
	s_mov_b32 m0, s34
	s_nop 0
	global_load_lds_dwordx4 v[88:89], off
	s_waitcnt vmcnt(8)
	s_waitcnt lgkmcnt(0)
	s_barrier
	s_setprio 1
	s_waitcnt lgkmcnt(0)
	v_mfma_f32_16x16x32_bf16 v[64:67], v[8:11], v[24:27], v[64:67]
	v_mfma_f32_16x16x32_bf16 v[124:127], v[12:15], v[28:31], v[64:67]
	v_mfma_f32_16x16x32_bf16 v[64:67], v[16:19], v[24:27], v[68:71]
	v_mfma_f32_16x16x32_bf16 v[120:123], v[20:23], v[28:31], v[64:67]
	v_mfma_f32_16x16x32_bf16 v[64:67], v[8:11], v[60:63], v[72:75]
	v_mfma_f32_16x16x32_bf16 v[108:111], v[12:15], v[148:151], v[64:67]
	v_mfma_f32_16x16x32_bf16 v[64:67], v[16:19], v[60:63], v[76:79]
	v_mfma_f32_16x16x32_bf16 v[104:107], v[20:23], v[148:151], v[64:67]
	v_mfma_f32_16x16x32_bf16 v[64:67], v[8:11], v[152:155], v[80:83]
	v_mfma_f32_16x16x32_bf16 v[92:95], v[12:15], v[180:183], v[64:67]
	v_mfma_f32_16x16x32_bf16 v[64:67], v[16:19], v[152:155], v[84:87]
	v_mfma_f32_16x16x32_bf16 v[88:91], v[20:23], v[180:183], v[64:67]
	v_mfma_f32_16x16x32_bf16 v[64:67], v[8:11], v[184:187], v[232:235]
	v_mfma_f32_16x16x32_bf16 v[68:71], v[12:15], v[158:161], v[64:67]
	v_mfma_f32_16x16x32_bf16 v[64:67], v[16:19], v[184:187], v[236:239]
	v_mfma_f32_16x16x32_bf16 v[64:67], v[20:23], v[158:161], v[64:67]
	v_mfma_f32_16x16x32_bf16 v[72:75], v[196:199], v[24:27], v[96:99]
	v_mfma_f32_16x16x32_bf16 v[24:27], v[220:223], v[24:27], v[32:35]
	v_mfma_f32_16x16x32_bf16 v[112:115], v[244:247], v[28:31], v[24:27]
	v_mfma_f32_16x16x32_bf16 v[24:27], v[196:199], v[60:63], v[36:39]
	v_mfma_f32_16x16x32_bf16 v[100:103], v[216:219], v[148:151], v[24:27]
	v_mfma_f32_16x16x32_bf16 v[24:27], v[220:223], v[60:63], v[40:43]
	v_mfma_f32_16x16x32_bf16 v[96:99], v[244:247], v[148:151], v[24:27]
	v_mfma_f32_16x16x32_bf16 v[24:27], v[196:199], v[152:155], v[44:47]
	v_mfma_f32_16x16x32_bf16 v[84:87], v[216:219], v[180:183], v[24:27]
	v_mfma_f32_16x16x32_bf16 v[24:27], v[220:223], v[152:155], v[48:51]
	v_mfma_f32_16x16x32_bf16 v[80:83], v[244:247], v[180:183], v[24:27]
	v_mfma_f32_16x16x32_bf16 v[24:27], v[196:199], v[184:187], v[52:55]
	v_mfma_f32_16x16x32_bf16 v[52:55], v[216:219], v[158:161], v[24:27]
	v_mfma_f32_16x16x32_bf16 v[24:27], v[220:223], v[184:187], v[56:59]
	v_mfma_f32_16x16x32_bf16 v[116:119], v[216:219], v[28:31], v[72:75]
	v_mfma_f32_16x16x32_bf16 v[48:51], v[244:247], v[158:161], v[24:27]
	s_setprio 0
	s_barrier
	s_mov_b32 m0, s51
	s_nop 2
	v_lshl_add_u64 v[24:25], v[134:135], 0, s[30:31]
	s_add_u32 s16, s12, 0x10080
	ds_read_b128 v[32:35], v137 offset:49152
	ds_read_b128 v[36:39], v137 offset:50176
	ds_read_b128 v[148:151], v137 offset:51200
	ds_read_b128 v[152:155], v137 offset:52224
	ds_read_b128 v[158:161], v137 offset:53248
	ds_read_b128 v[180:183], v137 offset:54272
	ds_read_b128 v[184:187], v137 offset:55296
	ds_read_b128 v[232:235], v137 offset:56320
	global_load_lds_dwordx4 v[24:25], off
	v_lshl_add_u64 v[24:25], v[142:143], 0, s[30:31]
	s_mov_b32 m0, s49
	s_addc_u32 s17, s13, 0
	global_load_lds_dwordx4 v[24:25], off
	v_lshl_add_u64 v[24:25], s[16:17], 0, v[144:145]
	s_mov_b32 m0, s18
	s_nop 0
	global_load_lds_dwordx4 v[24:25], off
	v_lshl_add_u64 v[24:25], s[16:17], 0, v[128:129]
	s_mov_b32 m0, s19
	s_nop 0
	global_load_lds_dwordx4 v[24:25], off
	v_lshl_add_u64 v[24:25], v[248:249], 0, s[30:31]
	s_mov_b32 m0, s38
	s_nop 0
	global_load_lds_dwordx4 v[24:25], off
	v_lshl_add_u64 v[24:25], v[146:147], 0, s[30:31]
	s_mov_b32 m0, s39
	s_nop 0
	global_load_lds_dwordx4 v[24:25], off
	s_waitcnt vmcnt(8)
	s_waitcnt lgkmcnt(0)
	s_barrier
	s_setprio 1
	s_waitcnt lgkmcnt(0)
	v_mfma_f32_16x16x32_bf16 v[24:27], v[8:11], v[32:35], v[138:141]
	v_mfma_f32_16x16x32_bf16 v[76:79], v[12:15], v[36:39], v[24:27]
	v_mfma_f32_16x16x32_bf16 v[24:27], v[16:19], v[32:35], v[162:165]
	v_mfma_f32_16x16x32_bf16 v[72:75], v[20:23], v[36:39], v[24:27]
	v_mfma_f32_16x16x32_bf16 v[24:27], v[8:11], v[148:151], v[166:169]
	v_mfma_f32_16x16x32_bf16 v[44:47], v[12:15], v[152:155], v[24:27]
	v_mfma_f32_16x16x32_bf16 v[24:27], v[16:19], v[148:151], v[170:173]
	v_mfma_f32_16x16x32_bf16 v[40:43], v[20:23], v[152:155], v[24:27]
	v_mfma_f32_16x16x32_bf16 v[24:27], v[8:11], v[158:161], v[174:177]
	v_mfma_f32_16x16x32_bf16 v[0:3], v[8:11], v[184:187], v[0:3]
	v_mfma_f32_16x16x32_bf16 v[28:31], v[12:15], v[180:183], v[24:27]
	v_mfma_f32_16x16x32_bf16 v[24:27], v[16:19], v[158:161], v[188:191]
	v_mfma_f32_16x16x32_bf16 v[12:15], v[12:15], v[232:235], v[0:3]
	v_mfma_f32_16x16x32_bf16 v[0:3], v[16:19], v[184:187], v[4:7]
	v_mfma_f32_16x16x32_bf16 v[24:27], v[20:23], v[180:183], v[24:27]
	v_mfma_f32_16x16x32_bf16 v[8:11], v[20:23], v[232:235], v[0:3]
	v_mfma_f32_16x16x32_bf16 v[0:3], v[196:199], v[32:35], v[224:227]
	v_mfma_f32_16x16x32_bf16 v[60:63], v[216:219], v[36:39], v[0:3]
	v_mfma_f32_16x16x32_bf16 v[0:3], v[220:223], v[32:35], v[228:231]
	v_mfma_f32_16x16x32_bf16 v[56:59], v[244:247], v[36:39], v[0:3]
	v_mfma_f32_16x16x32_bf16 v[0:3], v[196:199], v[148:151], v[240:243]
	v_mfma_f32_16x16x32_bf16 v[36:39], v[216:219], v[152:155], v[0:3]
	v_mfma_f32_16x16x32_bf16 v[0:3], v[220:223], v[148:151], v[200:203]
	v_mfma_f32_16x16x32_bf16 v[32:35], v[244:247], v[152:155], v[0:3]
	v_mfma_f32_16x16x32_bf16 v[0:3], v[196:199], v[158:161], v[204:207]
	v_mfma_f32_16x16x32_bf16 v[20:23], v[216:219], v[180:183], v[0:3]
	v_mfma_f32_16x16x32_bf16 v[0:3], v[220:223], v[158:161], v[208:211]
	v_mfma_f32_16x16x32_bf16 v[16:19], v[244:247], v[180:183], v[0:3]
	v_mfma_f32_16x16x32_bf16 v[0:3], v[196:199], v[184:187], v[212:215]
	v_mfma_f32_16x16x32_bf16 v[4:7], v[216:219], v[232:235], v[0:3]
	v_mfma_f32_16x16x32_bf16 v[0:3], v[220:223], v[184:187], v[192:195]
	v_mfma_f32_16x16x32_bf16 v[0:3], v[244:247], v[232:235], v[0:3]
	s_setprio 0
	s_barrier
	s_andn2_b64 vcc, exec, s[4:5]
	s_cbranch_vccnz .LBB0_250
	s_barrier

; #define PG8_STAGE(bufoff, gbase, voff) do { _Pragma("unroll") for (int _i = 0; _i < 2; ++_i) \
;         __builtin_amdgcn_global_load_lds((const unsigned*)((const char*)(gbase) + (voff)[_i]), (PG8_LAS unsigned*)(lds + (bufoff) + ldsw + _i * 8192), 16, 0, 0); } while (0)
; #define PG8_LDA(dst, b, h) do { _Pragma("unroll") for (int m = 0; m < 4; ++m) _Pragma("unroll") for (int k = 0; k < 2; ++k) dst[m][k] = *(const PG8_LAS bf16x8*)(lds + PG8_SA(b, h) + aoff + m * 2048 + k * 1024); } while (0)
; #define PG8_LDB(dst, b, h) do { _Pragma("unroll") for (int n = 0; n < 2; ++n) _Pragma("unroll") for (int k = 0; k < 2; ++k) dst[n][k] = *(const PG8_LAS bf16x8*)(lds + PG8_SB(b, h) + boff + n * 2048 + k * 1024); } while (0)
; #define PG8_MMA(ai, bj, At, Bt) do { __builtin_amdgcn_s_setprio(1); _Pragma("unroll") for (int m = 0; m < 4; ++m) _Pragma("unroll") for (int n = 0; n < 2; ++n) _Pragma("unroll") for (int k = 0; k < 2; ++k) \
;         acc[ai][bj][m][n] = __builtin_amdgcn_mfma_f32_16x16x32_bf16(Bt[n][k], At[m][k], acc[ai][bj][m][n], 0, 0, 0); __builtin_amdgcn_s_setprio(0); } while (0)
; #define PG8_WAIT_V(n) asm volatile("s_waitcnt vmcnt(" #n ")" ::: "memory")
; #define PG8_WAIT_L(n) asm volatile("s_waitcnt lgkmcnt(" #n ")" ::: "memory")
; #define PG8_BAR __builtin_amdgcn_s_barrier()
; #define PG8_SCHED __builtin_amdgcn_sched_barrier(0)
; template <class Epi, class Sched, int K, int lda, int ldb, bool ALIGN_EPI = true, bool SP2 = true>
; __device__ __forceinline__ void gemm_phase(PG8_LAS unsigned char* lds, const Sched& S, const Epi& E, const int wave_sgpr) {
;     ...
;         for (int t = 0; t < nt; t += 2) {
;             const bool last = (t == nt - 2);
;             const char* a1 = cA + (size_t)(t + 1) * kstep;
;             const char* a2 = last ? nA : cA + (size_t)(t + 2) * kstep; const char* b2 = last ? nB : cB + (size_t)(t + 2) * kstep;
;             const char* a3 = a2 + kstep; const char* b3 = b2 + kstep;
;             if constexpr (SP2) {
;             PG8_LDB(B0, 0, 0); PG8_LDB(B1, 0, 1); PG8_SCHED; PG8_LDA(At, 0, 0); PG8_STAGE(PG8_SA(1, 1), a1 + hstepA, voffA);
;             PG8_WAIT_V(8); PG8_WAIT_L(0); PG8_BAR; PG8_MMA(0, 0, At, B0); PG8_MMA(0, 1, At, B1); PG8_BAR; PG8_SCHED;
;             PG8_LDA(At, 0, 1); PG8_STAGE(PG8_SB(0, 0), b2, voffB); PG8_STAGE(PG8_SB(0, 1), b2 + hstepB, voffB); PG8_STAGE(PG8_SA(0, 0), a2, voffA);
.LBB0_498:
	s_add_u32 s20, s18, 0xfffc0080
	s_addc_u32 s21, s19, -1
	s_add_i32 s54, 0, 0x10000
	s_cmp_eq_u32 s53, 12
	s_cselect_b32 s23, s15, s21
	s_cselect_b32 s22, s14, s20
	s_cselect_b32 s21, s17, s13
	s_cselect_b32 s20, s16, s9
	s_add_i32 s56, 0, 0x14000
	v_add_u32_e32 v60, s54, v147
	v_add_u32_e32 v146, s56, v147
	ds_read_b128 v[40:43], v60
	ds_read_b128 v[44:47], v60 offset:1024
	ds_read_b128 v[56:59], v60 offset:2048
	ds_read_b128 v[60:63], v60 offset:3072
	ds_read_b128 v[148:151], v146
	ds_read_b128 v[152:155], v146 offset:1024
	ds_read_b128 v[158:161], v146 offset:2048
	ds_read_b128 v[172:175], v146 offset:3072
	v_lshl_add_u64 v[176:177], s[18:19], 0, v[170:171]
	s_add_i32 m0, s39, 0xc000
	ds_read_b128 v[180:183], v156
	ds_read_b128 v[184:187], v156 offset:1024
	ds_read_b128 v[188:191], v156 offset:2048
	ds_read_b128 v[192:195], v156 offset:3072
	ds_read_b128 v[196:199], v156 offset:4096
	ds_read_b128 v[200:203], v156 offset:5120
	ds_read_b128 v[204:207], v156 offset:6144
	ds_read_b128 v[208:211], v156 offset:7168
	global_load_lds_dwordx4 v[176:177], off
	v_lshl_add_u64 v[176:177], s[18:19], 0, v[168:169]
	s_add_i32 m0, s39, 0xe000
	s_nop 0
	global_load_lds_dwordx4 v[176:177], off
	s_waitcnt vmcnt(8)
	s_waitcnt lgkmcnt(0)
	s_barrier
	s_setprio 1
	s_waitcnt lgkmcnt(0)
	v_mfma_f32_16x16x32_bf16 v[140:143], v[40:43], v[180:183], v[140:143]
	v_mfma_f32_16x16x32_bf16 v[136:139], v[56:59], v[180:183], v[136:139]
	v_mfma_f32_16x16x32_bf16 v[124:127], v[40:43], v[188:191], v[124:127]
	v_mfma_f32_16x16x32_bf16 v[120:123], v[56:59], v[188:191], v[120:123]
	v_mfma_f32_16x16x32_bf16 v[108:111], v[40:43], v[196:199], v[108:111]
	v_mfma_f32_16x16x32_bf16 v[104:107], v[56:59], v[196:199], v[104:107]
	v_mfma_f32_16x16x32_bf16 v[92:95], v[40:43], v[204:207], v[92:95]
	v_mfma_f32_16x16x32_bf16 v[88:91], v[56:59], v[204:207], v[88:91]
	v_mfma_f32_16x16x32_bf16 v[140:143], v[44:47], v[184:187], v[140:143]
	v_mfma_f32_16x16x32_bf16 v[136:139], v[60:63], v[184:187], v[136:139]
	v_mfma_f32_16x16x32_bf16 v[124:127], v[44:47], v[192:195], v[124:127]
	v_mfma_f32_16x16x32_bf16 v[120:123], v[60:63], v[192:195], v[120:123]
	v_mfma_f32_16x16x32_bf16 v[108:111], v[44:47], v[200:203], v[108:111]
	v_mfma_f32_16x16x32_bf16 v[104:107], v[60:63], v[200:203], v[104:107]
	v_mfma_f32_16x16x32_bf16 v[92:95], v[44:47], v[208:211], v[92:95]
	v_mfma_f32_16x16x32_bf16 v[88:91], v[60:63], v[208:211], v[88:91]
	v_mfma_f32_16x16x32_bf16 v[132:135], v[148:151], v[180:183], v[132:135]
	v_mfma_f32_16x16x32_bf16 v[128:131], v[158:161], v[180:183], v[128:131]
	v_mfma_f32_16x16x32_bf16 v[116:119], v[148:151], v[188:191], v[116:119]
	v_mfma_f32_16x16x32_bf16 v[112:115], v[158:161], v[188:191], v[112:115]
	v_mfma_f32_16x16x32_bf16 v[100:103], v[148:151], v[196:199], v[100:103]
	v_mfma_f32_16x16x32_bf16 v[96:99], v[158:161], v[196:199], v[96:99]
	v_mfma_f32_16x16x32_bf16 v[84:87], v[148:151], v[204:207], v[84:87]
	v_mfma_f32_16x16x32_bf16 v[80:83], v[158:161], v[204:207], v[80:83]
	v_mfma_f32_16x16x32_bf16 v[132:135], v[152:155], v[184:187], v[132:135]
	v_mfma_f32_16x16x32_bf16 v[128:131], v[172:175], v[184:187], v[128:131]
	v_mfma_f32_16x16x32_bf16 v[116:119], v[152:155], v[192:195], v[116:119]
	v_mfma_f32_16x16x32_bf16 v[112:115], v[172:175], v[192:195], v[112:115]
	v_mfma_f32_16x16x32_bf16 v[100:103], v[152:155], v[200:203], v[100:103]
	v_mfma_f32_16x16x32_bf16 v[96:99], v[172:175], v[200:203], v[96:99]
	v_mfma_f32_16x16x32_bf16 v[84:87], v[152:155], v[208:211], v[84:87]
	v_mfma_f32_16x16x32_bf16 v[80:83], v[172:175], v[208:211], v[80:83]
	s_setprio 0
	s_barrier
	s_add_i32 s54, s54, s38
	v_lshl_add_u64 v[176:177], s[20:21], 0, v[144:145]
	s_mov_b32 m0, s54
	ds_read_b128 v[180:183], v156 offset:16384
	ds_read_b128 v[184:187], v156 offset:17408
	ds_read_b128 v[188:191], v156 offset:18432
	ds_read_b128 v[192:195], v156 offset:19456
	ds_read_b128 v[196:199], v156 offset:20480
	ds_read_b128 v[200:203], v156 offset:21504
	ds_read_b128 v[204:207], v156 offset:22528
	ds_read_b128 v[208:211], v156 offset:23552
	global_load_lds_dwordx4 v[176:177], off
	s_add_i32 m0, s54, 0x2000
	s_add_u32 s54, s20, 0x40000
	v_lshl_add_u64 v[212:213], s[20:21], 0, v[162:163]
	s_addc_u32 s55, s21, 0
	s_add_i32 s56, s56, s38
	global_load_lds_dwordx4 v[212:213], off
	v_lshl_add_u64 v[214:215], s[54:55], 0, v[144:145]
	s_mov_b32 m0, s56
	v_lshl_add_u64 v[216:217], s[22:23], 0, v[164:165]
	global_load_lds_dwordx4 v[214:215], off
	v_lshl_add_u64 v[214:215], s[54:55], 0, v[162:163]
	s_add_i32 m0, s56, 0x2000
	s_nop 0
	global_load_lds_dwordx4 v[214:215], off
	v_lshl_add_u64 v[214:215], s[22:23], 0, v[166:167]
	s_mov_b32 m0, s39
	s_nop 0
	global_load_lds_dwordx4 v[214:215], off
	s_mov_b32 m0, s40
	s_nop 0
	global_load_lds_dwordx4 v[216:217], off
	s_waitcnt vmcnt(8)
	s_waitcnt lgkmcnt(0)
	s_barrier
; #define PG8_STAGE(bufoff, gbase, voff) do { _Pragma("unroll") for (int _i = 0; _i < 2; ++_i) \
;         __builtin_amdgcn_global_load_lds((const unsigned*)((const char*)(gbase) + (voff)[_i]), (PG8_LAS unsigned*)(lds + (bufoff) + ldsw + _i * 8192), 16, 0, 0); } while (0)
; #define PG8_LDA(dst, b, h) do { _Pragma("unroll") for (int m = 0; m < 4; ++m) _Pragma("unroll") for (int k = 0; k < 2; ++k) dst[m][k] = *(const PG8_LAS bf16x8*)(lds + PG8_SA(b, h) + aoff + m * 2048 + k * 1024); } while (0)
; #define PG8_LDB(dst, b, h) do { _Pragma("unroll") for (int n = 0; n < 2; ++n) _Pragma("unroll") for (int k = 0; k < 2; ++k) dst[n][k] = *(const PG8_LAS bf16x8*)(lds + PG8_SB(b, h) + boff + n * 2048 + k * 1024); } while (0)
; #define PG8_MMA(ai, bj, At, Bt) do { __builtin_amdgcn_s_setprio(1); _Pragma("unroll") for (int m = 0; m < 4; ++m) _Pragma("unroll") for (int n = 0; n < 2; ++n) _Pragma("unroll") for (int k = 0; k < 2; ++k) \
;         acc[ai][bj][m][n] = __builtin_amdgcn_mfma_f32_16x16x32_bf16(Bt[n][k], At[m][k], acc[ai][bj][m][n], 0, 0, 0); __builtin_amdgcn_s_setprio(0); } while (0)
; #define PG8_WAIT_V(n) asm volatile("s_waitcnt vmcnt(" #n ")" ::: "memory")
; #define PG8_WAIT_L(n) asm volatile("s_waitcnt lgkmcnt(" #n ")" ::: "memory")
; #define PG8_BAR __builtin_amdgcn_s_barrier()
; #define PG8_SCHED __builtin_amdgcn_sched_barrier(0)
; template <class Epi, class Sched, int K, int lda, int ldb, bool ALIGN_EPI = true, bool SP2 = true>
; __device__ __forceinline__ void gemm_phase(PG8_LAS unsigned char* lds, const Sched& S, const Epi& E, const int wave_sgpr) {
;     ...
;             PG8_WAIT_V(8); PG8_WAIT_L(0); PG8_BAR; PG8_MMA(1, 0, At, B0); PG8_MMA(1, 1, At, B1); PG8_BAR; PG8_SCHED;
;             PG8_LDB(B0, 1, 0); PG8_LDB(B1, 1, 1); PG8_SCHED; PG8_LDA(At, 1, 0); PG8_STAGE(PG8_SA(0, 1), a2 + hstepA, voffA);
;             PG8_WAIT_V(8); PG8_WAIT_L(0); PG8_BAR; PG8_MMA(0, 0, At, B0); PG8_MMA(0, 1, At, B1); PG8_BAR; PG8_SCHED;
	s_setprio 1
	s_waitcnt lgkmcnt(0)
	v_mfma_f32_16x16x32_bf16 v[76:79], v[40:43], v[180:183], v[76:79]
	v_mfma_f32_16x16x32_bf16 v[72:75], v[56:59], v[180:183], v[72:75]
	v_mfma_f32_16x16x32_bf16 v[52:55], v[40:43], v[188:191], v[52:55]
	v_mfma_f32_16x16x32_bf16 v[48:51], v[56:59], v[188:191], v[48:51]
	v_mfma_f32_16x16x32_bf16 v[28:31], v[40:43], v[196:199], v[28:31]
	v_mfma_f32_16x16x32_bf16 v[24:27], v[56:59], v[196:199], v[24:27]
	v_mfma_f32_16x16x32_bf16 v[12:15], v[40:43], v[204:207], v[12:15]
	v_mfma_f32_16x16x32_bf16 v[8:11], v[56:59], v[204:207], v[8:11]
	v_mfma_f32_16x16x32_bf16 v[76:79], v[44:47], v[184:187], v[76:79]
	v_mfma_f32_16x16x32_bf16 v[72:75], v[60:63], v[184:187], v[72:75]
	v_mfma_f32_16x16x32_bf16 v[52:55], v[44:47], v[192:195], v[52:55]
	v_mfma_f32_16x16x32_bf16 v[48:51], v[60:63], v[192:195], v[48:51]
	v_mfma_f32_16x16x32_bf16 v[28:31], v[44:47], v[200:203], v[28:31]
	v_mfma_f32_16x16x32_bf16 v[24:27], v[60:63], v[200:203], v[24:27]
	v_mfma_f32_16x16x32_bf16 v[12:15], v[44:47], v[208:211], v[12:15]
	v_mfma_f32_16x16x32_bf16 v[8:11], v[60:63], v[208:211], v[8:11]
	v_mfma_f32_16x16x32_bf16 v[36:39], v[148:151], v[188:191], v[36:39]
	v_mfma_f32_16x16x32_bf16 v[32:35], v[158:161], v[188:191], v[32:35]
	v_mfma_f32_16x16x32_bf16 v[20:23], v[148:151], v[196:199], v[20:23]
	v_mfma_f32_16x16x32_bf16 v[16:19], v[158:161], v[196:199], v[16:19]
	v_mfma_f32_16x16x32_bf16 v[4:7], v[148:151], v[204:207], v[4:7]
	v_mfma_f32_16x16x32_bf16 v[0:3], v[158:161], v[204:207], v[0:3]
	v_mfma_f32_16x16x32_bf16 v[40:43], v[148:151], v[180:183], v[68:71]
	v_mfma_f32_16x16x32_bf16 v[44:47], v[158:161], v[180:183], v[64:67]
	v_mfma_f32_16x16x32_bf16 v[36:39], v[152:155], v[192:195], v[36:39]
	v_mfma_f32_16x16x32_bf16 v[32:35], v[172:175], v[192:195], v[32:35]
	v_mfma_f32_16x16x32_bf16 v[20:23], v[152:155], v[200:203], v[20:23]
	v_mfma_f32_16x16x32_bf16 v[16:19], v[172:175], v[200:203], v[16:19]
	v_mfma_f32_16x16x32_bf16 v[4:7], v[152:155], v[208:211], v[4:7]
	v_mfma_f32_16x16x32_bf16 v[0:3], v[172:175], v[208:211], v[0:3]
	v_mfma_f32_16x16x32_bf16 v[40:43], v[152:155], v[184:187], v[40:43]
	v_mfma_f32_16x16x32_bf16 v[44:47], v[172:175], v[184:187], v[44:47]
	s_setprio 0
	s_barrier
	s_add_i32 s54, 0, 0x18000
	s_add_i32 s55, 0, 0x1c000
	v_add_u32_e32 v68, s54, v147
	v_add_u32_e32 v146, s55, v147
	ds_read_b128 v[56:59], v68
	ds_read_b128 v[60:63], v68 offset:1024
	ds_read_b128 v[64:67], v68 offset:2048
	ds_read_b128 v[68:71], v68 offset:3072
	ds_read_b128 v[148:151], v146
	ds_read_b128 v[152:155], v146 offset:1024
	ds_read_b128 v[158:161], v146 offset:2048
	ds_read_b128 v[172:175], v146 offset:3072
	s_add_u32 s22, s22, 0x40000
	s_addc_u32 s23, s23, 0
	s_mov_b32 m0, s41
	v_lshl_add_u64 v[218:219], s[22:23], 0, v[166:167]
	ds_read_b128 v[180:183], v156 offset:32768
	ds_read_b128 v[184:187], v156 offset:33792
	ds_read_b128 v[188:191], v156 offset:34816
	ds_read_b128 v[192:195], v156 offset:35840
	ds_read_b128 v[196:199], v156 offset:36864
	ds_read_b128 v[200:203], v156 offset:37888
	ds_read_b128 v[204:207], v156 offset:38912
	ds_read_b128 v[208:211], v156 offset:39936
	global_load_lds_dwordx4 v[218:219], off
	v_lshl_add_u64 v[218:219], s[22:23], 0, v[164:165]
	s_mov_b32 m0, s42
	s_nop 0
	global_load_lds_dwordx4 v[218:219], off
	s_waitcnt vmcnt(8)
	s_waitcnt lgkmcnt(0)
	s_barrier
	s_setprio 1
	s_waitcnt lgkmcnt(0)
	v_mfma_f32_16x16x32_bf16 v[140:143], v[56:59], v[180:183], v[140:143]
	v_mfma_f32_16x16x32_bf16 v[136:139], v[64:67], v[180:183], v[136:139]
	v_mfma_f32_16x16x32_bf16 v[124:127], v[56:59], v[188:191], v[124:127]
	v_mfma_f32_16x16x32_bf16 v[120:123], v[64:67], v[188:191], v[120:123]
	v_mfma_f32_16x16x32_bf16 v[108:111], v[56:59], v[196:199], v[108:111]
	v_mfma_f32_16x16x32_bf16 v[104:107], v[64:67], v[196:199], v[104:107]
	v_mfma_f32_16x16x32_bf16 v[92:95], v[56:59], v[204:207], v[92:95]
	v_mfma_f32_16x16x32_bf16 v[88:91], v[64:67], v[204:207], v[88:91]
	v_mfma_f32_16x16x32_bf16 v[140:143], v[60:63], v[184:187], v[140:143]
	v_mfma_f32_16x16x32_bf16 v[136:139], v[68:71], v[184:187], v[136:139]
	v_mfma_f32_16x16x32_bf16 v[124:127], v[60:63], v[192:195], v[124:127]
	v_mfma_f32_16x16x32_bf16 v[120:123], v[68:71], v[192:195], v[120:123]
	v_mfma_f32_16x16x32_bf16 v[108:111], v[60:63], v[200:203], v[108:111]
	v_mfma_f32_16x16x32_bf16 v[104:107], v[68:71], v[200:203], v[104:107]
	v_mfma_f32_16x16x32_bf16 v[92:95], v[60:63], v[208:211], v[92:95]
	v_mfma_f32_16x16x32_bf16 v[88:91], v[68:71], v[208:211], v[88:91]
	v_mfma_f32_16x16x32_bf16 v[132:135], v[148:151], v[180:183], v[132:135]
	v_mfma_f32_16x16x32_bf16 v[128:131], v[158:161], v[180:183], v[128:131]
	v_mfma_f32_16x16x32_bf16 v[116:119], v[148:151], v[188:191], v[116:119]
	v_mfma_f32_16x16x32_bf16 v[112:115], v[158:161], v[188:191], v[112:115]
	v_mfma_f32_16x16x32_bf16 v[100:103], v[148:151], v[196:199], v[100:103]
	v_mfma_f32_16x16x32_bf16 v[96:99], v[158:161], v[196:199], v[96:99]
	v_mfma_f32_16x16x32_bf16 v[84:87], v[148:151], v[204:207], v[84:87]
	v_mfma_f32_16x16x32_bf16 v[80:83], v[158:161], v[204:207], v[80:83]
	v_mfma_f32_16x16x32_bf16 v[132:135], v[152:155], v[184:187], v[132:135]
	v_mfma_f32_16x16x32_bf16 v[128:131], v[172:175], v[184:187], v[128:131]
	v_mfma_f32_16x16x32_bf16 v[116:119], v[152:155], v[192:195], v[116:119]
	v_mfma_f32_16x16x32_bf16 v[112:115], v[172:175], v[192:195], v[112:115]
	v_mfma_f32_16x16x32_bf16 v[100:103], v[152:155], v[200:203], v[100:103]
	v_mfma_f32_16x16x32_bf16 v[96:99], v[172:175], v[200:203], v[96:99]
	v_mfma_f32_16x16x32_bf16 v[84:87], v[152:155], v[208:211], v[84:87]
	v_mfma_f32_16x16x32_bf16 v[80:83], v[172:175], v[208:211], v[80:83]
	s_setprio 0
	s_barrier
; #define PG8_STAGE(bufoff, gbase, voff) do { _Pragma("unroll") for (int _i = 0; _i < 2; ++_i) \
;         __builtin_amdgcn_global_load_lds((const unsigned*)((const char*)(gbase) + (voff)[_i]), (PG8_LAS unsigned*)(lds + (bufoff) + ldsw + _i * 8192), 16, 0, 0); } while (0)
; #define PG8_LDA(dst, b, h) do { _Pragma("unroll") for (int m = 0; m < 4; ++m) _Pragma("unroll") for (int k = 0; k < 2; ++k) dst[m][k] = *(const PG8_LAS bf16x8*)(lds + PG8_SA(b, h) + aoff + m * 2048 + k * 1024); } while (0)
; #define PG8_MMA(ai, bj, At, Bt) do { __builtin_amdgcn_s_setprio(1); _Pragma("unroll") for (int m = 0; m < 4; ++m) _Pragma("unroll") for (int n = 0; n < 2; ++n) _Pragma("unroll") for (int k = 0; k < 2; ++k) \
;         acc[ai][bj][m][n] = __builtin_amdgcn_mfma_f32_16x16x32_bf16(Bt[n][k], At[m][k], acc[ai][bj][m][n], 0, 0, 0); __builtin_amdgcn_s_setprio(0); } while (0)
; #define PG8_WAIT_V(n) asm volatile("s_waitcnt vmcnt(" #n ")" ::: "memory")
; #define PG8_WAIT_L(n) asm volatile("s_waitcnt lgkmcnt(" #n ")" ::: "memory")
; #define PG8_BAR __builtin_amdgcn_s_barrier()
; #define PG8_SCHED __builtin_amdgcn_sched_barrier(0)
; template <class Epi, class Sched, int K, int lda, int ldb, bool ALIGN_EPI = true, bool SP2 = true>
; __device__ __forceinline__ void gemm_phase(PG8_LAS unsigned char* lds, const Sched& S, const Epi& E, const int wave_sgpr) {
;     ...
;         for (int t = 0; t < nt; t += 2) {
;             const bool last = (t == nt - 2);
;     ...
;             PG8_LDA(At, 1, 1); PG8_STAGE(PG8_SB(1, 0), b3, voffB); PG8_STAGE(PG8_SB(1, 1), b3 + hstepB, voffB); PG8_STAGE(PG8_SA(1, 0), a3, voffA);
;             PG8_WAIT_V(8); PG8_WAIT_L(0); PG8_BAR; PG8_MMA(1, 0, At, B0); PG8_MMA(1, 1, At, B1); PG8_BAR; PG8_SCHED;
	s_add_i32 s22, s54, s38
	v_lshl_add_u64 v[176:177], v[176:177], 0, s[30:31]
	s_mov_b32 m0, s22
	ds_read_b128 v[180:183], v156 offset:49152
	ds_read_b128 v[184:187], v156 offset:50176
	ds_read_b128 v[188:191], v156 offset:51200
	ds_read_b128 v[192:195], v156 offset:52224
	ds_read_b128 v[196:199], v156 offset:53248
	ds_read_b128 v[200:203], v156 offset:54272
	ds_read_b128 v[204:207], v156 offset:55296
	ds_read_b128 v[208:211], v156 offset:56320
	global_load_lds_dwordx4 v[176:177], off
	s_add_i32 m0, s22, 0x2000
	s_add_u32 s20, s20, 0x40080
	v_lshl_add_u64 v[176:177], v[212:213], 0, s[30:31]
	s_addc_u32 s21, s21, 0
	s_add_i32 s22, s55, s38
	global_load_lds_dwordx4 v[176:177], off
	v_lshl_add_u64 v[176:177], s[20:21], 0, v[144:145]
	s_mov_b32 m0, s22
	s_nop 0
	global_load_lds_dwordx4 v[176:177], off
	v_lshl_add_u64 v[176:177], s[20:21], 0, v[162:163]
	s_add_i32 m0, s22, 0x2000
	s_nop 0
	global_load_lds_dwordx4 v[176:177], off
	v_lshl_add_u64 v[176:177], v[214:215], 0, s[30:31]
	s_mov_b32 m0, s48
	s_nop 0
	global_load_lds_dwordx4 v[176:177], off
	v_lshl_add_u64 v[176:177], v[216:217], 0, s[30:31]
	s_mov_b32 m0, s49
	s_nop 0
	global_load_lds_dwordx4 v[176:177], off
	s_waitcnt vmcnt(8)
	s_waitcnt lgkmcnt(0)
	s_barrier
	s_setprio 1
	s_waitcnt lgkmcnt(0)
	v_mfma_f32_16x16x32_bf16 v[76:79], v[56:59], v[180:183], v[76:79]
	v_mfma_f32_16x16x32_bf16 v[72:75], v[64:67], v[180:183], v[72:75]
	v_mfma_f32_16x16x32_bf16 v[52:55], v[56:59], v[188:191], v[52:55]
	v_mfma_f32_16x16x32_bf16 v[48:51], v[64:67], v[188:191], v[48:51]
	v_mfma_f32_16x16x32_bf16 v[28:31], v[56:59], v[196:199], v[28:31]
	v_mfma_f32_16x16x32_bf16 v[24:27], v[64:67], v[196:199], v[24:27]
	v_mfma_f32_16x16x32_bf16 v[12:15], v[56:59], v[204:207], v[12:15]
	v_mfma_f32_16x16x32_bf16 v[8:11], v[64:67], v[204:207], v[8:11]
	v_mfma_f32_16x16x32_bf16 v[76:79], v[60:63], v[184:187], v[76:79]
	v_mfma_f32_16x16x32_bf16 v[72:75], v[68:71], v[184:187], v[72:75]
	v_mfma_f32_16x16x32_bf16 v[52:55], v[60:63], v[192:195], v[52:55]
	v_mfma_f32_16x16x32_bf16 v[48:51], v[68:71], v[192:195], v[48:51]
	v_mfma_f32_16x16x32_bf16 v[28:31], v[60:63], v[200:203], v[28:31]
	v_mfma_f32_16x16x32_bf16 v[24:27], v[68:71], v[200:203], v[24:27]
	v_mfma_f32_16x16x32_bf16 v[12:15], v[60:63], v[208:211], v[12:15]
	v_mfma_f32_16x16x32_bf16 v[8:11], v[68:71], v[208:211], v[8:11]
	v_mfma_f32_16x16x32_bf16 v[40:43], v[148:151], v[180:183], v[40:43]
	v_mfma_f32_16x16x32_bf16 v[68:71], v[152:155], v[184:187], v[40:43]
	v_mfma_f32_16x16x32_bf16 v[40:43], v[158:161], v[180:183], v[44:47]
	v_mfma_f32_16x16x32_bf16 v[36:39], v[148:151], v[188:191], v[36:39]
	v_mfma_f32_16x16x32_bf16 v[32:35], v[158:161], v[188:191], v[32:35]
	v_mfma_f32_16x16x32_bf16 v[20:23], v[148:151], v[196:199], v[20:23]
	v_mfma_f32_16x16x32_bf16 v[16:19], v[158:161], v[196:199], v[16:19]
	v_mfma_f32_16x16x32_bf16 v[4:7], v[148:151], v[204:207], v[4:7]
	v_mfma_f32_16x16x32_bf16 v[0:3], v[158:161], v[204:207], v[0:3]
	v_mfma_f32_16x16x32_bf16 v[64:67], v[172:175], v[184:187], v[40:43]
	v_mfma_f32_16x16x32_bf16 v[36:39], v[152:155], v[192:195], v[36:39]
	v_mfma_f32_16x16x32_bf16 v[32:35], v[172:175], v[192:195], v[32:35]
	v_mfma_f32_16x16x32_bf16 v[20:23], v[152:155], v[200:203], v[20:23]
	v_mfma_f32_16x16x32_bf16 v[16:19], v[172:175], v[200:203], v[16:19]
	v_mfma_f32_16x16x32_bf16 v[4:7], v[152:155], v[208:211], v[4:7]
	v_mfma_f32_16x16x32_bf16 v[0:3], v[172:175], v[208:211], v[0:3]
	s_setprio 0
	s_barrier
	s_add_i32 s53, s53, 2
	s_add_u32 s9, s9, 0x100
	s_addc_u32 s13, s13, 0
	s_add_u32 s18, s18, 0x100
	s_addc_u32 s19, s19, 0
	s_cmp_gt_u32 s53, 13
	s_cbranch_scc0 .LBB0_498
	s_and_b64 vcc, exec, s[6:7]
	s_cbranch_vccz .LBB0_501
	s_barrier

; #define PG8_STAGE(bufoff, gbase, voff) do { _Pragma("unroll") for (int _i = 0; _i < 2; ++_i) \
;         __builtin_amdgcn_global_load_lds((const unsigned*)((const char*)(gbase) + (voff)[_i]), (PG8_LAS unsigned*)(lds + (bufoff) + ldsw + _i * 8192), 16, 0, 0); } while (0)
; #define PG8_LDA(dst, b, h) do { _Pragma("unroll") for (int m = 0; m < 4; ++m) _Pragma("unroll") for (int k = 0; k < 2; ++k) dst[m][k] = *(const PG8_LAS bf16x8*)(lds + PG8_SA(b, h) + aoff + m * 2048 + k * 1024); } while (0)
; #define PG8_LDB(dst, b, h) do { _Pragma("unroll") for (int n = 0; n < 2; ++n) _Pragma("unroll") for (int k = 0; k < 2; ++k) dst[n][k] = *(const PG8_LAS bf16x8*)(lds + PG8_SB(b, h) + boff + n * 2048 + k * 1024); } while (0)
; #define PG8_MMA(ai, bj, At, Bt) do { __builtin_amdgcn_s_setprio(1); _Pragma("unroll") for (int m = 0; m < 4; ++m) _Pragma("unroll") for (int n = 0; n < 2; ++n) _Pragma("unroll") for (int k = 0; k < 2; ++k) \
;         acc[ai][bj][m][n] = __builtin_amdgcn_mfma_f32_16x16x32_bf16(Bt[n][k], At[m][k], acc[ai][bj][m][n], 0, 0, 0); __builtin_amdgcn_s_setprio(0); } while (0)
; #define PG8_WAIT_V(n) asm volatile("s_waitcnt vmcnt(" #n ")" ::: "memory")
; #define PG8_WAIT_L(n) asm volatile("s_waitcnt lgkmcnt(" #n ")" ::: "memory")
; #define PG8_BAR __builtin_amdgcn_s_barrier()
; #define PG8_SCHED __builtin_amdgcn_sched_barrier(0)
; template <class Epi, class Sched, int K, int lda, int ldb, bool ALIGN_EPI = true, bool SP2 = true>
; __device__ __forceinline__ void gemm_phase(PG8_LAS unsigned char* lds, const Sched& S, const Epi& E, const int wave_sgpr) {
;     ...
;         for (int t = 0; t < nt; t += 2) {
;             const bool last = (t == nt - 2);
;             const char* a1 = cA + (size_t)(t + 1) * kstep;
;             const char* a2 = last ? nA : cA + (size_t)(t + 2) * kstep; const char* b2 = last ? nB : cB + (size_t)(t + 2) * kstep;
;             const char* a3 = a2 + kstep; const char* b3 = b2 + kstep;
;             if constexpr (SP2) {
;             PG8_LDB(B0, 0, 0); PG8_LDB(B1, 0, 1); PG8_SCHED; PG8_LDA(At, 0, 0); PG8_STAGE(PG8_SA(1, 1), a1 + hstepA, voffA);
;             PG8_WAIT_V(8); PG8_WAIT_L(0); PG8_BAR; PG8_MMA(0, 0, At, B0); PG8_MMA(0, 1, At, B1); PG8_BAR; PG8_SCHED;
;             PG8_LDA(At, 0, 1); PG8_STAGE(PG8_SB(0, 0), b2, voffB); PG8_STAGE(PG8_SB(0, 1), b2 + hstepB, voffB); PG8_STAGE(PG8_SA(0, 0), a2, voffA);
.LBB0_520:
	s_add_u32 s20, s18, 0xfff80080
	s_addc_u32 s21, s19, -1
	s_add_i32 s51, 0, 0x10000
	s_cmp_eq_u32 s50, 12
	s_cselect_b32 s23, s15, s21
	s_cselect_b32 s22, s14, s20
	v_add_u32_e32 v138, s51, v140
	s_cselect_b32 s21, s17, s13
	s_cselect_b32 s20, s16, s9
	s_add_i32 s53, 0, 0x14000
	ds_read_b128 v[148:151], v138
	ds_read_b128 v[152:155], v138 offset:1024
	ds_read_b128 v[158:161], v138 offset:2048
	ds_read_b128 v[162:165], v138 offset:3072
	v_add_u32_e32 v138, s53, v140
	ds_read_b128 v[166:169], v138
	ds_read_b128 v[170:173], v138 offset:1024
	ds_read_b128 v[174:177], v138 offset:2048
	ds_read_b128 v[180:183], v138 offset:3072
	v_lshl_add_u64 v[138:139], s[18:19], 0, v[136:137]
	s_add_i32 m0, s39, 0xc000
	ds_read_b128 v[184:187], v141
	ds_read_b128 v[188:191], v141 offset:1024
	ds_read_b128 v[192:195], v141 offset:2048
	ds_read_b128 v[196:199], v141 offset:3072
	ds_read_b128 v[200:203], v141 offset:4096
	ds_read_b128 v[204:207], v141 offset:5120
	ds_read_b128 v[208:211], v141 offset:6144
	ds_read_b128 v[212:215], v141 offset:7168
	global_load_lds_dwordx4 v[138:139], off
	v_lshl_add_u64 v[138:139], s[18:19], 0, v[134:135]
	s_add_i32 m0, s39, 0xe000
	s_nop 0
	global_load_lds_dwordx4 v[138:139], off
	s_waitcnt vmcnt(8)
	s_waitcnt lgkmcnt(0)
	s_barrier
	s_setprio 1
	s_waitcnt lgkmcnt(0)
	v_mfma_f32_16x16x32_bf16 v[124:127], v[148:151], v[184:187], v[124:127]
	v_mfma_f32_16x16x32_bf16 v[120:123], v[158:161], v[184:187], v[120:123]
	v_mfma_f32_16x16x32_bf16 v[116:119], v[148:151], v[192:195], v[116:119]
	v_mfma_f32_16x16x32_bf16 v[108:111], v[158:161], v[192:195], v[108:111]
	v_mfma_f32_16x16x32_bf16 v[100:103], v[148:151], v[200:203], v[100:103]
	v_mfma_f32_16x16x32_bf16 v[92:95], v[158:161], v[200:203], v[92:95]
	v_mfma_f32_16x16x32_bf16 v[84:87], v[148:151], v[208:211], v[84:87]
	v_mfma_f32_16x16x32_bf16 v[76:79], v[158:161], v[208:211], v[76:79]
	v_mfma_f32_16x16x32_bf16 v[124:127], v[152:155], v[188:191], v[124:127]
	v_mfma_f32_16x16x32_bf16 v[120:123], v[162:165], v[188:191], v[120:123]
	v_mfma_f32_16x16x32_bf16 v[116:119], v[152:155], v[196:199], v[116:119]
	v_mfma_f32_16x16x32_bf16 v[108:111], v[162:165], v[196:199], v[108:111]
	v_mfma_f32_16x16x32_bf16 v[100:103], v[152:155], v[204:207], v[100:103]
	v_mfma_f32_16x16x32_bf16 v[92:95], v[162:165], v[204:207], v[92:95]
	v_mfma_f32_16x16x32_bf16 v[84:87], v[152:155], v[212:215], v[84:87]
	v_mfma_f32_16x16x32_bf16 v[76:79], v[162:165], v[212:215], v[76:79]
	v_mfma_f32_16x16x32_bf16 v[112:115], v[166:169], v[184:187], v[112:115]
	v_mfma_f32_16x16x32_bf16 v[104:107], v[174:177], v[184:187], v[104:107]
	v_mfma_f32_16x16x32_bf16 v[96:99], v[166:169], v[192:195], v[96:99]
	v_mfma_f32_16x16x32_bf16 v[88:91], v[174:177], v[192:195], v[88:91]
	v_mfma_f32_16x16x32_bf16 v[80:83], v[166:169], v[200:203], v[80:83]
	v_mfma_f32_16x16x32_bf16 v[72:75], v[174:177], v[200:203], v[72:75]
	v_mfma_f32_16x16x32_bf16 v[68:71], v[166:169], v[208:211], v[68:71]
	v_mfma_f32_16x16x32_bf16 v[64:67], v[174:177], v[208:211], v[64:67]
	v_mfma_f32_16x16x32_bf16 v[112:115], v[170:173], v[188:191], v[112:115]
	v_mfma_f32_16x16x32_bf16 v[104:107], v[180:183], v[188:191], v[104:107]
	v_mfma_f32_16x16x32_bf16 v[96:99], v[170:173], v[196:199], v[96:99]
	v_mfma_f32_16x16x32_bf16 v[88:91], v[180:183], v[196:199], v[88:91]
	v_mfma_f32_16x16x32_bf16 v[80:83], v[170:173], v[204:207], v[80:83]
	v_mfma_f32_16x16x32_bf16 v[72:75], v[180:183], v[204:207], v[72:75]
	v_mfma_f32_16x16x32_bf16 v[68:71], v[170:173], v[212:215], v[68:71]
	v_mfma_f32_16x16x32_bf16 v[64:67], v[180:183], v[212:215], v[64:67]
	s_setprio 0
	s_barrier
	s_add_i32 s51, s51, s38
	v_lshl_add_u64 v[138:139], s[20:21], 0, v[144:145]
	s_mov_b32 m0, s51
	ds_read_b128 v[184:187], v141 offset:16384
	ds_read_b128 v[188:191], v141 offset:17408
	ds_read_b128 v[192:195], v141 offset:18432
	ds_read_b128 v[196:199], v141 offset:19456
	ds_read_b128 v[200:203], v141 offset:20480
	ds_read_b128 v[204:207], v141 offset:21504
	ds_read_b128 v[208:211], v141 offset:22528
	ds_read_b128 v[212:215], v141 offset:23552
	global_load_lds_dwordx4 v[138:139], off
	s_add_i32 m0, s51, 0x2000
	s_add_u32 s54, s20, 0x40000
	v_lshl_add_u64 v[142:143], s[20:21], 0, v[128:129]
	s_addc_u32 s55, s21, 0
	s_add_i32 s51, s53, s38
	global_load_lds_dwordx4 v[142:143], off
	v_lshl_add_u64 v[146:147], s[54:55], 0, v[144:145]
	s_mov_b32 m0, s51
	v_lshl_add_u64 v[216:217], s[22:23], 0, v[130:131]
	global_load_lds_dwordx4 v[146:147], off
	v_lshl_add_u64 v[146:147], s[54:55], 0, v[128:129]
	s_add_i32 m0, s51, 0x2000
	s_nop 0
	global_load_lds_dwordx4 v[146:147], off
	v_lshl_add_u64 v[146:147], s[22:23], 0, v[132:133]
	s_mov_b32 m0, s39
	s_nop 0
	global_load_lds_dwordx4 v[146:147], off
	s_mov_b32 m0, s40
	s_nop 0
	global_load_lds_dwordx4 v[216:217], off
	s_waitcnt vmcnt(8)
	s_waitcnt lgkmcnt(0)
	s_barrier
; #define PG8_STAGE(bufoff, gbase, voff) do { _Pragma("unroll") for (int _i = 0; _i < 2; ++_i) \
;         __builtin_amdgcn_global_load_lds((const unsigned*)((const char*)(gbase) + (voff)[_i]), (PG8_LAS unsigned*)(lds + (bufoff) + ldsw + _i * 8192), 16, 0, 0); } while (0)
; #define PG8_LDA(dst, b, h) do { _Pragma("unroll") for (int m = 0; m < 4; ++m) _Pragma("unroll") for (int k = 0; k < 2; ++k) dst[m][k] = *(const PG8_LAS bf16x8*)(lds + PG8_SA(b, h) + aoff + m * 2048 + k * 1024); } while (0)
; #define PG8_LDB(dst, b, h) do { _Pragma("unroll") for (int n = 0; n < 2; ++n) _Pragma("unroll") for (int k = 0; k < 2; ++k) dst[n][k] = *(const PG8_LAS bf16x8*)(lds + PG8_SB(b, h) + boff + n * 2048 + k * 1024); } while (0)
; #define PG8_MMA(ai, bj, At, Bt) do { __builtin_amdgcn_s_setprio(1); _Pragma("unroll") for (int m = 0; m < 4; ++m) _Pragma("unroll") for (int n = 0; n < 2; ++n) _Pragma("unroll") for (int k = 0; k < 2; ++k) \
;         acc[ai][bj][m][n] = __builtin_amdgcn_mfma_f32_16x16x32_bf16(Bt[n][k], At[m][k], acc[ai][bj][m][n], 0, 0, 0); __builtin_amdgcn_s_setprio(0); } while (0)
; #define PG8_WAIT_V(n) asm volatile("s_waitcnt vmcnt(" #n ")" ::: "memory")
; #define PG8_WAIT_L(n) asm volatile("s_waitcnt lgkmcnt(" #n ")" ::: "memory")
; #define PG8_BAR __builtin_amdgcn_s_barrier()
; #define PG8_SCHED __builtin_amdgcn_sched_barrier(0)
; template <class Epi, class Sched, int K, int lda, int ldb, bool ALIGN_EPI = true, bool SP2 = true>
; __device__ __forceinline__ void gemm_phase(PG8_LAS unsigned char* lds, const Sched& S, const Epi& E, const int wave_sgpr) {
;     ...
;             PG8_WAIT_V(8); PG8_WAIT_L(0); PG8_BAR; PG8_MMA(1, 0, At, B0); PG8_MMA(1, 1, At, B1); PG8_BAR; PG8_SCHED;
;             PG8_LDB(B0, 1, 0); PG8_LDB(B1, 1, 1); PG8_SCHED; PG8_LDA(At, 1, 0); PG8_STAGE(PG8_SA(0, 1), a2 + hstepA, voffA);
;             PG8_WAIT_V(8); PG8_WAIT_L(0); PG8_BAR; PG8_MMA(0, 0, At, B0); PG8_MMA(0, 1, At, B1); PG8_BAR; PG8_SCHED;
	s_setprio 1
	s_waitcnt lgkmcnt(0)
	v_mfma_f32_16x16x32_bf16 v[60:63], v[148:151], v[184:187], v[60:63]
	v_mfma_f32_16x16x32_bf16 v[56:59], v[158:161], v[184:187], v[56:59]
	v_mfma_f32_16x16x32_bf16 v[52:55], v[148:151], v[192:195], v[52:55]
	v_mfma_f32_16x16x32_bf16 v[44:47], v[158:161], v[192:195], v[44:47]
	v_mfma_f32_16x16x32_bf16 v[36:39], v[148:151], v[200:203], v[36:39]
	v_mfma_f32_16x16x32_bf16 v[28:31], v[158:161], v[200:203], v[28:31]
	v_mfma_f32_16x16x32_bf16 v[20:23], v[148:151], v[208:211], v[20:23]
	v_mfma_f32_16x16x32_bf16 v[12:15], v[158:161], v[208:211], v[12:15]
	v_mfma_f32_16x16x32_bf16 v[60:63], v[152:155], v[188:191], v[60:63]
	v_mfma_f32_16x16x32_bf16 v[56:59], v[162:165], v[188:191], v[56:59]
	v_mfma_f32_16x16x32_bf16 v[52:55], v[152:155], v[196:199], v[52:55]
	v_mfma_f32_16x16x32_bf16 v[44:47], v[162:165], v[196:199], v[44:47]
	v_mfma_f32_16x16x32_bf16 v[36:39], v[152:155], v[204:207], v[36:39]
	v_mfma_f32_16x16x32_bf16 v[28:31], v[162:165], v[204:207], v[28:31]
	v_mfma_f32_16x16x32_bf16 v[20:23], v[152:155], v[212:215], v[20:23]
	v_mfma_f32_16x16x32_bf16 v[12:15], v[162:165], v[212:215], v[12:15]
	v_mfma_f32_16x16x32_bf16 v[48:51], v[166:169], v[184:187], v[48:51]
	v_mfma_f32_16x16x32_bf16 v[40:43], v[174:177], v[184:187], v[40:43]
	v_mfma_f32_16x16x32_bf16 v[32:35], v[166:169], v[192:195], v[32:35]
	v_mfma_f32_16x16x32_bf16 v[24:27], v[174:177], v[192:195], v[24:27]
	v_mfma_f32_16x16x32_bf16 v[16:19], v[166:169], v[200:203], v[16:19]
	v_mfma_f32_16x16x32_bf16 v[8:11], v[174:177], v[200:203], v[8:11]
	v_mfma_f32_16x16x32_bf16 v[4:7], v[166:169], v[208:211], v[4:7]
	v_mfma_f32_16x16x32_bf16 v[0:3], v[174:177], v[208:211], v[0:3]
	v_mfma_f32_16x16x32_bf16 v[48:51], v[170:173], v[188:191], v[48:51]
	v_mfma_f32_16x16x32_bf16 v[40:43], v[180:183], v[188:191], v[40:43]
	v_mfma_f32_16x16x32_bf16 v[32:35], v[170:173], v[196:199], v[32:35]
	v_mfma_f32_16x16x32_bf16 v[24:27], v[180:183], v[196:199], v[24:27]
	v_mfma_f32_16x16x32_bf16 v[16:19], v[170:173], v[204:207], v[16:19]
	v_mfma_f32_16x16x32_bf16 v[8:11], v[180:183], v[204:207], v[8:11]
	v_mfma_f32_16x16x32_bf16 v[4:7], v[170:173], v[212:215], v[4:7]
	v_mfma_f32_16x16x32_bf16 v[0:3], v[180:183], v[212:215], v[0:3]
	s_setprio 0
	s_barrier
	s_add_i32 s51, 0, 0x18000
	v_add_u32_e32 v156, s51, v140
	s_add_i32 s53, 0, 0x1c000
	ds_read_b128 v[148:151], v156
	ds_read_b128 v[152:155], v156 offset:1024
	ds_read_b128 v[158:161], v156 offset:2048
	ds_read_b128 v[162:165], v156 offset:3072
	v_add_u32_e32 v156, s53, v140
	ds_read_b128 v[166:169], v156
	ds_read_b128 v[170:173], v156 offset:1024
	ds_read_b128 v[174:177], v156 offset:2048
	ds_read_b128 v[180:183], v156 offset:3072
	s_add_u32 s22, s22, 0x80000
	s_addc_u32 s23, s23, 0
	s_mov_b32 m0, s41
	v_lshl_add_u64 v[218:219], s[22:23], 0, v[132:133]
	ds_read_b128 v[184:187], v141 offset:32768
	ds_read_b128 v[188:191], v141 offset:33792
	ds_read_b128 v[192:195], v141 offset:34816
	ds_read_b128 v[196:199], v141 offset:35840
	ds_read_b128 v[200:203], v141 offset:36864
	ds_read_b128 v[204:207], v141 offset:37888
	ds_read_b128 v[208:211], v141 offset:38912
	ds_read_b128 v[212:215], v141 offset:39936
	global_load_lds_dwordx4 v[218:219], off
	v_lshl_add_u64 v[218:219], s[22:23], 0, v[130:131]
	s_mov_b32 m0, s42
	s_nop 0
	global_load_lds_dwordx4 v[218:219], off
	s_waitcnt vmcnt(8)
	s_waitcnt lgkmcnt(0)
	s_barrier
	s_setprio 1
	s_waitcnt lgkmcnt(0)
	v_mfma_f32_16x16x32_bf16 v[124:127], v[148:151], v[184:187], v[124:127]
	v_mfma_f32_16x16x32_bf16 v[120:123], v[158:161], v[184:187], v[120:123]
	v_mfma_f32_16x16x32_bf16 v[116:119], v[148:151], v[192:195], v[116:119]
	v_mfma_f32_16x16x32_bf16 v[108:111], v[158:161], v[192:195], v[108:111]
	v_mfma_f32_16x16x32_bf16 v[100:103], v[148:151], v[200:203], v[100:103]
	v_mfma_f32_16x16x32_bf16 v[92:95], v[158:161], v[200:203], v[92:95]
	v_mfma_f32_16x16x32_bf16 v[84:87], v[148:151], v[208:211], v[84:87]
	v_mfma_f32_16x16x32_bf16 v[76:79], v[158:161], v[208:211], v[76:79]
	v_mfma_f32_16x16x32_bf16 v[124:127], v[152:155], v[188:191], v[124:127]
	v_mfma_f32_16x16x32_bf16 v[120:123], v[162:165], v[188:191], v[120:123]
	v_mfma_f32_16x16x32_bf16 v[116:119], v[152:155], v[196:199], v[116:119]
	v_mfma_f32_16x16x32_bf16 v[108:111], v[162:165], v[196:199], v[108:111]
	v_mfma_f32_16x16x32_bf16 v[100:103], v[152:155], v[204:207], v[100:103]
	v_mfma_f32_16x16x32_bf16 v[92:95], v[162:165], v[204:207], v[92:95]
	v_mfma_f32_16x16x32_bf16 v[84:87], v[152:155], v[212:215], v[84:87]
	v_mfma_f32_16x16x32_bf16 v[76:79], v[162:165], v[212:215], v[76:79]
	v_mfma_f32_16x16x32_bf16 v[112:115], v[166:169], v[184:187], v[112:115]
	v_mfma_f32_16x16x32_bf16 v[104:107], v[174:177], v[184:187], v[104:107]
	v_mfma_f32_16x16x32_bf16 v[96:99], v[166:169], v[192:195], v[96:99]
	v_mfma_f32_16x16x32_bf16 v[88:91], v[174:177], v[192:195], v[88:91]
	v_mfma_f32_16x16x32_bf16 v[80:83], v[166:169], v[200:203], v[80:83]
	v_mfma_f32_16x16x32_bf16 v[72:75], v[174:177], v[200:203], v[72:75]
	v_mfma_f32_16x16x32_bf16 v[68:71], v[166:169], v[208:211], v[68:71]
	v_mfma_f32_16x16x32_bf16 v[64:67], v[174:177], v[208:211], v[64:67]
	v_mfma_f32_16x16x32_bf16 v[112:115], v[170:173], v[188:191], v[112:115]
	v_mfma_f32_16x16x32_bf16 v[104:107], v[180:183], v[188:191], v[104:107]
	v_mfma_f32_16x16x32_bf16 v[96:99], v[170:173], v[196:199], v[96:99]
	v_mfma_f32_16x16x32_bf16 v[88:91], v[180:183], v[196:199], v[88:91]
	v_mfma_f32_16x16x32_bf16 v[80:83], v[170:173], v[204:207], v[80:83]
	v_mfma_f32_16x16x32_bf16 v[72:75], v[180:183], v[204:207], v[72:75]
	v_mfma_f32_16x16x32_bf16 v[68:71], v[170:173], v[212:215], v[68:71]
	v_mfma_f32_16x16x32_bf16 v[64:67], v[180:183], v[212:215], v[64:67]
	s_setprio 0
	s_barrier
; #define PG8_STAGE(bufoff, gbase, voff) do { _Pragma("unroll") for (int _i = 0; _i < 2; ++_i) \
;         __builtin_amdgcn_global_load_lds((const unsigned*)((const char*)(gbase) + (voff)[_i]), (PG8_LAS unsigned*)(lds + (bufoff) + ldsw + _i * 8192), 16, 0, 0); } while (0)
; #define PG8_LDA(dst, b, h) do { _Pragma("unroll") for (int m = 0; m < 4; ++m) _Pragma("unroll") for (int k = 0; k < 2; ++k) dst[m][k] = *(const PG8_LAS bf16x8*)(lds + PG8_SA(b, h) + aoff + m * 2048 + k * 1024); } while (0)
; #define PG8_MMA(ai, bj, At, Bt) do { __builtin_amdgcn_s_setprio(1); _Pragma("unroll") for (int m = 0; m < 4; ++m) _Pragma("unroll") for (int n = 0; n < 2; ++n) _Pragma("unroll") for (int k = 0; k < 2; ++k) \
;         acc[ai][bj][m][n] = __builtin_amdgcn_mfma_f32_16x16x32_bf16(Bt[n][k], At[m][k], acc[ai][bj][m][n], 0, 0, 0); __builtin_amdgcn_s_setprio(0); } while (0)
; #define PG8_WAIT_V(n) asm volatile("s_waitcnt vmcnt(" #n ")" ::: "memory")
; #define PG8_WAIT_L(n) asm volatile("s_waitcnt lgkmcnt(" #n ")" ::: "memory")
; #define PG8_BAR __builtin_amdgcn_s_barrier()
; #define PG8_SCHED __builtin_amdgcn_sched_barrier(0)
; template <class Epi, class Sched, int K, int lda, int ldb, bool ALIGN_EPI = true, bool SP2 = true>
; __device__ __forceinline__ void gemm_phase(PG8_LAS unsigned char* lds, const Sched& S, const Epi& E, const int wave_sgpr) {
;     ...
;         for (int t = 0; t < nt; t += 2) {
;             const bool last = (t == nt - 2);
;     ...
;             PG8_LDA(At, 1, 1); PG8_STAGE(PG8_SB(1, 0), b3, voffB); PG8_STAGE(PG8_SB(1, 1), b3 + hstepB, voffB); PG8_STAGE(PG8_SA(1, 0), a3, voffA);
;             PG8_WAIT_V(8); PG8_WAIT_L(0); PG8_BAR; PG8_MMA(1, 0, At, B0); PG8_MMA(1, 1, At, B1); PG8_BAR; PG8_SCHED;
	s_add_i32 s22, s51, s38
	v_lshl_add_u64 v[138:139], v[138:139], 0, s[30:31]
	s_mov_b32 m0, s22
	ds_read_b128 v[184:187], v141 offset:49152
	ds_read_b128 v[188:191], v141 offset:50176
	ds_read_b128 v[192:195], v141 offset:51200
	ds_read_b128 v[196:199], v141 offset:52224
	ds_read_b128 v[200:203], v141 offset:53248
	ds_read_b128 v[204:207], v141 offset:54272
	ds_read_b128 v[208:211], v141 offset:55296
	ds_read_b128 v[212:215], v141 offset:56320
	global_load_lds_dwordx4 v[138:139], off
	s_add_i32 m0, s22, 0x2000
	s_add_u32 s20, s20, 0x40080
	v_lshl_add_u64 v[138:139], v[142:143], 0, s[30:31]
	s_addc_u32 s21, s21, 0
	s_add_i32 s22, s53, s38
	global_load_lds_dwordx4 v[138:139], off
	v_lshl_add_u64 v[138:139], s[20:21], 0, v[144:145]
	s_mov_b32 m0, s22
	s_nop 0
	global_load_lds_dwordx4 v[138:139], off
	v_lshl_add_u64 v[138:139], s[20:21], 0, v[128:129]
	s_add_i32 m0, s22, 0x2000
	s_nop 0
	global_load_lds_dwordx4 v[138:139], off
	v_lshl_add_u64 v[138:139], v[146:147], 0, s[30:31]
	s_mov_b32 m0, s45
	s_nop 0
	global_load_lds_dwordx4 v[138:139], off
	v_lshl_add_u64 v[138:139], v[216:217], 0, s[30:31]
	s_mov_b32 m0, s47
	s_nop 0
	global_load_lds_dwordx4 v[138:139], off
	s_waitcnt vmcnt(8)
	s_waitcnt lgkmcnt(0)
	s_barrier
	s_setprio 1
	s_waitcnt lgkmcnt(0)
	v_mfma_f32_16x16x32_bf16 v[60:63], v[148:151], v[184:187], v[60:63]
	v_mfma_f32_16x16x32_bf16 v[56:59], v[158:161], v[184:187], v[56:59]
	v_mfma_f32_16x16x32_bf16 v[52:55], v[148:151], v[192:195], v[52:55]
	v_mfma_f32_16x16x32_bf16 v[44:47], v[158:161], v[192:195], v[44:47]
	v_mfma_f32_16x16x32_bf16 v[36:39], v[148:151], v[200:203], v[36:39]
	v_mfma_f32_16x16x32_bf16 v[28:31], v[158:161], v[200:203], v[28:31]
	v_mfma_f32_16x16x32_bf16 v[20:23], v[148:151], v[208:211], v[20:23]
	v_mfma_f32_16x16x32_bf16 v[12:15], v[158:161], v[208:211], v[12:15]
	v_mfma_f32_16x16x32_bf16 v[60:63], v[152:155], v[188:191], v[60:63]
	v_mfma_f32_16x16x32_bf16 v[56:59], v[162:165], v[188:191], v[56:59]
	v_mfma_f32_16x16x32_bf16 v[52:55], v[152:155], v[196:199], v[52:55]
	v_mfma_f32_16x16x32_bf16 v[44:47], v[162:165], v[196:199], v[44:47]
	v_mfma_f32_16x16x32_bf16 v[36:39], v[152:155], v[204:207], v[36:39]
	v_mfma_f32_16x16x32_bf16 v[28:31], v[162:165], v[204:207], v[28:31]
	v_mfma_f32_16x16x32_bf16 v[20:23], v[152:155], v[212:215], v[20:23]
	v_mfma_f32_16x16x32_bf16 v[12:15], v[162:165], v[212:215], v[12:15]
	v_mfma_f32_16x16x32_bf16 v[48:51], v[166:169], v[184:187], v[48:51]
	v_mfma_f32_16x16x32_bf16 v[40:43], v[174:177], v[184:187], v[40:43]
	v_mfma_f32_16x16x32_bf16 v[32:35], v[166:169], v[192:195], v[32:35]
	v_mfma_f32_16x16x32_bf16 v[24:27], v[174:177], v[192:195], v[24:27]
	v_mfma_f32_16x16x32_bf16 v[16:19], v[166:169], v[200:203], v[16:19]
	v_mfma_f32_16x16x32_bf16 v[8:11], v[174:177], v[200:203], v[8:11]
	v_mfma_f32_16x16x32_bf16 v[4:7], v[166:169], v[208:211], v[4:7]
	v_mfma_f32_16x16x32_bf16 v[0:3], v[174:177], v[208:211], v[0:3]
	v_mfma_f32_16x16x32_bf16 v[48:51], v[170:173], v[188:191], v[48:51]
	v_mfma_f32_16x16x32_bf16 v[40:43], v[180:183], v[188:191], v[40:43]
	v_mfma_f32_16x16x32_bf16 v[32:35], v[170:173], v[196:199], v[32:35]
	v_mfma_f32_16x16x32_bf16 v[24:27], v[180:183], v[196:199], v[24:27]
	v_mfma_f32_16x16x32_bf16 v[16:19], v[170:173], v[204:207], v[16:19]
	v_mfma_f32_16x16x32_bf16 v[8:11], v[180:183], v[204:207], v[8:11]
	v_mfma_f32_16x16x32_bf16 v[4:7], v[170:173], v[212:215], v[4:7]
	v_mfma_f32_16x16x32_bf16 v[0:3], v[180:183], v[212:215], v[0:3]
	s_setprio 0
	s_barrier
	s_add_i32 s50, s50, 2
	s_add_u32 s9, s9, 0x100
	s_addc_u32 s13, s13, 0
	s_add_u32 s18, s18, 0x100
	s_addc_u32 s19, s19, 0
	s_cmp_gt_u32 s50, 13
	s_cbranch_scc0 .LBB0_520
	s_and_b64 vcc, exec, s[6:7]
	s_cbranch_vccz .LBB0_523
	s_barrier

; #define PG8_STAGE(bufoff, gbase, voff) do { _Pragma("unroll") for (int _i = 0; _i < 2; ++_i) \
;         __builtin_amdgcn_global_load_lds((const unsigned*)((const char*)(gbase) + (voff)[_i]), (PG8_LAS unsigned*)(lds + (bufoff) + ldsw + _i * 8192), 16, 0, 0); } while (0)
; #define PG8_LDA(dst, b, h) do { _Pragma("unroll") for (int m = 0; m < 4; ++m) _Pragma("unroll") for (int k = 0; k < 2; ++k) dst[m][k] = *(const PG8_LAS bf16x8*)(lds + PG8_SA(b, h) + aoff + m * 2048 + k * 1024); } while (0)
; #define PG8_LDB(dst, b, h) do { _Pragma("unroll") for (int n = 0; n < 2; ++n) _Pragma("unroll") for (int k = 0; k < 2; ++k) dst[n][k] = *(const PG8_LAS bf16x8*)(lds + PG8_SB(b, h) + boff + n * 2048 + k * 1024); } while (0)
; #define PG8_MMA(ai, bj, At, Bt) do { __builtin_amdgcn_s_setprio(1); _Pragma("unroll") for (int m = 0; m < 4; ++m) _Pragma("unroll") for (int n = 0; n < 2; ++n) _Pragma("unroll") for (int k = 0; k < 2; ++k) \
;         acc[ai][bj][m][n] = __builtin_amdgcn_mfma_f32_16x16x32_bf16(Bt[n][k], At[m][k], acc[ai][bj][m][n], 0, 0, 0); __builtin_amdgcn_s_setprio(0); } while (0)
; #define PG8_WAIT_V(n) asm volatile("s_waitcnt vmcnt(" #n ")" ::: "memory")
; #define PG8_WAIT_L(n) asm volatile("s_waitcnt lgkmcnt(" #n ")" ::: "memory")
; #define PG8_BAR __builtin_amdgcn_s_barrier()
; #define PG8_SCHED __builtin_amdgcn_sched_barrier(0)
; template <class Epi, class Sched, int K, int lda, int ldb, bool ALIGN_EPI = true, bool SP2 = true>
; __device__ __forceinline__ void gemm_phase(PG8_LAS unsigned char* lds, const Sched& S, const Epi& E, const int wave_sgpr) {
;     ...
;         for (int t = 0; t < nt; t += 2) {
;             const bool last = (t == nt - 2);
;             const char* a1 = cA + (size_t)(t + 1) * kstep;
;             const char* a2 = last ? nA : cA + (size_t)(t + 2) * kstep; const char* b2 = last ? nB : cB + (size_t)(t + 2) * kstep;
;             const char* a3 = a2 + kstep; const char* b3 = b2 + kstep;
;             if constexpr (SP2) {
;             PG8_LDB(B0, 0, 0); PG8_LDB(B1, 0, 1); PG8_SCHED; PG8_LDA(At, 0, 0); PG8_STAGE(PG8_SA(1, 1), a1 + hstepA, voffA);
;             PG8_WAIT_V(8); PG8_WAIT_L(0); PG8_BAR; PG8_MMA(0, 0, At, B0); PG8_MMA(0, 1, At, B1); PG8_BAR; PG8_SCHED;
;             PG8_LDA(At, 0, 1); PG8_STAGE(PG8_SB(0, 0), b2, voffB); PG8_STAGE(PG8_SB(0, 1), b2 + hstepB, voffB); PG8_STAGE(PG8_SA(0, 0), a2, voffA);
.LBB0_1265:
	s_add_u32 s38, s36, 0xfffc0080
	s_addc_u32 s39, s37, -1
	s_add_i32 s80, 0, 0x10000
	s_cmp_eq_u32 s79, 12
	s_cselect_b32 s41, s21, s39
	s_cselect_b32 s40, s75, s38
	v_add_u32_e32 v142, s80, v147
	s_cselect_b32 s39, s76, s78
	s_cselect_b32 s38, s77, s60
	s_add_i32 s82, 0, 0x14000
	ds_read_b128 v[138:141], v142
	ds_read_b128 v[148:151], v142 offset:1024
	ds_read_b128 v[152:155], v142 offset:2048
	ds_read_b128 v[158:161], v142 offset:3072
	v_add_u32_e32 v142, s82, v147
	ds_read_b128 v[162:165], v142
	ds_read_b128 v[166:169], v142 offset:1024
	ds_read_b128 v[170:173], v142 offset:2048
	ds_read_b128 v[174:177], v142 offset:3072
	v_lshl_add_u64 v[142:143], s[36:37], 0, v[136:137]
	s_add_i32 m0, s29, 0xc000
	ds_read_b128 v[180:183], v156
	ds_read_b128 v[184:187], v156 offset:1024
	ds_read_b128 v[188:191], v156 offset:2048
	ds_read_b128 v[192:195], v156 offset:3072
	ds_read_b128 v[196:199], v156 offset:4096
	ds_read_b128 v[200:203], v156 offset:5120
	ds_read_b128 v[204:207], v156 offset:6144
	ds_read_b128 v[208:211], v156 offset:7168
	global_load_lds_dwordx4 v[142:143], off
	v_lshl_add_u64 v[142:143], s[36:37], 0, v[134:135]
	s_add_i32 m0, s29, 0xe000
	s_nop 0
	global_load_lds_dwordx4 v[142:143], off
	s_waitcnt vmcnt(8)
	s_waitcnt lgkmcnt(0)
	s_barrier
	s_setprio 1
	s_waitcnt lgkmcnt(0)
	v_mfma_f32_16x16x32_bf16 v[124:127], v[138:141], v[180:183], v[124:127]
	v_mfma_f32_16x16x32_bf16 v[120:123], v[152:155], v[180:183], v[120:123]
	v_mfma_f32_16x16x32_bf16 v[108:111], v[138:141], v[188:191], v[108:111]
	v_mfma_f32_16x16x32_bf16 v[104:107], v[152:155], v[188:191], v[104:107]
	v_mfma_f32_16x16x32_bf16 v[92:95], v[138:141], v[196:199], v[92:95]
	v_mfma_f32_16x16x32_bf16 v[88:91], v[152:155], v[196:199], v[88:91]
	v_mfma_f32_16x16x32_bf16 v[76:79], v[138:141], v[204:207], v[76:79]
	v_mfma_f32_16x16x32_bf16 v[72:75], v[152:155], v[204:207], v[72:75]
	v_mfma_f32_16x16x32_bf16 v[124:127], v[148:151], v[184:187], v[124:127]
	v_mfma_f32_16x16x32_bf16 v[120:123], v[158:161], v[184:187], v[120:123]
	v_mfma_f32_16x16x32_bf16 v[108:111], v[148:151], v[192:195], v[108:111]
	v_mfma_f32_16x16x32_bf16 v[104:107], v[158:161], v[192:195], v[104:107]
	v_mfma_f32_16x16x32_bf16 v[92:95], v[148:151], v[200:203], v[92:95]
	v_mfma_f32_16x16x32_bf16 v[88:91], v[158:161], v[200:203], v[88:91]
	v_mfma_f32_16x16x32_bf16 v[76:79], v[148:151], v[208:211], v[76:79]
	v_mfma_f32_16x16x32_bf16 v[72:75], v[158:161], v[208:211], v[72:75]
	v_mfma_f32_16x16x32_bf16 v[116:119], v[162:165], v[180:183], v[116:119]
	v_mfma_f32_16x16x32_bf16 v[112:115], v[170:173], v[180:183], v[112:115]
	v_mfma_f32_16x16x32_bf16 v[100:103], v[162:165], v[188:191], v[100:103]
	v_mfma_f32_16x16x32_bf16 v[96:99], v[170:173], v[188:191], v[96:99]
	v_mfma_f32_16x16x32_bf16 v[84:87], v[162:165], v[196:199], v[84:87]
	v_mfma_f32_16x16x32_bf16 v[80:83], v[170:173], v[196:199], v[80:83]
	v_mfma_f32_16x16x32_bf16 v[68:71], v[162:165], v[204:207], v[68:71]
	v_mfma_f32_16x16x32_bf16 v[64:67], v[170:173], v[204:207], v[64:67]
	v_mfma_f32_16x16x32_bf16 v[116:119], v[166:169], v[184:187], v[116:119]
	v_mfma_f32_16x16x32_bf16 v[112:115], v[174:177], v[184:187], v[112:115]
	v_mfma_f32_16x16x32_bf16 v[100:103], v[166:169], v[192:195], v[100:103]
	v_mfma_f32_16x16x32_bf16 v[96:99], v[174:177], v[192:195], v[96:99]
	v_mfma_f32_16x16x32_bf16 v[84:87], v[166:169], v[200:203], v[84:87]
	v_mfma_f32_16x16x32_bf16 v[80:83], v[174:177], v[200:203], v[80:83]
	v_mfma_f32_16x16x32_bf16 v[68:71], v[166:169], v[208:211], v[68:71]
	v_mfma_f32_16x16x32_bf16 v[64:67], v[174:177], v[208:211], v[64:67]
	s_setprio 0
	s_barrier
	s_add_i32 s80, s80, s58
	v_lshl_add_u64 v[142:143], s[38:39], 0, v[144:145]
	s_mov_b32 m0, s80
	ds_read_b128 v[180:183], v156 offset:16384
	ds_read_b128 v[184:187], v156 offset:17408
	ds_read_b128 v[188:191], v156 offset:18432
	ds_read_b128 v[192:195], v156 offset:19456
	ds_read_b128 v[196:199], v156 offset:20480
	ds_read_b128 v[200:203], v156 offset:21504
	ds_read_b128 v[204:207], v156 offset:22528
	ds_read_b128 v[208:211], v156 offset:23552
	global_load_lds_dwordx4 v[142:143], off
	s_add_i32 m0, s80, 0x2000
	s_add_u32 s80, s38, 0x40000
	v_lshl_add_u64 v[212:213], s[38:39], 0, v[132:133]
	s_addc_u32 s81, s39, 0
	s_add_i32 s82, s82, s58
	global_load_lds_dwordx4 v[212:213], off
	v_lshl_add_u64 v[214:215], s[80:81], 0, v[144:145]
	s_mov_b32 m0, s82
	v_lshl_add_u64 v[216:217], s[40:41], 0, v[130:131]
	global_load_lds_dwordx4 v[214:215], off
	v_lshl_add_u64 v[214:215], s[80:81], 0, v[132:133]
	s_add_i32 m0, s82, 0x2000
	s_nop 0
	global_load_lds_dwordx4 v[214:215], off
	v_lshl_add_u64 v[214:215], s[40:41], 0, v[128:129]
	s_mov_b32 m0, s29
	s_nop 0
	global_load_lds_dwordx4 v[214:215], off
	s_mov_b32 m0, s65
	s_nop 0
	global_load_lds_dwordx4 v[216:217], off
	s_waitcnt vmcnt(8)
	s_waitcnt lgkmcnt(0)
	s_barrier
; #define PG8_STAGE(bufoff, gbase, voff) do { _Pragma("unroll") for (int _i = 0; _i < 2; ++_i) \
;         __builtin_amdgcn_global_load_lds((const unsigned*)((const char*)(gbase) + (voff)[_i]), (PG8_LAS unsigned*)(lds + (bufoff) + ldsw + _i * 8192), 16, 0, 0); } while (0)
; #define PG8_LDA(dst, b, h) do { _Pragma("unroll") for (int m = 0; m < 4; ++m) _Pragma("unroll") for (int k = 0; k < 2; ++k) dst[m][k] = *(const PG8_LAS bf16x8*)(lds + PG8_SA(b, h) + aoff + m * 2048 + k * 1024); } while (0)
; #define PG8_LDB(dst, b, h) do { _Pragma("unroll") for (int n = 0; n < 2; ++n) _Pragma("unroll") for (int k = 0; k < 2; ++k) dst[n][k] = *(const PG8_LAS bf16x8*)(lds + PG8_SB(b, h) + boff + n * 2048 + k * 1024); } while (0)
; #define PG8_MMA(ai, bj, At, Bt) do { __builtin_amdgcn_s_setprio(1); _Pragma("unroll") for (int m = 0; m < 4; ++m) _Pragma("unroll") for (int n = 0; n < 2; ++n) _Pragma("unroll") for (int k = 0; k < 2; ++k) \
;         acc[ai][bj][m][n] = __builtin_amdgcn_mfma_f32_16x16x32_bf16(Bt[n][k], At[m][k], acc[ai][bj][m][n], 0, 0, 0); __builtin_amdgcn_s_setprio(0); } while (0)
; #define PG8_WAIT_V(n) asm volatile("s_waitcnt vmcnt(" #n ")" ::: "memory")
; #define PG8_WAIT_L(n) asm volatile("s_waitcnt lgkmcnt(" #n ")" ::: "memory")
; #define PG8_BAR __builtin_amdgcn_s_barrier()
; #define PG8_SCHED __builtin_amdgcn_sched_barrier(0)
; template <class Epi, class Sched, int K, int lda, int ldb, bool ALIGN_EPI = true, bool SP2 = true>
; __device__ __forceinline__ void gemm_phase(PG8_LAS unsigned char* lds, const Sched& S, const Epi& E, const int wave_sgpr) {
;     ...
;             PG8_WAIT_V(8); PG8_WAIT_L(0); PG8_BAR; PG8_MMA(1, 0, At, B0); PG8_MMA(1, 1, At, B1); PG8_BAR; PG8_SCHED;
;             PG8_LDB(B0, 1, 0); PG8_LDB(B1, 1, 1); PG8_SCHED; PG8_LDA(At, 1, 0); PG8_STAGE(PG8_SA(0, 1), a2 + hstepA, voffA);
;             PG8_WAIT_V(8); PG8_WAIT_L(0); PG8_BAR; PG8_MMA(0, 0, At, B0); PG8_MMA(0, 1, At, B1); PG8_BAR; PG8_SCHED;
	s_setprio 1
	s_waitcnt lgkmcnt(0)
	v_mfma_f32_16x16x32_bf16 v[60:63], v[138:141], v[180:183], v[60:63]
	v_mfma_f32_16x16x32_bf16 v[56:59], v[152:155], v[180:183], v[56:59]
	v_mfma_f32_16x16x32_bf16 v[44:47], v[138:141], v[188:191], v[44:47]
	v_mfma_f32_16x16x32_bf16 v[40:43], v[152:155], v[188:191], v[40:43]
	v_mfma_f32_16x16x32_bf16 v[28:31], v[138:141], v[196:199], v[28:31]
	v_mfma_f32_16x16x32_bf16 v[24:27], v[152:155], v[196:199], v[24:27]
	v_mfma_f32_16x16x32_bf16 v[12:15], v[138:141], v[204:207], v[12:15]
	v_mfma_f32_16x16x32_bf16 v[8:11], v[152:155], v[204:207], v[8:11]
	v_mfma_f32_16x16x32_bf16 v[60:63], v[148:151], v[184:187], v[60:63]
	v_mfma_f32_16x16x32_bf16 v[56:59], v[158:161], v[184:187], v[56:59]
	v_mfma_f32_16x16x32_bf16 v[44:47], v[148:151], v[192:195], v[44:47]
	v_mfma_f32_16x16x32_bf16 v[40:43], v[158:161], v[192:195], v[40:43]
	v_mfma_f32_16x16x32_bf16 v[28:31], v[148:151], v[200:203], v[28:31]
	v_mfma_f32_16x16x32_bf16 v[24:27], v[158:161], v[200:203], v[24:27]
	v_mfma_f32_16x16x32_bf16 v[12:15], v[148:151], v[208:211], v[12:15]
	v_mfma_f32_16x16x32_bf16 v[8:11], v[158:161], v[208:211], v[8:11]
	v_mfma_f32_16x16x32_bf16 v[52:55], v[162:165], v[180:183], v[52:55]
	v_mfma_f32_16x16x32_bf16 v[48:51], v[170:173], v[180:183], v[48:51]
	v_mfma_f32_16x16x32_bf16 v[36:39], v[162:165], v[188:191], v[36:39]
	v_mfma_f32_16x16x32_bf16 v[32:35], v[170:173], v[188:191], v[32:35]
	v_mfma_f32_16x16x32_bf16 v[20:23], v[162:165], v[196:199], v[20:23]
	v_mfma_f32_16x16x32_bf16 v[16:19], v[170:173], v[196:199], v[16:19]
	v_mfma_f32_16x16x32_bf16 v[4:7], v[162:165], v[204:207], v[4:7]
	v_mfma_f32_16x16x32_bf16 v[0:3], v[170:173], v[204:207], v[0:3]
	v_mfma_f32_16x16x32_bf16 v[52:55], v[166:169], v[184:187], v[52:55]
	v_mfma_f32_16x16x32_bf16 v[48:51], v[174:177], v[184:187], v[48:51]
	v_mfma_f32_16x16x32_bf16 v[36:39], v[166:169], v[192:195], v[36:39]
	v_mfma_f32_16x16x32_bf16 v[32:35], v[174:177], v[192:195], v[32:35]
	v_mfma_f32_16x16x32_bf16 v[20:23], v[166:169], v[200:203], v[20:23]
	v_mfma_f32_16x16x32_bf16 v[16:19], v[174:177], v[200:203], v[16:19]
	v_mfma_f32_16x16x32_bf16 v[4:7], v[166:169], v[208:211], v[4:7]
	v_mfma_f32_16x16x32_bf16 v[0:3], v[174:177], v[208:211], v[0:3]
	s_setprio 0
	s_barrier
	s_add_i32 s80, 0, 0x18000
	v_add_u32_e32 v146, s80, v147
	s_add_i32 s81, 0, 0x1c000
	ds_read_b128 v[138:141], v146
	ds_read_b128 v[148:151], v146 offset:1024
	ds_read_b128 v[152:155], v146 offset:2048
	ds_read_b128 v[158:161], v146 offset:3072
	v_add_u32_e32 v146, s81, v147
	ds_read_b128 v[162:165], v146
	ds_read_b128 v[166:169], v146 offset:1024
	ds_read_b128 v[170:173], v146 offset:2048
	ds_read_b128 v[174:177], v146 offset:3072
	s_add_u32 s40, s40, 0x40000
	s_addc_u32 s41, s41, 0
	s_mov_b32 m0, s66
	v_lshl_add_u64 v[218:219], s[40:41], 0, v[128:129]
	ds_read_b128 v[180:183], v156 offset:32768
	ds_read_b128 v[184:187], v156 offset:33792
	ds_read_b128 v[188:191], v156 offset:34816
	ds_read_b128 v[192:195], v156 offset:35840
	ds_read_b128 v[196:199], v156 offset:36864
	ds_read_b128 v[200:203], v156 offset:37888
	ds_read_b128 v[204:207], v156 offset:38912
	ds_read_b128 v[208:211], v156 offset:39936
	global_load_lds_dwordx4 v[218:219], off
	v_lshl_add_u64 v[218:219], s[40:41], 0, v[130:131]
	s_mov_b32 m0, s67
	s_nop 0
	global_load_lds_dwordx4 v[218:219], off
	s_waitcnt vmcnt(8)
	s_waitcnt lgkmcnt(0)
	s_barrier
	s_setprio 1
	s_waitcnt lgkmcnt(0)
	v_mfma_f32_16x16x32_bf16 v[124:127], v[138:141], v[180:183], v[124:127]
	v_mfma_f32_16x16x32_bf16 v[120:123], v[152:155], v[180:183], v[120:123]
	v_mfma_f32_16x16x32_bf16 v[108:111], v[138:141], v[188:191], v[108:111]
	v_mfma_f32_16x16x32_bf16 v[104:107], v[152:155], v[188:191], v[104:107]
	v_mfma_f32_16x16x32_bf16 v[92:95], v[138:141], v[196:199], v[92:95]
	v_mfma_f32_16x16x32_bf16 v[88:91], v[152:155], v[196:199], v[88:91]
	v_mfma_f32_16x16x32_bf16 v[76:79], v[138:141], v[204:207], v[76:79]
	v_mfma_f32_16x16x32_bf16 v[72:75], v[152:155], v[204:207], v[72:75]
	v_mfma_f32_16x16x32_bf16 v[124:127], v[148:151], v[184:187], v[124:127]
	v_mfma_f32_16x16x32_bf16 v[120:123], v[158:161], v[184:187], v[120:123]
	v_mfma_f32_16x16x32_bf16 v[108:111], v[148:151], v[192:195], v[108:111]
	v_mfma_f32_16x16x32_bf16 v[104:107], v[158:161], v[192:195], v[104:107]
	v_mfma_f32_16x16x32_bf16 v[92:95], v[148:151], v[200:203], v[92:95]
	v_mfma_f32_16x16x32_bf16 v[88:91], v[158:161], v[200:203], v[88:91]
	v_mfma_f32_16x16x32_bf16 v[76:79], v[148:151], v[208:211], v[76:79]
	v_mfma_f32_16x16x32_bf16 v[72:75], v[158:161], v[208:211], v[72:75]
	v_mfma_f32_16x16x32_bf16 v[116:119], v[162:165], v[180:183], v[116:119]
	v_mfma_f32_16x16x32_bf16 v[112:115], v[170:173], v[180:183], v[112:115]
	v_mfma_f32_16x16x32_bf16 v[100:103], v[162:165], v[188:191], v[100:103]
	v_mfma_f32_16x16x32_bf16 v[96:99], v[170:173], v[188:191], v[96:99]
	v_mfma_f32_16x16x32_bf16 v[84:87], v[162:165], v[196:199], v[84:87]
	v_mfma_f32_16x16x32_bf16 v[80:83], v[170:173], v[196:199], v[80:83]
	v_mfma_f32_16x16x32_bf16 v[68:71], v[162:165], v[204:207], v[68:71]
	v_mfma_f32_16x16x32_bf16 v[64:67], v[170:173], v[204:207], v[64:67]
	v_mfma_f32_16x16x32_bf16 v[116:119], v[166:169], v[184:187], v[116:119]
	v_mfma_f32_16x16x32_bf16 v[112:115], v[174:177], v[184:187], v[112:115]
	v_mfma_f32_16x16x32_bf16 v[100:103], v[166:169], v[192:195], v[100:103]
	v_mfma_f32_16x16x32_bf16 v[96:99], v[174:177], v[192:195], v[96:99]
	v_mfma_f32_16x16x32_bf16 v[84:87], v[166:169], v[200:203], v[84:87]
	v_mfma_f32_16x16x32_bf16 v[80:83], v[174:177], v[200:203], v[80:83]
	v_mfma_f32_16x16x32_bf16 v[68:71], v[166:169], v[208:211], v[68:71]
	v_mfma_f32_16x16x32_bf16 v[64:67], v[174:177], v[208:211], v[64:67]
	s_setprio 0
	s_barrier
; #define PG8_STAGE(bufoff, gbase, voff) do { _Pragma("unroll") for (int _i = 0; _i < 2; ++_i) \
;         __builtin_amdgcn_global_load_lds((const unsigned*)((const char*)(gbase) + (voff)[_i]), (PG8_LAS unsigned*)(lds + (bufoff) + ldsw + _i * 8192), 16, 0, 0); } while (0)
; #define PG8_LDA(dst, b, h) do { _Pragma("unroll") for (int m = 0; m < 4; ++m) _Pragma("unroll") for (int k = 0; k < 2; ++k) dst[m][k] = *(const PG8_LAS bf16x8*)(lds + PG8_SA(b, h) + aoff + m * 2048 + k * 1024); } while (0)
; #define PG8_MMA(ai, bj, At, Bt) do { __builtin_amdgcn_s_setprio(1); _Pragma("unroll") for (int m = 0; m < 4; ++m) _Pragma("unroll") for (int n = 0; n < 2; ++n) _Pragma("unroll") for (int k = 0; k < 2; ++k) \
;         acc[ai][bj][m][n] = __builtin_amdgcn_mfma_f32_16x16x32_bf16(Bt[n][k], At[m][k], acc[ai][bj][m][n], 0, 0, 0); __builtin_amdgcn_s_setprio(0); } while (0)
; #define PG8_WAIT_V(n) asm volatile("s_waitcnt vmcnt(" #n ")" ::: "memory")
; #define PG8_WAIT_L(n) asm volatile("s_waitcnt lgkmcnt(" #n ")" ::: "memory")
; #define PG8_BAR __builtin_amdgcn_s_barrier()
; #define PG8_SCHED __builtin_amdgcn_sched_barrier(0)
; template <class Epi, class Sched, int K, int lda, int ldb, bool ALIGN_EPI = true, bool SP2 = true>
; __device__ __forceinline__ void gemm_phase(PG8_LAS unsigned char* lds, const Sched& S, const Epi& E, const int wave_sgpr) {
;     ...
;         for (int t = 0; t < nt; t += 2) {
;             const bool last = (t == nt - 2);
;     ...
;             PG8_LDA(At, 1, 1); PG8_STAGE(PG8_SB(1, 0), b3, voffB); PG8_STAGE(PG8_SB(1, 1), b3 + hstepB, voffB); PG8_STAGE(PG8_SA(1, 0), a3, voffA);
;             PG8_WAIT_V(8); PG8_WAIT_L(0); PG8_BAR; PG8_MMA(1, 0, At, B0); PG8_MMA(1, 1, At, B1); PG8_BAR; PG8_SCHED;
	s_add_i32 s40, s80, s58
	v_lshl_add_u64 v[142:143], v[142:143], 0, s[30:31]
	s_mov_b32 m0, s40
	ds_read_b128 v[180:183], v156 offset:49152
	ds_read_b128 v[184:187], v156 offset:50176
	ds_read_b128 v[188:191], v156 offset:51200
	ds_read_b128 v[192:195], v156 offset:52224
	ds_read_b128 v[196:199], v156 offset:53248
	ds_read_b128 v[200:203], v156 offset:54272
	ds_read_b128 v[204:207], v156 offset:55296
	ds_read_b128 v[208:211], v156 offset:56320
	global_load_lds_dwordx4 v[142:143], off
	s_add_i32 m0, s40, 0x2000
	s_add_u32 s38, s38, 0x40080
	v_lshl_add_u64 v[142:143], v[212:213], 0, s[30:31]
	s_addc_u32 s39, s39, 0
	s_add_i32 s40, s81, s58
	global_load_lds_dwordx4 v[142:143], off
	v_lshl_add_u64 v[142:143], s[38:39], 0, v[144:145]
	s_mov_b32 m0, s40
	s_nop 0
	global_load_lds_dwordx4 v[142:143], off
	v_lshl_add_u64 v[142:143], s[38:39], 0, v[132:133]
	s_add_i32 m0, s40, 0x2000
	s_nop 0
	global_load_lds_dwordx4 v[142:143], off
	v_lshl_add_u64 v[142:143], v[214:215], 0, s[30:31]
	s_mov_b32 m0, s70
	s_nop 0
	global_load_lds_dwordx4 v[142:143], off
	v_lshl_add_u64 v[142:143], v[216:217], 0, s[30:31]
	s_mov_b32 m0, s71
	s_nop 0
	global_load_lds_dwordx4 v[142:143], off
	s_waitcnt vmcnt(8)
	s_waitcnt lgkmcnt(0)
	s_barrier
	s_setprio 1
	s_waitcnt lgkmcnt(0)
	v_mfma_f32_16x16x32_bf16 v[60:63], v[138:141], v[180:183], v[60:63]
	v_mfma_f32_16x16x32_bf16 v[56:59], v[152:155], v[180:183], v[56:59]
	v_mfma_f32_16x16x32_bf16 v[44:47], v[138:141], v[188:191], v[44:47]
	v_mfma_f32_16x16x32_bf16 v[40:43], v[152:155], v[188:191], v[40:43]
	v_mfma_f32_16x16x32_bf16 v[28:31], v[138:141], v[196:199], v[28:31]
	v_mfma_f32_16x16x32_bf16 v[24:27], v[152:155], v[196:199], v[24:27]
	v_mfma_f32_16x16x32_bf16 v[12:15], v[138:141], v[204:207], v[12:15]
	v_mfma_f32_16x16x32_bf16 v[8:11], v[152:155], v[204:207], v[8:11]
	v_mfma_f32_16x16x32_bf16 v[60:63], v[148:151], v[184:187], v[60:63]
	v_mfma_f32_16x16x32_bf16 v[56:59], v[158:161], v[184:187], v[56:59]
	v_mfma_f32_16x16x32_bf16 v[44:47], v[148:151], v[192:195], v[44:47]
	v_mfma_f32_16x16x32_bf16 v[40:43], v[158:161], v[192:195], v[40:43]
	v_mfma_f32_16x16x32_bf16 v[28:31], v[148:151], v[200:203], v[28:31]
	v_mfma_f32_16x16x32_bf16 v[24:27], v[158:161], v[200:203], v[24:27]
	v_mfma_f32_16x16x32_bf16 v[12:15], v[148:151], v[208:211], v[12:15]
	v_mfma_f32_16x16x32_bf16 v[8:11], v[158:161], v[208:211], v[8:11]
	v_mfma_f32_16x16x32_bf16 v[52:55], v[162:165], v[180:183], v[52:55]
	v_mfma_f32_16x16x32_bf16 v[48:51], v[170:173], v[180:183], v[48:51]
	v_mfma_f32_16x16x32_bf16 v[36:39], v[162:165], v[188:191], v[36:39]
	v_mfma_f32_16x16x32_bf16 v[32:35], v[170:173], v[188:191], v[32:35]
	v_mfma_f32_16x16x32_bf16 v[20:23], v[162:165], v[196:199], v[20:23]
	v_mfma_f32_16x16x32_bf16 v[16:19], v[170:173], v[196:199], v[16:19]
	v_mfma_f32_16x16x32_bf16 v[4:7], v[162:165], v[204:207], v[4:7]
	v_mfma_f32_16x16x32_bf16 v[0:3], v[170:173], v[204:207], v[0:3]
	v_mfma_f32_16x16x32_bf16 v[52:55], v[166:169], v[184:187], v[52:55]
	v_mfma_f32_16x16x32_bf16 v[48:51], v[174:177], v[184:187], v[48:51]
	v_mfma_f32_16x16x32_bf16 v[36:39], v[166:169], v[192:195], v[36:39]
	v_mfma_f32_16x16x32_bf16 v[32:35], v[174:177], v[192:195], v[32:35]
	v_mfma_f32_16x16x32_bf16 v[20:23], v[166:169], v[200:203], v[20:23]
	v_mfma_f32_16x16x32_bf16 v[16:19], v[174:177], v[200:203], v[16:19]
	v_mfma_f32_16x16x32_bf16 v[4:7], v[166:169], v[208:211], v[4:7]
	v_mfma_f32_16x16x32_bf16 v[0:3], v[174:177], v[208:211], v[0:3]
	s_setprio 0
	s_barrier
	s_add_i32 s79, s79, 2
	s_add_u32 s60, s60, 0x100
	s_addc_u32 s78, s78, 0
	s_add_u32 s36, s36, 0x100
	s_addc_u32 s37, s37, 0
	s_cmp_gt_u32 s79, 13
	s_cbranch_scc0 .LBB0_1265
	s_and_b64 vcc, exec, s[18:19]
	s_cbranch_vccz .LBB0_1268
	s_barrier

; #define PG8_STAGE(bufoff, gbase, voff) do { _Pragma("unroll") for (int _i = 0; _i < 2; ++_i) \
;         __builtin_amdgcn_global_load_lds((const unsigned*)((const char*)(gbase) + (voff)[_i]), (PG8_LAS unsigned*)(lds + (bufoff) + ldsw + _i * 8192), 16, 0, 0); } while (0)
; #define PG8_LDA(dst, b, h) do { _Pragma("unroll") for (int m = 0; m < 4; ++m) _Pragma("unroll") for (int k = 0; k < 2; ++k) dst[m][k] = *(const PG8_LAS bf16x8*)(lds + PG8_SA(b, h) + aoff + m * 2048 + k * 1024); } while (0)
; #define PG8_LDB(dst, b, h) do { _Pragma("unroll") for (int n = 0; n < 2; ++n) _Pragma("unroll") for (int k = 0; k < 2; ++k) dst[n][k] = *(const PG8_LAS bf16x8*)(lds + PG8_SB(b, h) + boff + n * 2048 + k * 1024); } while (0)
; #define PG8_MMA(ai, bj, At, Bt) do { __builtin_amdgcn_s_setprio(1); _Pragma("unroll") for (int m = 0; m < 4; ++m) _Pragma("unroll") for (int n = 0; n < 2; ++n) _Pragma("unroll") for (int k = 0; k < 2; ++k) \
;         acc[ai][bj][m][n] = __builtin_amdgcn_mfma_f32_16x16x32_bf16(Bt[n][k], At[m][k], acc[ai][bj][m][n], 0, 0, 0); __builtin_amdgcn_s_setprio(0); } while (0)
; #define PG8_WAIT_V(n) asm volatile("s_waitcnt vmcnt(" #n ")" ::: "memory")
; #define PG8_WAIT_L(n) asm volatile("s_waitcnt lgkmcnt(" #n ")" ::: "memory")
; #define PG8_BAR __builtin_amdgcn_s_barrier()
; #define PG8_SCHED __builtin_amdgcn_sched_barrier(0)
; template <class Epi, class Sched, int K, int lda, int ldb, bool ALIGN_EPI = true, bool SP2 = true>
; __device__ __forceinline__ void gemm_phase(PG8_LAS unsigned char* lds, const Sched& S, const Epi& E, const int wave_sgpr) {
;     ...
;         for (int t = 0; t < nt; t += 2) {
;             const bool last = (t == nt - 2);
;             const char* a1 = cA + (size_t)(t + 1) * kstep;
;             const char* a2 = last ? nA : cA + (size_t)(t + 2) * kstep; const char* b2 = last ? nB : cB + (size_t)(t + 2) * kstep;
;             const char* a3 = a2 + kstep; const char* b3 = b2 + kstep;
;             if constexpr (SP2) {
;             PG8_LDB(B0, 0, 0); PG8_LDB(B1, 0, 1); PG8_SCHED; PG8_LDA(At, 0, 0); PG8_STAGE(PG8_SA(1, 1), a1 + hstepA, voffA);
;             PG8_WAIT_V(8); PG8_WAIT_L(0); PG8_BAR; PG8_MMA(0, 0, At, B0); PG8_MMA(0, 1, At, B1); PG8_BAR; PG8_SCHED;
;             PG8_LDA(At, 0, 1); PG8_STAGE(PG8_SB(0, 0), b2, voffB); PG8_STAGE(PG8_SB(0, 1), b2 + hstepB, voffB); PG8_STAGE(PG8_SA(0, 0), a2, voffA);
.LBB0_1366:
	s_add_u32 s18, s16, 0xfff80080
	s_addc_u32 s19, s17, -1
	s_add_i32 s51, 0, 0x10000
	s_cmp_eq_u32 s50, 28
	s_cselect_b32 s21, s9, s19
	s_cselect_b32 s20, s44, s18
	v_add_u32_e32 v142, s51, v147
	s_cselect_b32 s19, s45, s49
	s_cselect_b32 s18, s47, s48
	s_add_i32 s53, 0, 0x14000
	ds_read_b128 v[138:141], v142
	ds_read_b128 v[148:151], v142 offset:1024
	ds_read_b128 v[152:155], v142 offset:2048
	ds_read_b128 v[158:161], v142 offset:3072
	v_add_u32_e32 v142, s53, v147
	ds_read_b128 v[162:165], v142
	ds_read_b128 v[166:169], v142 offset:1024
	ds_read_b128 v[170:173], v142 offset:2048
	ds_read_b128 v[174:177], v142 offset:3072
	v_lshl_add_u64 v[142:143], s[16:17], 0, v[136:137]
	s_add_i32 m0, s27, 0xc000
	ds_read_b128 v[180:183], v156
	ds_read_b128 v[184:187], v156 offset:1024
	ds_read_b128 v[188:191], v156 offset:2048
	ds_read_b128 v[192:195], v156 offset:3072
	ds_read_b128 v[196:199], v156 offset:4096
	ds_read_b128 v[200:203], v156 offset:5120
	ds_read_b128 v[204:207], v156 offset:6144
	ds_read_b128 v[208:211], v156 offset:7168
	global_load_lds_dwordx4 v[142:143], off
	v_lshl_add_u64 v[142:143], s[16:17], 0, v[134:135]
	s_add_i32 m0, s27, 0xe000
	s_nop 0
	global_load_lds_dwordx4 v[142:143], off
	s_waitcnt vmcnt(8)
	s_waitcnt lgkmcnt(0)
	s_barrier
	s_setprio 1
	s_waitcnt lgkmcnt(0)
	v_mfma_f32_16x16x32_bf16 v[124:127], v[138:141], v[180:183], v[124:127]
	v_mfma_f32_16x16x32_bf16 v[120:123], v[152:155], v[180:183], v[120:123]
	v_mfma_f32_16x16x32_bf16 v[108:111], v[138:141], v[188:191], v[108:111]
	v_mfma_f32_16x16x32_bf16 v[104:107], v[152:155], v[188:191], v[104:107]
	v_mfma_f32_16x16x32_bf16 v[92:95], v[138:141], v[196:199], v[92:95]
	v_mfma_f32_16x16x32_bf16 v[88:91], v[152:155], v[196:199], v[88:91]
	v_mfma_f32_16x16x32_bf16 v[76:79], v[138:141], v[204:207], v[76:79]
	v_mfma_f32_16x16x32_bf16 v[72:75], v[152:155], v[204:207], v[72:75]
	v_mfma_f32_16x16x32_bf16 v[124:127], v[148:151], v[184:187], v[124:127]
	v_mfma_f32_16x16x32_bf16 v[120:123], v[158:161], v[184:187], v[120:123]
	v_mfma_f32_16x16x32_bf16 v[108:111], v[148:151], v[192:195], v[108:111]
	v_mfma_f32_16x16x32_bf16 v[104:107], v[158:161], v[192:195], v[104:107]
	v_mfma_f32_16x16x32_bf16 v[92:95], v[148:151], v[200:203], v[92:95]
	v_mfma_f32_16x16x32_bf16 v[88:91], v[158:161], v[200:203], v[88:91]
	v_mfma_f32_16x16x32_bf16 v[76:79], v[148:151], v[208:211], v[76:79]
	v_mfma_f32_16x16x32_bf16 v[72:75], v[158:161], v[208:211], v[72:75]
	v_mfma_f32_16x16x32_bf16 v[116:119], v[162:165], v[180:183], v[116:119]
	v_mfma_f32_16x16x32_bf16 v[112:115], v[170:173], v[180:183], v[112:115]
	v_mfma_f32_16x16x32_bf16 v[100:103], v[162:165], v[188:191], v[100:103]
	v_mfma_f32_16x16x32_bf16 v[96:99], v[170:173], v[188:191], v[96:99]
	v_mfma_f32_16x16x32_bf16 v[84:87], v[162:165], v[196:199], v[84:87]
	v_mfma_f32_16x16x32_bf16 v[80:83], v[170:173], v[196:199], v[80:83]
	v_mfma_f32_16x16x32_bf16 v[68:71], v[162:165], v[204:207], v[68:71]
	v_mfma_f32_16x16x32_bf16 v[64:67], v[170:173], v[204:207], v[64:67]
	v_mfma_f32_16x16x32_bf16 v[116:119], v[166:169], v[184:187], v[116:119]
	v_mfma_f32_16x16x32_bf16 v[112:115], v[174:177], v[184:187], v[112:115]
	v_mfma_f32_16x16x32_bf16 v[100:103], v[166:169], v[192:195], v[100:103]
	v_mfma_f32_16x16x32_bf16 v[96:99], v[174:177], v[192:195], v[96:99]
	v_mfma_f32_16x16x32_bf16 v[84:87], v[166:169], v[200:203], v[84:87]
	v_mfma_f32_16x16x32_bf16 v[80:83], v[174:177], v[200:203], v[80:83]
	v_mfma_f32_16x16x32_bf16 v[68:71], v[166:169], v[208:211], v[68:71]
	v_mfma_f32_16x16x32_bf16 v[64:67], v[174:177], v[208:211], v[64:67]
	s_setprio 0
	s_barrier
	s_add_i32 s51, s51, s26
	v_lshl_add_u64 v[142:143], s[18:19], 0, v[144:145]
	s_mov_b32 m0, s51
	ds_read_b128 v[180:183], v156 offset:16384
	ds_read_b128 v[184:187], v156 offset:17408
	ds_read_b128 v[188:191], v156 offset:18432
	ds_read_b128 v[192:195], v156 offset:19456
	ds_read_b128 v[196:199], v156 offset:20480
	ds_read_b128 v[200:203], v156 offset:21504
	ds_read_b128 v[204:207], v156 offset:22528
	ds_read_b128 v[208:211], v156 offset:23552
	global_load_lds_dwordx4 v[142:143], off
	s_add_i32 m0, s51, 0x2000
	s_add_u32 s54, s18, 0x80000
	v_lshl_add_u64 v[212:213], s[18:19], 0, v[128:129]
	s_addc_u32 s55, s19, 0
	s_add_i32 s51, s53, s26
	global_load_lds_dwordx4 v[212:213], off
	v_lshl_add_u64 v[214:215], s[54:55], 0, v[144:145]
	s_mov_b32 m0, s51
	v_lshl_add_u64 v[216:217], s[20:21], 0, v[130:131]
	global_load_lds_dwordx4 v[214:215], off
	v_lshl_add_u64 v[214:215], s[54:55], 0, v[128:129]
	s_add_i32 m0, s51, 0x2000
	s_nop 0
	global_load_lds_dwordx4 v[214:215], off
	v_lshl_add_u64 v[214:215], s[20:21], 0, v[132:133]
	s_mov_b32 m0, s27
	s_nop 0
	global_load_lds_dwordx4 v[214:215], off
	s_mov_b32 m0, s28
	s_nop 0
	global_load_lds_dwordx4 v[216:217], off
	s_waitcnt vmcnt(8)
	s_waitcnt lgkmcnt(0)
	s_barrier
; #define PG8_STAGE(bufoff, gbase, voff) do { _Pragma("unroll") for (int _i = 0; _i < 2; ++_i) \
;         __builtin_amdgcn_global_load_lds((const unsigned*)((const char*)(gbase) + (voff)[_i]), (PG8_LAS unsigned*)(lds + (bufoff) + ldsw + _i * 8192), 16, 0, 0); } while (0)
; #define PG8_LDA(dst, b, h) do { _Pragma("unroll") for (int m = 0; m < 4; ++m) _Pragma("unroll") for (int k = 0; k < 2; ++k) dst[m][k] = *(const PG8_LAS bf16x8*)(lds + PG8_SA(b, h) + aoff + m * 2048 + k * 1024); } while (0)
; #define PG8_LDB(dst, b, h) do { _Pragma("unroll") for (int n = 0; n < 2; ++n) _Pragma("unroll") for (int k = 0; k < 2; ++k) dst[n][k] = *(const PG8_LAS bf16x8*)(lds + PG8_SB(b, h) + boff + n * 2048 + k * 1024); } while (0)
; #define PG8_MMA(ai, bj, At, Bt) do { __builtin_amdgcn_s_setprio(1); _Pragma("unroll") for (int m = 0; m < 4; ++m) _Pragma("unroll") for (int n = 0; n < 2; ++n) _Pragma("unroll") for (int k = 0; k < 2; ++k) \
;         acc[ai][bj][m][n] = __builtin_amdgcn_mfma_f32_16x16x32_bf16(Bt[n][k], At[m][k], acc[ai][bj][m][n], 0, 0, 0); __builtin_amdgcn_s_setprio(0); } while (0)
; #define PG8_WAIT_V(n) asm volatile("s_waitcnt vmcnt(" #n ")" ::: "memory")
; #define PG8_WAIT_L(n) asm volatile("s_waitcnt lgkmcnt(" #n ")" ::: "memory")
; #define PG8_BAR __builtin_amdgcn_s_barrier()
; #define PG8_SCHED __builtin_amdgcn_sched_barrier(0)
; template <class Epi, class Sched, int K, int lda, int ldb, bool ALIGN_EPI = true, bool SP2 = true>
; __device__ __forceinline__ void gemm_phase(PG8_LAS unsigned char* lds, const Sched& S, const Epi& E, const int wave_sgpr) {
;     ...
;             PG8_WAIT_V(8); PG8_WAIT_L(0); PG8_BAR; PG8_MMA(1, 0, At, B0); PG8_MMA(1, 1, At, B1); PG8_BAR; PG8_SCHED;
;             PG8_LDB(B0, 1, 0); PG8_LDB(B1, 1, 1); PG8_SCHED; PG8_LDA(At, 1, 0); PG8_STAGE(PG8_SA(0, 1), a2 + hstepA, voffA);
;             PG8_WAIT_V(8); PG8_WAIT_L(0); PG8_BAR; PG8_MMA(0, 0, At, B0); PG8_MMA(0, 1, At, B1); PG8_BAR; PG8_SCHED;
	s_setprio 1
	s_waitcnt lgkmcnt(0)
	v_mfma_f32_16x16x32_bf16 v[60:63], v[138:141], v[180:183], v[60:63]
	v_mfma_f32_16x16x32_bf16 v[56:59], v[152:155], v[180:183], v[56:59]
	v_mfma_f32_16x16x32_bf16 v[44:47], v[138:141], v[188:191], v[44:47]
	v_mfma_f32_16x16x32_bf16 v[40:43], v[152:155], v[188:191], v[40:43]
	v_mfma_f32_16x16x32_bf16 v[28:31], v[138:141], v[196:199], v[28:31]
	v_mfma_f32_16x16x32_bf16 v[24:27], v[152:155], v[196:199], v[24:27]
	v_mfma_f32_16x16x32_bf16 v[12:15], v[138:141], v[204:207], v[12:15]
	v_mfma_f32_16x16x32_bf16 v[8:11], v[152:155], v[204:207], v[8:11]
	v_mfma_f32_16x16x32_bf16 v[60:63], v[148:151], v[184:187], v[60:63]
	v_mfma_f32_16x16x32_bf16 v[56:59], v[158:161], v[184:187], v[56:59]
	v_mfma_f32_16x16x32_bf16 v[44:47], v[148:151], v[192:195], v[44:47]
	v_mfma_f32_16x16x32_bf16 v[40:43], v[158:161], v[192:195], v[40:43]
	v_mfma_f32_16x16x32_bf16 v[28:31], v[148:151], v[200:203], v[28:31]
	v_mfma_f32_16x16x32_bf16 v[24:27], v[158:161], v[200:203], v[24:27]
	v_mfma_f32_16x16x32_bf16 v[12:15], v[148:151], v[208:211], v[12:15]
	v_mfma_f32_16x16x32_bf16 v[8:11], v[158:161], v[208:211], v[8:11]
	v_mfma_f32_16x16x32_bf16 v[52:55], v[162:165], v[180:183], v[52:55]
	v_mfma_f32_16x16x32_bf16 v[48:51], v[170:173], v[180:183], v[48:51]
	v_mfma_f32_16x16x32_bf16 v[36:39], v[162:165], v[188:191], v[36:39]
	v_mfma_f32_16x16x32_bf16 v[32:35], v[170:173], v[188:191], v[32:35]
	v_mfma_f32_16x16x32_bf16 v[20:23], v[162:165], v[196:199], v[20:23]
	v_mfma_f32_16x16x32_bf16 v[16:19], v[170:173], v[196:199], v[16:19]
	v_mfma_f32_16x16x32_bf16 v[4:7], v[162:165], v[204:207], v[4:7]
	v_mfma_f32_16x16x32_bf16 v[0:3], v[170:173], v[204:207], v[0:3]
	v_mfma_f32_16x16x32_bf16 v[52:55], v[166:169], v[184:187], v[52:55]
	v_mfma_f32_16x16x32_bf16 v[48:51], v[174:177], v[184:187], v[48:51]
	v_mfma_f32_16x16x32_bf16 v[36:39], v[166:169], v[192:195], v[36:39]
	v_mfma_f32_16x16x32_bf16 v[32:35], v[174:177], v[192:195], v[32:35]
	v_mfma_f32_16x16x32_bf16 v[20:23], v[166:169], v[200:203], v[20:23]
	v_mfma_f32_16x16x32_bf16 v[16:19], v[174:177], v[200:203], v[16:19]
	v_mfma_f32_16x16x32_bf16 v[4:7], v[166:169], v[208:211], v[4:7]
	v_mfma_f32_16x16x32_bf16 v[0:3], v[174:177], v[208:211], v[0:3]
	s_setprio 0
	s_barrier
	s_add_i32 s51, 0, 0x18000
	v_add_u32_e32 v146, s51, v147
	s_add_i32 s53, 0, 0x1c000
	ds_read_b128 v[138:141], v146
	ds_read_b128 v[148:151], v146 offset:1024
	ds_read_b128 v[152:155], v146 offset:2048
	ds_read_b128 v[158:161], v146 offset:3072
	v_add_u32_e32 v146, s53, v147
	ds_read_b128 v[162:165], v146
	ds_read_b128 v[166:169], v146 offset:1024
	ds_read_b128 v[170:173], v146 offset:2048
	ds_read_b128 v[174:177], v146 offset:3072
	s_add_u32 s20, s20, 0x80000
	s_addc_u32 s21, s21, 0
	s_mov_b32 m0, s29
	v_lshl_add_u64 v[218:219], s[20:21], 0, v[132:133]
	ds_read_b128 v[180:183], v156 offset:32768
	ds_read_b128 v[184:187], v156 offset:33792
	ds_read_b128 v[188:191], v156 offset:34816
	ds_read_b128 v[192:195], v156 offset:35840
	ds_read_b128 v[196:199], v156 offset:36864
	ds_read_b128 v[200:203], v156 offset:37888
	ds_read_b128 v[204:207], v156 offset:38912
	ds_read_b128 v[208:211], v156 offset:39936
	global_load_lds_dwordx4 v[218:219], off
	v_lshl_add_u64 v[218:219], s[20:21], 0, v[130:131]
	s_mov_b32 m0, s34
	s_nop 0
	global_load_lds_dwordx4 v[218:219], off
	s_waitcnt vmcnt(8)
	s_waitcnt lgkmcnt(0)
	s_barrier
	s_setprio 1
	s_waitcnt lgkmcnt(0)
	v_mfma_f32_16x16x32_bf16 v[124:127], v[138:141], v[180:183], v[124:127]
	v_mfma_f32_16x16x32_bf16 v[120:123], v[152:155], v[180:183], v[120:123]
	v_mfma_f32_16x16x32_bf16 v[108:111], v[138:141], v[188:191], v[108:111]
	v_mfma_f32_16x16x32_bf16 v[104:107], v[152:155], v[188:191], v[104:107]
	v_mfma_f32_16x16x32_bf16 v[92:95], v[138:141], v[196:199], v[92:95]
	v_mfma_f32_16x16x32_bf16 v[88:91], v[152:155], v[196:199], v[88:91]
	v_mfma_f32_16x16x32_bf16 v[76:79], v[138:141], v[204:207], v[76:79]
	v_mfma_f32_16x16x32_bf16 v[72:75], v[152:155], v[204:207], v[72:75]
	v_mfma_f32_16x16x32_bf16 v[124:127], v[148:151], v[184:187], v[124:127]
	v_mfma_f32_16x16x32_bf16 v[120:123], v[158:161], v[184:187], v[120:123]
	v_mfma_f32_16x16x32_bf16 v[108:111], v[148:151], v[192:195], v[108:111]
	v_mfma_f32_16x16x32_bf16 v[104:107], v[158:161], v[192:195], v[104:107]
	v_mfma_f32_16x16x32_bf16 v[92:95], v[148:151], v[200:203], v[92:95]
	v_mfma_f32_16x16x32_bf16 v[88:91], v[158:161], v[200:203], v[88:91]
	v_mfma_f32_16x16x32_bf16 v[76:79], v[148:151], v[208:211], v[76:79]
	v_mfma_f32_16x16x32_bf16 v[72:75], v[158:161], v[208:211], v[72:75]
	v_mfma_f32_16x16x32_bf16 v[116:119], v[162:165], v[180:183], v[116:119]
	v_mfma_f32_16x16x32_bf16 v[112:115], v[170:173], v[180:183], v[112:115]
	v_mfma_f32_16x16x32_bf16 v[100:103], v[162:165], v[188:191], v[100:103]
	v_mfma_f32_16x16x32_bf16 v[96:99], v[170:173], v[188:191], v[96:99]
	v_mfma_f32_16x16x32_bf16 v[84:87], v[162:165], v[196:199], v[84:87]
	v_mfma_f32_16x16x32_bf16 v[80:83], v[170:173], v[196:199], v[80:83]
	v_mfma_f32_16x16x32_bf16 v[68:71], v[162:165], v[204:207], v[68:71]
	v_mfma_f32_16x16x32_bf16 v[64:67], v[170:173], v[204:207], v[64:67]
	v_mfma_f32_16x16x32_bf16 v[116:119], v[166:169], v[184:187], v[116:119]
	v_mfma_f32_16x16x32_bf16 v[112:115], v[174:177], v[184:187], v[112:115]
	v_mfma_f32_16x16x32_bf16 v[100:103], v[166:169], v[192:195], v[100:103]
	v_mfma_f32_16x16x32_bf16 v[96:99], v[174:177], v[192:195], v[96:99]
	v_mfma_f32_16x16x32_bf16 v[84:87], v[166:169], v[200:203], v[84:87]
	v_mfma_f32_16x16x32_bf16 v[80:83], v[174:177], v[200:203], v[80:83]
	v_mfma_f32_16x16x32_bf16 v[68:71], v[166:169], v[208:211], v[68:71]
	v_mfma_f32_16x16x32_bf16 v[64:67], v[174:177], v[208:211], v[64:67]
	s_setprio 0
	s_barrier
; #define PG8_STAGE(bufoff, gbase, voff) do { _Pragma("unroll") for (int _i = 0; _i < 2; ++_i) \
;         __builtin_amdgcn_global_load_lds((const unsigned*)((const char*)(gbase) + (voff)[_i]), (PG8_LAS unsigned*)(lds + (bufoff) + ldsw + _i * 8192), 16, 0, 0); } while (0)
; #define PG8_LDA(dst, b, h) do { _Pragma("unroll") for (int m = 0; m < 4; ++m) _Pragma("unroll") for (int k = 0; k < 2; ++k) dst[m][k] = *(const PG8_LAS bf16x8*)(lds + PG8_SA(b, h) + aoff + m * 2048 + k * 1024); } while (0)
; #define PG8_MMA(ai, bj, At, Bt) do { __builtin_amdgcn_s_setprio(1); _Pragma("unroll") for (int m = 0; m < 4; ++m) _Pragma("unroll") for (int n = 0; n < 2; ++n) _Pragma("unroll") for (int k = 0; k < 2; ++k) \
;         acc[ai][bj][m][n] = __builtin_amdgcn_mfma_f32_16x16x32_bf16(Bt[n][k], At[m][k], acc[ai][bj][m][n], 0, 0, 0); __builtin_amdgcn_s_setprio(0); } while (0)
; #define PG8_WAIT_V(n) asm volatile("s_waitcnt vmcnt(" #n ")" ::: "memory")
; #define PG8_WAIT_L(n) asm volatile("s_waitcnt lgkmcnt(" #n ")" ::: "memory")
; #define PG8_BAR __builtin_amdgcn_s_barrier()
; #define PG8_SCHED __builtin_amdgcn_sched_barrier(0)
; template <class Epi, class Sched, int K, int lda, int ldb, bool ALIGN_EPI = true, bool SP2 = true>
; __device__ __forceinline__ void gemm_phase(PG8_LAS unsigned char* lds, const Sched& S, const Epi& E, const int wave_sgpr) {
;     ...
;         for (int t = 0; t < nt; t += 2) {
;             const bool last = (t == nt - 2);
;     ...
;             PG8_LDA(At, 1, 1); PG8_STAGE(PG8_SB(1, 0), b3, voffB); PG8_STAGE(PG8_SB(1, 1), b3 + hstepB, voffB); PG8_STAGE(PG8_SA(1, 0), a3, voffA);
;             PG8_WAIT_V(8); PG8_WAIT_L(0); PG8_BAR; PG8_MMA(1, 0, At, B0); PG8_MMA(1, 1, At, B1); PG8_BAR; PG8_SCHED;
	s_add_i32 s20, s51, s26
	v_lshl_add_u64 v[142:143], v[142:143], 0, s[30:31]
	s_mov_b32 m0, s20
	ds_read_b128 v[180:183], v156 offset:49152
	ds_read_b128 v[184:187], v156 offset:50176
	ds_read_b128 v[188:191], v156 offset:51200
	ds_read_b128 v[192:195], v156 offset:52224
	ds_read_b128 v[196:199], v156 offset:53248
	ds_read_b128 v[200:203], v156 offset:54272
	ds_read_b128 v[204:207], v156 offset:55296
	ds_read_b128 v[208:211], v156 offset:56320
	global_load_lds_dwordx4 v[142:143], off
	s_add_i32 m0, s20, 0x2000
	s_add_u32 s18, s18, 0x80080
	v_lshl_add_u64 v[142:143], v[212:213], 0, s[30:31]
	s_addc_u32 s19, s19, 0
	s_add_i32 s20, s53, s26
	global_load_lds_dwordx4 v[142:143], off
	v_lshl_add_u64 v[142:143], s[18:19], 0, v[144:145]
	s_mov_b32 m0, s20
	s_nop 0
	global_load_lds_dwordx4 v[142:143], off
	v_lshl_add_u64 v[142:143], s[18:19], 0, v[128:129]
	s_add_i32 m0, s20, 0x2000
	s_nop 0
	global_load_lds_dwordx4 v[142:143], off
	v_lshl_add_u64 v[142:143], v[214:215], 0, s[30:31]
	s_mov_b32 m0, s38
	s_nop 0
	global_load_lds_dwordx4 v[142:143], off
	v_lshl_add_u64 v[142:143], v[216:217], 0, s[30:31]
	s_mov_b32 m0, s39
	s_nop 0
	global_load_lds_dwordx4 v[142:143], off
	s_waitcnt vmcnt(8)
	s_waitcnt lgkmcnt(0)
	s_barrier
	s_setprio 1
	s_waitcnt lgkmcnt(0)
	v_mfma_f32_16x16x32_bf16 v[60:63], v[138:141], v[180:183], v[60:63]
	v_mfma_f32_16x16x32_bf16 v[56:59], v[152:155], v[180:183], v[56:59]
	v_mfma_f32_16x16x32_bf16 v[44:47], v[138:141], v[188:191], v[44:47]
	v_mfma_f32_16x16x32_bf16 v[40:43], v[152:155], v[188:191], v[40:43]
	v_mfma_f32_16x16x32_bf16 v[28:31], v[138:141], v[196:199], v[28:31]
	v_mfma_f32_16x16x32_bf16 v[24:27], v[152:155], v[196:199], v[24:27]
	v_mfma_f32_16x16x32_bf16 v[12:15], v[138:141], v[204:207], v[12:15]
	v_mfma_f32_16x16x32_bf16 v[8:11], v[152:155], v[204:207], v[8:11]
	v_mfma_f32_16x16x32_bf16 v[60:63], v[148:151], v[184:187], v[60:63]
	v_mfma_f32_16x16x32_bf16 v[56:59], v[158:161], v[184:187], v[56:59]
	v_mfma_f32_16x16x32_bf16 v[44:47], v[148:151], v[192:195], v[44:47]
	v_mfma_f32_16x16x32_bf16 v[40:43], v[158:161], v[192:195], v[40:43]
	v_mfma_f32_16x16x32_bf16 v[28:31], v[148:151], v[200:203], v[28:31]
	v_mfma_f32_16x16x32_bf16 v[24:27], v[158:161], v[200:203], v[24:27]
	v_mfma_f32_16x16x32_bf16 v[12:15], v[148:151], v[208:211], v[12:15]
	v_mfma_f32_16x16x32_bf16 v[8:11], v[158:161], v[208:211], v[8:11]
	v_mfma_f32_16x16x32_bf16 v[52:55], v[162:165], v[180:183], v[52:55]
	v_mfma_f32_16x16x32_bf16 v[48:51], v[170:173], v[180:183], v[48:51]
	v_mfma_f32_16x16x32_bf16 v[36:39], v[162:165], v[188:191], v[36:39]
	v_mfma_f32_16x16x32_bf16 v[32:35], v[170:173], v[188:191], v[32:35]
	v_mfma_f32_16x16x32_bf16 v[20:23], v[162:165], v[196:199], v[20:23]
	v_mfma_f32_16x16x32_bf16 v[16:19], v[170:173], v[196:199], v[16:19]
	v_mfma_f32_16x16x32_bf16 v[4:7], v[162:165], v[204:207], v[4:7]
	v_mfma_f32_16x16x32_bf16 v[0:3], v[170:173], v[204:207], v[0:3]
	v_mfma_f32_16x16x32_bf16 v[52:55], v[166:169], v[184:187], v[52:55]
	v_mfma_f32_16x16x32_bf16 v[48:51], v[174:177], v[184:187], v[48:51]
	v_mfma_f32_16x16x32_bf16 v[36:39], v[166:169], v[192:195], v[36:39]
	v_mfma_f32_16x16x32_bf16 v[32:35], v[174:177], v[192:195], v[32:35]
	v_mfma_f32_16x16x32_bf16 v[20:23], v[166:169], v[200:203], v[20:23]
	v_mfma_f32_16x16x32_bf16 v[16:19], v[174:177], v[200:203], v[16:19]
	v_mfma_f32_16x16x32_bf16 v[4:7], v[166:169], v[208:211], v[4:7]
	v_mfma_f32_16x16x32_bf16 v[0:3], v[174:177], v[208:211], v[0:3]
	s_setprio 0
	s_barrier
	s_add_i32 s50, s50, 2
	s_add_u32 s48, s48, 0x100
	s_addc_u32 s49, s49, 0
	s_add_u32 s16, s16, 0x100
	s_addc_u32 s17, s17, 0
	s_cmp_gt_u32 s50, 29
	s_cbranch_scc0 .LBB0_1366
	s_and_b64 vcc, exec, s[6:7]
	s_cbranch_vccz .LBB0_1369
	s_barrier
